# v9 + open barrier of each MFMA segment moved after the 4th MFMA (was after the 1st)
# baseline (speedup 1.0000x reference)
.LBB0_642:
	ds_read_b128 v[148:151], v139
	ds_read_b128 v[152:155], v139 offset:1024
	ds_read_b128 v[156:159], v139 offset:2048
	ds_read_b128 v[160:163], v139 offset:3072
	ds_read_b128 v[164:167], v140
	ds_read_b128 v[168:171], v140 offset:1024
	ds_read_b128 v[172:175], v140 offset:2048
	ds_read_b128 v[176:179], v140 offset:3072
	s_add_i32 s18, s71, 0xffe80080
	s_cmp_eq_u32 s58, s73
	s_cselect_b32 s74, s69, s18
	s_cselect_b32 s76, s70, s72
	s_or_b32 s75, s74, 0x80
	s_add_i32 s18, s71, 0xfff80000
	s_mov_b32 m0, s59
	ds_read_b128 v[180:183], v141
	ds_read_b128 v[184:187], v141 offset:1024
	ds_read_b128 v[188:191], v141 offset:2048
	ds_read_b128 v[192:195], v141 offset:3072
	ds_read_b128 v[196:199], v141 offset:4096
	ds_read_b128 v[200:203], v141 offset:5120
	ds_read_b128 v[204:207], v141 offset:6144
	ds_read_b128 v[208:211], v141 offset:7168
	buffer_load_dwordx4 v137, s[12:15], s18 offen lds
	s_mov_b32 m0, s60
	s_nop 0
	buffer_load_dwordx4 v137, s[12:15], s71 offen lds
	s_waitcnt vmcnt(8)
	s_waitcnt lgkmcnt(0)
	s_setprio 1
	v_mfma_f32_16x16x32_bf16 v[118:121], v[148:151], v[180:183], v[118:121]
	v_mfma_f32_16x16x32_bf16 v[118:121], v[152:155], v[184:187], v[118:121]
	v_mfma_f32_16x16x32_bf16 v[114:117], v[156:159], v[180:183], v[114:117]
	v_mfma_f32_16x16x32_bf16 v[114:117], v[160:163], v[184:187], v[114:117]
	s_barrier
	v_mfma_f32_16x16x32_bf16 v[110:113], v[148:151], v[188:191], v[110:113]
	v_mfma_f32_16x16x32_bf16 v[110:113], v[152:155], v[192:195], v[110:113]
	v_mfma_f32_16x16x32_bf16 v[102:105], v[156:159], v[188:191], v[102:105]
	v_mfma_f32_16x16x32_bf16 v[102:105], v[160:163], v[192:195], v[102:105]
	v_mfma_f32_16x16x32_bf16 v[94:97], v[148:151], v[196:199], v[94:97]
	v_mfma_f32_16x16x32_bf16 v[94:97], v[152:155], v[200:203], v[94:97]
	v_mfma_f32_16x16x32_bf16 v[86:89], v[156:159], v[196:199], v[86:89]
	v_mfma_f32_16x16x32_bf16 v[86:89], v[160:163], v[200:203], v[86:89]
	v_mfma_f32_16x16x32_bf16 v[78:81], v[148:151], v[204:207], v[78:81]
	v_mfma_f32_16x16x32_bf16 v[78:81], v[152:155], v[208:211], v[78:81]
	v_mfma_f32_16x16x32_bf16 v[66:69], v[156:159], v[204:207], v[66:69]
	v_mfma_f32_16x16x32_bf16 v[66:69], v[160:163], v[208:211], v[66:69]
	v_mfma_f32_16x16x32_bf16 v[126:129], v[164:167], v[180:183], v[126:129]
	v_mfma_f32_16x16x32_bf16 v[126:129], v[168:171], v[184:187], v[126:129]
	v_mfma_f32_16x16x32_bf16 v[122:125], v[172:175], v[180:183], v[122:125]
	v_mfma_f32_16x16x32_bf16 v[122:125], v[176:179], v[184:187], v[122:125]
	v_mfma_f32_16x16x32_bf16 v[106:109], v[164:167], v[188:191], v[106:109]
	v_mfma_f32_16x16x32_bf16 v[106:109], v[168:171], v[192:195], v[106:109]
	v_mfma_f32_16x16x32_bf16 v[98:101], v[172:175], v[188:191], v[98:101]
	v_mfma_f32_16x16x32_bf16 v[98:101], v[176:179], v[192:195], v[98:101]
	v_mfma_f32_16x16x32_bf16 v[90:93], v[164:167], v[196:199], v[90:93]
	v_mfma_f32_16x16x32_bf16 v[90:93], v[168:171], v[200:203], v[90:93]
	v_mfma_f32_16x16x32_bf16 v[82:85], v[172:175], v[196:199], v[82:85]
	v_mfma_f32_16x16x32_bf16 v[82:85], v[176:179], v[200:203], v[82:85]
	v_mfma_f32_16x16x32_bf16 v[74:77], v[164:167], v[204:207], v[74:77]
	v_mfma_f32_16x16x32_bf16 v[74:77], v[168:171], v[208:211], v[74:77]
	v_mfma_f32_16x16x32_bf16 v[70:73], v[172:175], v[204:207], v[70:73]
	v_mfma_f32_16x16x32_bf16 v[70:73], v[176:179], v[208:211], v[70:73]
	s_setprio 0
	s_barrier
	s_mov_b32 m0, s30
	s_mov_b32 s18, s14
	s_mov_b32 s19, s15
	ds_read_b128 v[180:183], v141 offset:16384
	ds_read_b128 v[184:187], v141 offset:17408
	ds_read_b128 v[188:191], v141 offset:18432
	ds_read_b128 v[192:195], v141 offset:19456
	ds_read_b128 v[196:199], v141 offset:20480
	ds_read_b128 v[200:203], v141 offset:21504
	ds_read_b128 v[204:207], v141 offset:22528
	ds_read_b128 v[208:211], v141 offset:23552
	buffer_load_dwordx4 v138, s[16:19], s76 offen lds
	s_add_i32 s77, s76, 0x80000
	s_mov_b32 m0, s31
	s_nop 0
	buffer_load_dwordx4 v138, s[16:19], s77 offen lds
	s_add_i32 s77, s76, 0x100000
	s_mov_b32 m0, s44
	s_nop 0
	buffer_load_dwordx4 v138, s[16:19], s77 offen lds
	s_add_i32 s77, s76, 0x180000
	s_mov_b32 m0, s45
	s_nop 0
	buffer_load_dwordx4 v138, s[16:19], s77 offen lds
	s_mov_b32 m0, s27
	s_add_i32 s77, s74, 0x80000
	buffer_load_dwordx4 v137, s[12:15], s74 offen lds
	s_mov_b32 m0, s46
	s_nop 0
	buffer_load_dwordx4 v137, s[12:15], s77 offen lds
	s_waitcnt vmcnt(8)
	s_waitcnt lgkmcnt(0)
	s_setprio 1
	v_mfma_f32_16x16x32_bf16 v[62:65], v[148:151], v[180:183], v[62:65]
	v_mfma_f32_16x16x32_bf16 v[62:65], v[152:155], v[184:187], v[62:65]
	v_mfma_f32_16x16x32_bf16 v[54:57], v[156:159], v[180:183], v[54:57]
	v_mfma_f32_16x16x32_bf16 v[54:57], v[160:163], v[184:187], v[54:57]
	s_barrier
	v_mfma_f32_16x16x32_bf16 v[46:49], v[148:151], v[188:191], v[46:49]
	v_mfma_f32_16x16x32_bf16 v[46:49], v[152:155], v[192:195], v[46:49]
	v_mfma_f32_16x16x32_bf16 v[38:41], v[156:159], v[188:191], v[38:41]
	v_mfma_f32_16x16x32_bf16 v[38:41], v[160:163], v[192:195], v[38:41]
	v_mfma_f32_16x16x32_bf16 v[30:33], v[148:151], v[196:199], v[30:33]
	v_mfma_f32_16x16x32_bf16 v[30:33], v[152:155], v[200:203], v[30:33]
	v_mfma_f32_16x16x32_bf16 v[22:25], v[156:159], v[196:199], v[22:25]
	v_mfma_f32_16x16x32_bf16 v[22:25], v[160:163], v[200:203], v[22:25]
	v_mfma_f32_16x16x32_bf16 v[14:17], v[148:151], v[204:207], v[14:17]
	v_mfma_f32_16x16x32_bf16 v[14:17], v[152:155], v[208:211], v[14:17]
	v_mfma_f32_16x16x32_bf16 v[6:9], v[156:159], v[204:207], v[6:9]
	v_mfma_f32_16x16x32_bf16 v[6:9], v[160:163], v[208:211], v[6:9]
	v_mfma_f32_16x16x32_bf16 v[58:61], v[164:167], v[180:183], v[58:61]
	v_mfma_f32_16x16x32_bf16 v[58:61], v[168:171], v[184:187], v[58:61]
	v_mfma_f32_16x16x32_bf16 v[50:53], v[172:175], v[180:183], v[50:53]
	v_mfma_f32_16x16x32_bf16 v[50:53], v[176:179], v[184:187], v[50:53]
	v_mfma_f32_16x16x32_bf16 v[42:45], v[164:167], v[188:191], v[42:45]
	v_mfma_f32_16x16x32_bf16 v[42:45], v[168:171], v[192:195], v[42:45]
	v_mfma_f32_16x16x32_bf16 v[34:37], v[172:175], v[188:191], v[34:37]
	v_mfma_f32_16x16x32_bf16 v[34:37], v[176:179], v[192:195], v[34:37]
	v_mfma_f32_16x16x32_bf16 v[26:29], v[164:167], v[196:199], v[26:29]
	v_mfma_f32_16x16x32_bf16 v[26:29], v[168:171], v[200:203], v[26:29]
	v_mfma_f32_16x16x32_bf16 v[18:21], v[172:175], v[196:199], v[18:21]
	v_mfma_f32_16x16x32_bf16 v[18:21], v[176:179], v[200:203], v[18:21]
	v_mfma_f32_16x16x32_bf16 v[10:13], v[164:167], v[204:207], v[10:13]
	v_mfma_f32_16x16x32_bf16 v[10:13], v[168:171], v[208:211], v[10:13]
	v_mfma_f32_16x16x32_bf16 v[2:5], v[172:175], v[204:207], v[2:5]
	v_mfma_f32_16x16x32_bf16 v[2:5], v[176:179], v[208:211], v[2:5]
	s_setprio 0
	s_barrier
	ds_read_b128 v[148:151], v142
	ds_read_b128 v[152:155], v142 offset:1024
	ds_read_b128 v[156:159], v142 offset:2048
	ds_read_b128 v[160:163], v142 offset:3072
	ds_read_b128 v[164:167], v143
	ds_read_b128 v[168:171], v143 offset:1024
	ds_read_b128 v[172:175], v143 offset:2048
	ds_read_b128 v[176:179], v143 offset:3072
	s_mov_b32 m0, s47
	s_add_i32 s77, s74, 0x100000
	ds_read_b128 v[180:183], v141 offset:32768
	ds_read_b128 v[184:187], v141 offset:33792
	ds_read_b128 v[188:191], v141 offset:34816
	ds_read_b128 v[192:195], v141 offset:35840
	ds_read_b128 v[196:199], v141 offset:36864
	ds_read_b128 v[200:203], v141 offset:37888
	ds_read_b128 v[204:207], v141 offset:38912
	ds_read_b128 v[208:211], v141 offset:39936
	buffer_load_dwordx4 v137, s[12:15], s77 offen lds
	s_add_i32 s77, s74, 0x180000
	s_mov_b32 m0, s48
	s_nop 0
	buffer_load_dwordx4 v137, s[12:15], s77 offen lds
	s_waitcnt vmcnt(8)
	s_waitcnt lgkmcnt(0)
	s_setprio 1
	v_mfma_f32_16x16x32_bf16 v[118:121], v[148:151], v[180:183], v[118:121]
	v_mfma_f32_16x16x32_bf16 v[118:121], v[152:155], v[184:187], v[118:121]
	v_mfma_f32_16x16x32_bf16 v[114:117], v[156:159], v[180:183], v[114:117]
	v_mfma_f32_16x16x32_bf16 v[114:117], v[160:163], v[184:187], v[114:117]
	s_barrier
	v_mfma_f32_16x16x32_bf16 v[110:113], v[148:151], v[188:191], v[110:113]
	v_mfma_f32_16x16x32_bf16 v[110:113], v[152:155], v[192:195], v[110:113]
	v_mfma_f32_16x16x32_bf16 v[102:105], v[156:159], v[188:191], v[102:105]
	v_mfma_f32_16x16x32_bf16 v[102:105], v[160:163], v[192:195], v[102:105]
	v_mfma_f32_16x16x32_bf16 v[94:97], v[148:151], v[196:199], v[94:97]
	v_mfma_f32_16x16x32_bf16 v[94:97], v[152:155], v[200:203], v[94:97]
	v_mfma_f32_16x16x32_bf16 v[86:89], v[156:159], v[196:199], v[86:89]
	v_mfma_f32_16x16x32_bf16 v[86:89], v[160:163], v[200:203], v[86:89]
	v_mfma_f32_16x16x32_bf16 v[78:81], v[148:151], v[204:207], v[78:81]
	v_mfma_f32_16x16x32_bf16 v[78:81], v[152:155], v[208:211], v[78:81]
	v_mfma_f32_16x16x32_bf16 v[66:69], v[156:159], v[204:207], v[66:69]
	v_mfma_f32_16x16x32_bf16 v[66:69], v[160:163], v[208:211], v[66:69]
	v_mfma_f32_16x16x32_bf16 v[126:129], v[164:167], v[180:183], v[126:129]
	v_mfma_f32_16x16x32_bf16 v[126:129], v[168:171], v[184:187], v[126:129]
	v_mfma_f32_16x16x32_bf16 v[122:125], v[172:175], v[180:183], v[122:125]
	v_mfma_f32_16x16x32_bf16 v[122:125], v[176:179], v[184:187], v[122:125]
	v_mfma_f32_16x16x32_bf16 v[106:109], v[164:167], v[188:191], v[106:109]
	v_mfma_f32_16x16x32_bf16 v[106:109], v[168:171], v[192:195], v[106:109]
	v_mfma_f32_16x16x32_bf16 v[98:101], v[172:175], v[188:191], v[98:101]
	v_mfma_f32_16x16x32_bf16 v[98:101], v[176:179], v[192:195], v[98:101]
	v_mfma_f32_16x16x32_bf16 v[90:93], v[164:167], v[196:199], v[90:93]
	v_mfma_f32_16x16x32_bf16 v[90:93], v[168:171], v[200:203], v[90:93]
	v_mfma_f32_16x16x32_bf16 v[82:85], v[172:175], v[196:199], v[82:85]
	v_mfma_f32_16x16x32_bf16 v[82:85], v[176:179], v[200:203], v[82:85]
	v_mfma_f32_16x16x32_bf16 v[74:77], v[164:167], v[204:207], v[74:77]
	v_mfma_f32_16x16x32_bf16 v[74:77], v[168:171], v[208:211], v[74:77]
	v_mfma_f32_16x16x32_bf16 v[70:73], v[172:175], v[204:207], v[70:73]
	v_mfma_f32_16x16x32_bf16 v[70:73], v[176:179], v[208:211], v[70:73]
	s_setprio 0
	s_barrier
	s_mov_b32 m0, s50
	s_or_b32 s77, s76, 0x80
	ds_read_b128 v[180:183], v141 offset:49152
	ds_read_b128 v[184:187], v141 offset:50176
	ds_read_b128 v[188:191], v141 offset:51200
	ds_read_b128 v[192:195], v141 offset:52224
	ds_read_b128 v[196:199], v141 offset:53248
	ds_read_b128 v[200:203], v141 offset:54272
	ds_read_b128 v[204:207], v141 offset:55296
	ds_read_b128 v[208:211], v141 offset:56320
	buffer_load_dwordx4 v138, s[16:19], s77 offen lds
	s_add_i32 s77, s76, 0x80080
	s_mov_b32 m0, s51
	s_add_i32 s74, s74, 0x80080
	buffer_load_dwordx4 v138, s[16:19], s77 offen lds
	s_add_i32 s77, s76, 0x100080
	s_mov_b32 m0, s54
	s_add_i32 s76, s76, 0x180080
	buffer_load_dwordx4 v138, s[16:19], s77 offen lds
	s_mov_b32 m0, s55
	s_nop 0
	buffer_load_dwordx4 v138, s[16:19], s76 offen lds
	s_mov_b32 m0, s52
	s_nop 0
	buffer_load_dwordx4 v137, s[12:15], s75 offen lds
	s_mov_b32 m0, s53
	s_nop 0
	buffer_load_dwordx4 v137, s[12:15], s74 offen lds
	s_waitcnt vmcnt(8)
	s_waitcnt lgkmcnt(0)
	s_setprio 1
	v_mfma_f32_16x16x32_bf16 v[62:65], v[148:151], v[180:183], v[62:65]
	v_mfma_f32_16x16x32_bf16 v[62:65], v[152:155], v[184:187], v[62:65]
	v_mfma_f32_16x16x32_bf16 v[54:57], v[156:159], v[180:183], v[54:57]
	v_mfma_f32_16x16x32_bf16 v[54:57], v[160:163], v[184:187], v[54:57]
	s_barrier
	v_mfma_f32_16x16x32_bf16 v[46:49], v[148:151], v[188:191], v[46:49]
	v_mfma_f32_16x16x32_bf16 v[46:49], v[152:155], v[192:195], v[46:49]
	v_mfma_f32_16x16x32_bf16 v[38:41], v[156:159], v[188:191], v[38:41]
	v_mfma_f32_16x16x32_bf16 v[38:41], v[160:163], v[192:195], v[38:41]
	v_mfma_f32_16x16x32_bf16 v[30:33], v[148:151], v[196:199], v[30:33]
	v_mfma_f32_16x16x32_bf16 v[30:33], v[152:155], v[200:203], v[30:33]
	v_mfma_f32_16x16x32_bf16 v[22:25], v[156:159], v[196:199], v[22:25]
	v_mfma_f32_16x16x32_bf16 v[22:25], v[160:163], v[200:203], v[22:25]
	v_mfma_f32_16x16x32_bf16 v[14:17], v[148:151], v[204:207], v[14:17]
	v_mfma_f32_16x16x32_bf16 v[14:17], v[152:155], v[208:211], v[14:17]
	v_mfma_f32_16x16x32_bf16 v[6:9], v[156:159], v[204:207], v[6:9]
	v_mfma_f32_16x16x32_bf16 v[6:9], v[160:163], v[208:211], v[6:9]
	v_mfma_f32_16x16x32_bf16 v[58:61], v[164:167], v[180:183], v[58:61]
	v_mfma_f32_16x16x32_bf16 v[58:61], v[168:171], v[184:187], v[58:61]
	v_mfma_f32_16x16x32_bf16 v[50:53], v[172:175], v[180:183], v[50:53]
	v_mfma_f32_16x16x32_bf16 v[50:53], v[176:179], v[184:187], v[50:53]
	v_mfma_f32_16x16x32_bf16 v[42:45], v[164:167], v[188:191], v[42:45]
	v_mfma_f32_16x16x32_bf16 v[42:45], v[168:171], v[192:195], v[42:45]
	v_mfma_f32_16x16x32_bf16 v[34:37], v[172:175], v[188:191], v[34:37]
	v_mfma_f32_16x16x32_bf16 v[34:37], v[176:179], v[192:195], v[34:37]
	v_mfma_f32_16x16x32_bf16 v[26:29], v[164:167], v[196:199], v[26:29]
	v_mfma_f32_16x16x32_bf16 v[26:29], v[168:171], v[200:203], v[26:29]
	v_mfma_f32_16x16x32_bf16 v[18:21], v[172:175], v[196:199], v[18:21]
	v_mfma_f32_16x16x32_bf16 v[18:21], v[176:179], v[200:203], v[18:21]
	v_mfma_f32_16x16x32_bf16 v[10:13], v[164:167], v[204:207], v[10:13]
	v_mfma_f32_16x16x32_bf16 v[10:13], v[168:171], v[208:211], v[10:13]
	v_mfma_f32_16x16x32_bf16 v[2:5], v[172:175], v[204:207], v[2:5]
	v_mfma_f32_16x16x32_bf16 v[2:5], v[176:179], v[208:211], v[2:5]
	s_setprio 0
	s_barrier
	s_add_i32 s73, s73, 2
	s_addk_i32 s71, 0x100
	s_addk_i32 s72, 0x100
	s_cmp_ge_i32 s73, s3
	s_cbranch_scc0 .LBB0_642
	s_and_b64 vcc, exec, s[42:43]
	s_cbranch_vccz .LBB0_645

.LBB0_799:
	ds_read_b128 v[134:137], v210
	ds_read_b128 v[138:141], v210 offset:1024
	ds_read_b128 v[142:145], v210 offset:2048
	ds_read_b128 v[148:151], v210 offset:3072
	ds_read_b128 v[152:155], v211
	ds_read_b128 v[156:159], v211 offset:1024
	ds_read_b128 v[160:163], v211 offset:2048
	ds_read_b128 v[164:167], v211 offset:3072
	s_add_i32 s18, s77, 0xffbf8080
	s_cmp_eq_u32 s62, s79
	s_cselect_b32 s80, s6, s18
	s_cselect_b32 s82, s7, s78
	s_or_b32 s81, s80, 0x80
	s_add_i32 s18, s77, 0xffea8000
	s_mov_b32 m0, s63
	ds_read_b128 v[168:171], v212
	ds_read_b128 v[172:175], v212 offset:1024
	ds_read_b128 v[176:179], v212 offset:2048
	ds_read_b128 v[180:183], v212 offset:3072
	ds_read_b128 v[184:187], v212 offset:4096
	ds_read_b128 v[188:191], v212 offset:5120
	ds_read_b128 v[192:195], v212 offset:6144
	ds_read_b128 v[196:199], v212 offset:7168
	buffer_load_dwordx4 v208, s[12:15], s18 offen lds
	s_mov_b32 m0, s66
	s_nop 0
	buffer_load_dwordx4 v208, s[12:15], s77 offen lds
	s_waitcnt vmcnt(8)
	s_waitcnt lgkmcnt(0)
	s_setprio 1
	v_mfma_f32_16x16x32_bf16 v[126:129], v[134:137], v[168:171], v[126:129]
	v_mfma_f32_16x16x32_bf16 v[126:129], v[138:141], v[172:175], v[126:129]
	v_mfma_f32_16x16x32_bf16 v[122:125], v[142:145], v[168:171], v[122:125]
	v_mfma_f32_16x16x32_bf16 v[122:125], v[148:151], v[172:175], v[122:125]
	s_barrier
	v_mfma_f32_16x16x32_bf16 v[118:121], v[134:137], v[176:179], v[118:121]
	v_mfma_f32_16x16x32_bf16 v[118:121], v[138:141], v[180:183], v[118:121]
	v_mfma_f32_16x16x32_bf16 v[114:117], v[142:145], v[176:179], v[114:117]
	v_mfma_f32_16x16x32_bf16 v[114:117], v[148:151], v[180:183], v[114:117]
	v_mfma_f32_16x16x32_bf16 v[106:109], v[134:137], v[184:187], v[106:109]
	v_mfma_f32_16x16x32_bf16 v[106:109], v[138:141], v[188:191], v[106:109]
	v_mfma_f32_16x16x32_bf16 v[98:101], v[142:145], v[184:187], v[98:101]
	v_mfma_f32_16x16x32_bf16 v[98:101], v[148:151], v[188:191], v[98:101]
	v_mfma_f32_16x16x32_bf16 v[90:93], v[134:137], v[192:195], v[90:93]
	v_mfma_f32_16x16x32_bf16 v[90:93], v[138:141], v[196:199], v[90:93]
	v_mfma_f32_16x16x32_bf16 v[82:85], v[142:145], v[192:195], v[82:85]
	v_mfma_f32_16x16x32_bf16 v[82:85], v[148:151], v[196:199], v[82:85]
	v_mfma_f32_16x16x32_bf16 v[110:113], v[152:155], v[168:171], v[110:113]
	v_mfma_f32_16x16x32_bf16 v[110:113], v[156:159], v[172:175], v[110:113]
	v_mfma_f32_16x16x32_bf16 v[102:105], v[160:163], v[168:171], v[102:105]
	v_mfma_f32_16x16x32_bf16 v[102:105], v[164:167], v[172:175], v[102:105]
	v_mfma_f32_16x16x32_bf16 v[94:97], v[152:155], v[176:179], v[94:97]
	v_mfma_f32_16x16x32_bf16 v[94:97], v[156:159], v[180:183], v[94:97]
	v_mfma_f32_16x16x32_bf16 v[86:89], v[160:163], v[176:179], v[86:89]
	v_mfma_f32_16x16x32_bf16 v[86:89], v[164:167], v[180:183], v[86:89]
	v_mfma_f32_16x16x32_bf16 v[78:81], v[152:155], v[184:187], v[78:81]
	v_mfma_f32_16x16x32_bf16 v[78:81], v[156:159], v[188:191], v[78:81]
	v_mfma_f32_16x16x32_bf16 v[74:77], v[160:163], v[184:187], v[74:77]
	v_mfma_f32_16x16x32_bf16 v[74:77], v[164:167], v[188:191], v[74:77]
	v_mfma_f32_16x16x32_bf16 v[70:73], v[152:155], v[192:195], v[70:73]
	v_mfma_f32_16x16x32_bf16 v[70:73], v[156:159], v[196:199], v[70:73]
	v_mfma_f32_16x16x32_bf16 v[66:69], v[160:163], v[192:195], v[66:69]
	v_mfma_f32_16x16x32_bf16 v[66:69], v[164:167], v[196:199], v[66:69]
	s_setprio 0
	s_barrier
	s_mov_b32 m0, s25
	s_mov_b32 s18, s14
	s_mov_b32 s19, s15
	ds_read_b128 v[168:171], v212 offset:16384
	ds_read_b128 v[172:175], v212 offset:17408
	ds_read_b128 v[176:179], v212 offset:18432
	ds_read_b128 v[180:183], v212 offset:19456
	ds_read_b128 v[184:187], v212 offset:20480
	ds_read_b128 v[188:191], v212 offset:21504
	ds_read_b128 v[192:195], v212 offset:22528
	ds_read_b128 v[196:199], v212 offset:23552
	buffer_load_dwordx4 v209, s[16:19], s82 offen lds
	s_add_i32 s83, s82, 0x158000
	s_mov_b32 m0, s27
	s_nop 0
	buffer_load_dwordx4 v209, s[16:19], s83 offen lds
	s_add_i32 s83, s82, 0x2b0000
	s_mov_b32 m0, s30
	s_nop 0
	buffer_load_dwordx4 v209, s[16:19], s83 offen lds
	s_add_i32 s83, s82, 0x408000
	s_mov_b32 m0, s31
	s_nop 0
	buffer_load_dwordx4 v209, s[16:19], s83 offen lds
	s_mov_b32 m0, s21
	s_add_i32 s83, s80, 0x158000
	buffer_load_dwordx4 v208, s[12:15], s80 offen lds
	s_mov_b32 m0, s48
	s_nop 0
	buffer_load_dwordx4 v208, s[12:15], s83 offen lds
	s_waitcnt vmcnt(8)
	s_waitcnt lgkmcnt(0)
	s_setprio 1
	v_mfma_f32_16x16x32_bf16 v[62:65], v[134:137], v[168:171], v[62:65]
	v_mfma_f32_16x16x32_bf16 v[62:65], v[138:141], v[172:175], v[62:65]
	v_mfma_f32_16x16x32_bf16 v[58:61], v[142:145], v[168:171], v[58:61]
	v_mfma_f32_16x16x32_bf16 v[58:61], v[148:151], v[172:175], v[58:61]
	s_barrier
	v_mfma_f32_16x16x32_bf16 v[54:57], v[134:137], v[176:179], v[54:57]
	v_mfma_f32_16x16x32_bf16 v[54:57], v[138:141], v[180:183], v[54:57]
	v_mfma_f32_16x16x32_bf16 v[50:53], v[142:145], v[176:179], v[50:53]
	v_mfma_f32_16x16x32_bf16 v[50:53], v[148:151], v[180:183], v[50:53]
	v_mfma_f32_16x16x32_bf16 v[42:45], v[134:137], v[184:187], v[42:45]
	v_mfma_f32_16x16x32_bf16 v[42:45], v[138:141], v[188:191], v[42:45]
	v_mfma_f32_16x16x32_bf16 v[34:37], v[142:145], v[184:187], v[34:37]
	v_mfma_f32_16x16x32_bf16 v[34:37], v[148:151], v[188:191], v[34:37]
	v_mfma_f32_16x16x32_bf16 v[26:29], v[134:137], v[192:195], v[26:29]
	v_mfma_f32_16x16x32_bf16 v[26:29], v[138:141], v[196:199], v[26:29]
	v_mfma_f32_16x16x32_bf16 v[18:21], v[142:145], v[192:195], v[18:21]
	v_mfma_f32_16x16x32_bf16 v[18:21], v[148:151], v[196:199], v[18:21]
	v_mfma_f32_16x16x32_bf16 v[46:49], v[152:155], v[168:171], v[46:49]
	v_mfma_f32_16x16x32_bf16 v[46:49], v[156:159], v[172:175], v[46:49]
	v_mfma_f32_16x16x32_bf16 v[38:41], v[160:163], v[168:171], v[38:41]
	v_mfma_f32_16x16x32_bf16 v[38:41], v[164:167], v[172:175], v[38:41]
	v_mfma_f32_16x16x32_bf16 v[30:33], v[152:155], v[176:179], v[30:33]
	v_mfma_f32_16x16x32_bf16 v[30:33], v[156:159], v[180:183], v[30:33]
	v_mfma_f32_16x16x32_bf16 v[22:25], v[160:163], v[176:179], v[22:25]
	v_mfma_f32_16x16x32_bf16 v[22:25], v[164:167], v[180:183], v[22:25]
	v_mfma_f32_16x16x32_bf16 v[14:17], v[152:155], v[184:187], v[14:17]
	v_mfma_f32_16x16x32_bf16 v[14:17], v[156:159], v[188:191], v[14:17]
	v_mfma_f32_16x16x32_bf16 v[10:13], v[160:163], v[184:187], v[10:13]
	v_mfma_f32_16x16x32_bf16 v[10:13], v[164:167], v[188:191], v[10:13]
	v_mfma_f32_16x16x32_bf16 v[6:9], v[152:155], v[192:195], v[6:9]
	v_mfma_f32_16x16x32_bf16 v[6:9], v[156:159], v[196:199], v[6:9]
	v_mfma_f32_16x16x32_bf16 v[2:5], v[160:163], v[192:195], v[2:5]
	v_mfma_f32_16x16x32_bf16 v[2:5], v[164:167], v[196:199], v[2:5]
	s_setprio 0
	s_barrier
	ds_read_b128 v[134:137], v213
	ds_read_b128 v[138:141], v213 offset:1024
	ds_read_b128 v[142:145], v213 offset:2048
	ds_read_b128 v[148:151], v213 offset:3072
	ds_read_b128 v[152:155], v214
	ds_read_b128 v[156:159], v214 offset:1024
	ds_read_b128 v[160:163], v214 offset:2048
	ds_read_b128 v[164:167], v214 offset:3072
	s_mov_b32 m0, s49
	s_add_i32 s83, s80, 0x2b0000
	ds_read_b128 v[168:171], v212 offset:32768
	ds_read_b128 v[172:175], v212 offset:33792
	ds_read_b128 v[176:179], v212 offset:34816
	ds_read_b128 v[180:183], v212 offset:35840
	ds_read_b128 v[184:187], v212 offset:36864
	ds_read_b128 v[188:191], v212 offset:37888
	ds_read_b128 v[192:195], v212 offset:38912
	ds_read_b128 v[196:199], v212 offset:39936
	buffer_load_dwordx4 v208, s[12:15], s83 offen lds
	s_add_i32 s83, s80, 0x408000
	s_mov_b32 m0, s50
	s_nop 0
	buffer_load_dwordx4 v208, s[12:15], s83 offen lds
	s_waitcnt vmcnt(8)
	s_waitcnt lgkmcnt(0)
	s_setprio 1
	v_mfma_f32_16x16x32_bf16 v[126:129], v[134:137], v[168:171], v[126:129]
	v_mfma_f32_16x16x32_bf16 v[126:129], v[138:141], v[172:175], v[126:129]
	v_mfma_f32_16x16x32_bf16 v[122:125], v[142:145], v[168:171], v[122:125]
	v_mfma_f32_16x16x32_bf16 v[122:125], v[148:151], v[172:175], v[122:125]
	s_barrier
	v_mfma_f32_16x16x32_bf16 v[118:121], v[134:137], v[176:179], v[118:121]
	v_mfma_f32_16x16x32_bf16 v[118:121], v[138:141], v[180:183], v[118:121]
	v_mfma_f32_16x16x32_bf16 v[114:117], v[142:145], v[176:179], v[114:117]
	v_mfma_f32_16x16x32_bf16 v[114:117], v[148:151], v[180:183], v[114:117]
	v_mfma_f32_16x16x32_bf16 v[106:109], v[134:137], v[184:187], v[106:109]
	v_mfma_f32_16x16x32_bf16 v[106:109], v[138:141], v[188:191], v[106:109]
	v_mfma_f32_16x16x32_bf16 v[98:101], v[142:145], v[184:187], v[98:101]
	v_mfma_f32_16x16x32_bf16 v[98:101], v[148:151], v[188:191], v[98:101]
	v_mfma_f32_16x16x32_bf16 v[90:93], v[134:137], v[192:195], v[90:93]
	v_mfma_f32_16x16x32_bf16 v[90:93], v[138:141], v[196:199], v[90:93]
	v_mfma_f32_16x16x32_bf16 v[82:85], v[142:145], v[192:195], v[82:85]
	v_mfma_f32_16x16x32_bf16 v[82:85], v[148:151], v[196:199], v[82:85]
	v_mfma_f32_16x16x32_bf16 v[110:113], v[152:155], v[168:171], v[110:113]
	v_mfma_f32_16x16x32_bf16 v[110:113], v[156:159], v[172:175], v[110:113]
	v_mfma_f32_16x16x32_bf16 v[102:105], v[160:163], v[168:171], v[102:105]
	v_mfma_f32_16x16x32_bf16 v[102:105], v[164:167], v[172:175], v[102:105]
	v_mfma_f32_16x16x32_bf16 v[94:97], v[152:155], v[176:179], v[94:97]
	v_mfma_f32_16x16x32_bf16 v[94:97], v[156:159], v[180:183], v[94:97]
	v_mfma_f32_16x16x32_bf16 v[86:89], v[160:163], v[176:179], v[86:89]
	v_mfma_f32_16x16x32_bf16 v[86:89], v[164:167], v[180:183], v[86:89]
	v_mfma_f32_16x16x32_bf16 v[78:81], v[152:155], v[184:187], v[78:81]
	v_mfma_f32_16x16x32_bf16 v[78:81], v[156:159], v[188:191], v[78:81]
	v_mfma_f32_16x16x32_bf16 v[74:77], v[160:163], v[184:187], v[74:77]
	v_mfma_f32_16x16x32_bf16 v[74:77], v[164:167], v[188:191], v[74:77]
	v_mfma_f32_16x16x32_bf16 v[70:73], v[152:155], v[192:195], v[70:73]
	v_mfma_f32_16x16x32_bf16 v[70:73], v[156:159], v[196:199], v[70:73]
	v_mfma_f32_16x16x32_bf16 v[66:69], v[160:163], v[192:195], v[66:69]
	v_mfma_f32_16x16x32_bf16 v[66:69], v[164:167], v[196:199], v[66:69]
	s_setprio 0
	s_barrier
	s_mov_b32 m0, s54
	s_or_b32 s83, s82, 0x80
	ds_read_b128 v[168:171], v212 offset:49152
	ds_read_b128 v[172:175], v212 offset:50176
	ds_read_b128 v[176:179], v212 offset:51200
	ds_read_b128 v[180:183], v212 offset:52224
	ds_read_b128 v[184:187], v212 offset:53248
	ds_read_b128 v[188:191], v212 offset:54272
	ds_read_b128 v[192:195], v212 offset:55296
	ds_read_b128 v[196:199], v212 offset:56320
	buffer_load_dwordx4 v209, s[16:19], s83 offen lds
	s_add_i32 s83, s82, 0x158080
	s_mov_b32 m0, s55
	s_add_i32 s80, s80, 0x158080
	buffer_load_dwordx4 v209, s[16:19], s83 offen lds
	s_add_i32 s83, s82, 0x2b0080
	s_mov_b32 m0, s58
	s_add_i32 s82, s82, 0x408080
	buffer_load_dwordx4 v209, s[16:19], s83 offen lds
	s_mov_b32 m0, s59
	s_nop 0
	buffer_load_dwordx4 v209, s[16:19], s82 offen lds
	s_mov_b32 m0, s56
	s_nop 0
	buffer_load_dwordx4 v208, s[12:15], s81 offen lds
	s_mov_b32 m0, s57
	s_nop 0
	buffer_load_dwordx4 v208, s[12:15], s80 offen lds
	s_waitcnt vmcnt(8)
	s_waitcnt lgkmcnt(0)
	s_setprio 1
	v_mfma_f32_16x16x32_bf16 v[62:65], v[134:137], v[168:171], v[62:65]
	v_mfma_f32_16x16x32_bf16 v[62:65], v[138:141], v[172:175], v[62:65]
	v_mfma_f32_16x16x32_bf16 v[58:61], v[142:145], v[168:171], v[58:61]
	v_mfma_f32_16x16x32_bf16 v[58:61], v[148:151], v[172:175], v[58:61]
	s_barrier
	v_mfma_f32_16x16x32_bf16 v[54:57], v[134:137], v[176:179], v[54:57]
	v_mfma_f32_16x16x32_bf16 v[54:57], v[138:141], v[180:183], v[54:57]
	v_mfma_f32_16x16x32_bf16 v[50:53], v[142:145], v[176:179], v[50:53]
	v_mfma_f32_16x16x32_bf16 v[50:53], v[148:151], v[180:183], v[50:53]
	v_mfma_f32_16x16x32_bf16 v[42:45], v[134:137], v[184:187], v[42:45]
	v_mfma_f32_16x16x32_bf16 v[42:45], v[138:141], v[188:191], v[42:45]
	v_mfma_f32_16x16x32_bf16 v[34:37], v[142:145], v[184:187], v[34:37]
	v_mfma_f32_16x16x32_bf16 v[34:37], v[148:151], v[188:191], v[34:37]
	v_mfma_f32_16x16x32_bf16 v[26:29], v[134:137], v[192:195], v[26:29]
	v_mfma_f32_16x16x32_bf16 v[26:29], v[138:141], v[196:199], v[26:29]
	v_mfma_f32_16x16x32_bf16 v[18:21], v[142:145], v[192:195], v[18:21]
	v_mfma_f32_16x16x32_bf16 v[18:21], v[148:151], v[196:199], v[18:21]
	v_mfma_f32_16x16x32_bf16 v[46:49], v[152:155], v[168:171], v[46:49]
	v_mfma_f32_16x16x32_bf16 v[46:49], v[156:159], v[172:175], v[46:49]
	v_mfma_f32_16x16x32_bf16 v[38:41], v[160:163], v[168:171], v[38:41]
	v_mfma_f32_16x16x32_bf16 v[38:41], v[164:167], v[172:175], v[38:41]
	v_mfma_f32_16x16x32_bf16 v[30:33], v[152:155], v[176:179], v[30:33]
	v_mfma_f32_16x16x32_bf16 v[30:33], v[156:159], v[180:183], v[30:33]
	v_mfma_f32_16x16x32_bf16 v[22:25], v[160:163], v[176:179], v[22:25]
	v_mfma_f32_16x16x32_bf16 v[22:25], v[164:167], v[180:183], v[22:25]
	v_mfma_f32_16x16x32_bf16 v[14:17], v[152:155], v[184:187], v[14:17]
	v_mfma_f32_16x16x32_bf16 v[14:17], v[156:159], v[188:191], v[14:17]
	v_mfma_f32_16x16x32_bf16 v[10:13], v[160:163], v[184:187], v[10:13]
	v_mfma_f32_16x16x32_bf16 v[10:13], v[164:167], v[188:191], v[10:13]
	v_mfma_f32_16x16x32_bf16 v[6:9], v[152:155], v[192:195], v[6:9]
	v_mfma_f32_16x16x32_bf16 v[6:9], v[156:159], v[196:199], v[6:9]
	v_mfma_f32_16x16x32_bf16 v[2:5], v[160:163], v[192:195], v[2:5]
	v_mfma_f32_16x16x32_bf16 v[2:5], v[164:167], v[196:199], v[2:5]
	s_setprio 0
	s_barrier
	s_add_i32 s79, s79, 2
	s_addk_i32 s77, 0x100
	s_addk_i32 s78, 0x100
	s_cmp_ge_i32 s79, s3
	s_cbranch_scc0 .LBB0_799
	v_pk_mul_f32 v[184:185], v[128:129], 0.5 op_sel_hi:[1,0]
	v_pk_mul_f32 v[186:187], v[126:127], 0.5 op_sel_hi:[1,0]
	v_pk_mul_f32 v[188:189], v[124:125], 0.5 op_sel_hi:[1,0]
	v_pk_mul_f32 v[190:191], v[122:123], 0.5 op_sel_hi:[1,0]
	v_pk_mul_f32 v[198:199], v[112:113], 0.5 op_sel_hi:[1,0]
	v_pk_mul_f32 v[196:197], v[110:111], 0.5 op_sel_hi:[1,0]
	v_pk_mul_f32 v[194:195], v[104:105], 0.5 op_sel_hi:[1,0]
	v_pk_mul_f32 v[192:193], v[102:103], 0.5 op_sel_hi:[1,0]
	v_pk_mul_f32 v[182:183], v[120:121], 0.5 op_sel_hi:[1,0]
	v_pk_mul_f32 v[180:181], v[118:119], 0.5 op_sel_hi:[1,0]
	v_pk_mul_f32 v[178:179], v[116:117], 0.5 op_sel_hi:[1,0]
	v_pk_mul_f32 v[176:177], v[114:115], 0.5 op_sel_hi:[1,0]
	v_pk_mul_f32 v[172:173], v[96:97], 0.5 op_sel_hi:[1,0]
	v_pk_mul_f32 v[170:171], v[94:95], 0.5 op_sel_hi:[1,0]
	v_pk_mul_f32 v[168:169], v[88:89], 0.5 op_sel_hi:[1,0]
	v_pk_mul_f32 v[166:167], v[86:87], 0.5 op_sel_hi:[1,0]
	v_pk_mul_f32 v[164:165], v[108:109], 0.5 op_sel_hi:[1,0]
	v_pk_mul_f32 v[162:163], v[106:107], 0.5 op_sel_hi:[1,0]
	v_pk_mul_f32 v[160:161], v[100:101], 0.5 op_sel_hi:[1,0]
	v_pk_mul_f32 v[158:159], v[98:99], 0.5 op_sel_hi:[1,0]
	v_pk_mul_f32 v[156:157], v[80:81], 0.5 op_sel_hi:[1,0]
	v_pk_mul_f32 v[154:155], v[78:79], 0.5 op_sel_hi:[1,0]
	v_pk_mul_f32 v[152:153], v[76:77], 0.5 op_sel_hi:[1,0]
	v_pk_mul_f32 v[150:151], v[74:75], 0.5 op_sel_hi:[1,0]
	v_pk_mul_f32 v[144:145], v[92:93], 0.5 op_sel_hi:[1,0]
	v_pk_mul_f32 v[142:143], v[90:91], 0.5 op_sel_hi:[1,0]
	v_pk_mul_f32 v[140:141], v[84:85], 0.5 op_sel_hi:[1,0]
	v_pk_mul_f32 v[138:139], v[82:83], 0.5 op_sel_hi:[1,0]
	v_pk_mul_f32 v[136:137], v[72:73], 0.5 op_sel_hi:[1,0]
	v_pk_mul_f32 v[134:135], v[70:71], 0.5 op_sel_hi:[1,0]
	v_pk_mul_f32 v[128:129], v[68:69], 0.5 op_sel_hi:[1,0]
	v_pk_mul_f32 v[126:127], v[66:67], 0.5 op_sel_hi:[1,0]
	v_pk_mul_f32 v[122:123], v[64:65], 0.5 op_sel_hi:[1,0]
	v_pk_mul_f32 v[120:121], v[62:63], 0.5 op_sel_hi:[1,0]
	v_pk_mul_f32 v[118:119], v[60:61], 0.5 op_sel_hi:[1,0]
	v_pk_mul_f32 v[116:117], v[58:59], 0.5 op_sel_hi:[1,0]
	v_pk_mul_f32 v[112:113], v[48:49], 0.5 op_sel_hi:[1,0]
	v_pk_mul_f32 v[110:111], v[46:47], 0.5 op_sel_hi:[1,0]
	v_pk_mul_f32 v[108:109], v[40:41], 0.5 op_sel_hi:[1,0]
	v_pk_mul_f32 v[106:107], v[38:39], 0.5 op_sel_hi:[1,0]
	v_pk_mul_f32 v[104:105], v[56:57], 0.5 op_sel_hi:[1,0]
	v_pk_mul_f32 v[102:103], v[54:55], 0.5 op_sel_hi:[1,0]
	v_pk_mul_f32 v[100:101], v[52:53], 0.5 op_sel_hi:[1,0]
	v_pk_mul_f32 v[98:99], v[50:51], 0.5 op_sel_hi:[1,0]
	v_pk_mul_f32 v[96:97], v[32:33], 0.5 op_sel_hi:[1,0]
	v_pk_mul_f32 v[94:95], v[30:31], 0.5 op_sel_hi:[1,0]
	v_pk_mul_f32 v[92:93], v[24:25], 0.5 op_sel_hi:[1,0]
	v_pk_mul_f32 v[90:91], v[22:23], 0.5 op_sel_hi:[1,0]
	v_pk_mul_f32 v[88:89], v[44:45], 0.5 op_sel_hi:[1,0]
	v_pk_mul_f32 v[86:87], v[42:43], 0.5 op_sel_hi:[1,0]
	v_pk_mul_f32 v[84:85], v[36:37], 0.5 op_sel_hi:[1,0]
	v_pk_mul_f32 v[82:83], v[34:35], 0.5 op_sel_hi:[1,0]
	v_pk_mul_f32 v[80:81], v[16:17], 0.5 op_sel_hi:[1,0]
	v_pk_mul_f32 v[78:79], v[14:15], 0.5 op_sel_hi:[1,0]
	v_pk_mul_f32 v[76:77], v[12:13], 0.5 op_sel_hi:[1,0]
	v_pk_mul_f32 v[74:75], v[10:11], 0.5 op_sel_hi:[1,0]
	v_pk_mul_f32 v[72:73], v[28:29], 0.5 op_sel_hi:[1,0]
	v_pk_mul_f32 v[70:71], v[26:27], 0.5 op_sel_hi:[1,0]
	v_pk_mul_f32 v[68:69], v[20:21], 0.5 op_sel_hi:[1,0]
	v_pk_mul_f32 v[66:67], v[18:19], 0.5 op_sel_hi:[1,0]
	v_pk_mul_f32 v[64:65], v[8:9], 0.5 op_sel_hi:[1,0]
	v_pk_mul_f32 v[62:63], v[6:7], 0.5 op_sel_hi:[1,0]
	v_pk_mul_f32 v[60:61], v[4:5], 0.5 op_sel_hi:[1,0]
	v_pk_mul_f32 v[58:59], v[2:3], 0.5 op_sel_hi:[1,0]
	s_and_b64 vcc, exec, s[38:39]
	s_cbranch_vccz .LBB0_802

.LBB0_892:
	ds_read_b128 v[130:133], v172
	ds_read_b128 v[134:137], v172 offset:1024
	ds_read_b128 v[148:151], v172 offset:2048
	ds_read_b128 v[152:155], v172 offset:3072
	ds_read_b128 v[156:159], v173
	ds_read_b128 v[160:163], v173 offset:1024
	ds_read_b128 v[164:167], v173 offset:2048
	ds_read_b128 v[180:183], v173 offset:3072
	s_add_i32 s18, s8, 0xffe80080
	s_cmp_eq_u32 s77, s52
	s_cselect_b32 s53, s6, s18
	s_cselect_b32 s58, s7, s9
	s_or_b32 s57, s53, 0x80
	s_add_i32 s18, s8, 0xfff80000
	s_mov_b32 m0, s78
	ds_read_b128 v[184:187], v174
	ds_read_b128 v[188:191], v174 offset:1024
	ds_read_b128 v[192:195], v174 offset:2048
	ds_read_b128 v[196:199], v174 offset:3072
	ds_read_b128 v[200:203], v174 offset:4096
	ds_read_b128 v[204:207], v174 offset:5120
	ds_read_b128 v[208:211], v174 offset:6144
	ds_read_b128 v[212:215], v174 offset:7168
	buffer_load_dwordx4 v170, s[12:15], s18 offen lds
	s_mov_b32 m0, s79
	s_nop 0
	buffer_load_dwordx4 v170, s[12:15], s8 offen lds
	s_waitcnt vmcnt(8)
	s_waitcnt lgkmcnt(0)
	s_setprio 1
	v_mfma_f32_16x16x32_bf16 v[126:129], v[130:133], v[184:187], v[126:129]
	v_mfma_f32_16x16x32_bf16 v[126:129], v[134:137], v[188:191], v[126:129]
	v_mfma_f32_16x16x32_bf16 v[118:121], v[148:151], v[184:187], v[118:121]
	v_mfma_f32_16x16x32_bf16 v[118:121], v[152:155], v[188:191], v[118:121]
	s_barrier
	v_mfma_f32_16x16x32_bf16 v[110:113], v[130:133], v[192:195], v[110:113]
	v_mfma_f32_16x16x32_bf16 v[110:113], v[134:137], v[196:199], v[110:113]
	v_mfma_f32_16x16x32_bf16 v[102:105], v[148:151], v[192:195], v[102:105]
	v_mfma_f32_16x16x32_bf16 v[102:105], v[152:155], v[196:199], v[102:105]
	v_mfma_f32_16x16x32_bf16 v[94:97], v[130:133], v[200:203], v[94:97]
	v_mfma_f32_16x16x32_bf16 v[94:97], v[134:137], v[204:207], v[94:97]
	v_mfma_f32_16x16x32_bf16 v[90:93], v[148:151], v[200:203], v[90:93]
	v_mfma_f32_16x16x32_bf16 v[90:93], v[152:155], v[204:207], v[90:93]
	v_mfma_f32_16x16x32_bf16 v[78:81], v[130:133], v[208:211], v[78:81]
	v_mfma_f32_16x16x32_bf16 v[78:81], v[134:137], v[212:215], v[78:81]
	v_mfma_f32_16x16x32_bf16 v[70:73], v[148:151], v[208:211], v[70:73]
	v_mfma_f32_16x16x32_bf16 v[70:73], v[152:155], v[212:215], v[70:73]
	v_mfma_f32_16x16x32_bf16 v[122:125], v[156:159], v[184:187], v[122:125]
	v_mfma_f32_16x16x32_bf16 v[122:125], v[160:163], v[188:191], v[122:125]
	v_mfma_f32_16x16x32_bf16 v[114:117], v[164:167], v[184:187], v[114:117]
	v_mfma_f32_16x16x32_bf16 v[114:117], v[180:183], v[188:191], v[114:117]
	v_mfma_f32_16x16x32_bf16 v[106:109], v[156:159], v[192:195], v[106:109]
	v_mfma_f32_16x16x32_bf16 v[106:109], v[160:163], v[196:199], v[106:109]
	v_mfma_f32_16x16x32_bf16 v[98:101], v[164:167], v[192:195], v[98:101]
	v_mfma_f32_16x16x32_bf16 v[98:101], v[180:183], v[196:199], v[98:101]
	v_mfma_f32_16x16x32_bf16 v[86:89], v[156:159], v[200:203], v[86:89]
	v_mfma_f32_16x16x32_bf16 v[86:89], v[160:163], v[204:207], v[86:89]
	v_mfma_f32_16x16x32_bf16 v[82:85], v[164:167], v[200:203], v[82:85]
	v_mfma_f32_16x16x32_bf16 v[82:85], v[180:183], v[204:207], v[82:85]
	v_mfma_f32_16x16x32_bf16 v[74:77], v[156:159], v[208:211], v[74:77]
	v_mfma_f32_16x16x32_bf16 v[74:77], v[160:163], v[212:215], v[74:77]
	v_mfma_f32_16x16x32_bf16 v[66:69], v[164:167], v[208:211], v[66:69]
	v_mfma_f32_16x16x32_bf16 v[66:69], v[180:183], v[212:215], v[66:69]
	s_setprio 0
	s_barrier
	s_mov_b32 m0, s27
	s_mov_b32 s18, s14
	s_mov_b32 s19, s15
	ds_read_b128 v[184:187], v174 offset:16384
	ds_read_b128 v[188:191], v174 offset:17408
	ds_read_b128 v[192:195], v174 offset:18432
	ds_read_b128 v[196:199], v174 offset:19456
	ds_read_b128 v[200:203], v174 offset:20480
	ds_read_b128 v[204:207], v174 offset:21504
	ds_read_b128 v[208:211], v174 offset:22528
	ds_read_b128 v[212:215], v174 offset:23552
	buffer_load_dwordx4 v171, s[16:19], s58 offen lds
	s_add_i32 s59, s58, 0x80000
	s_mov_b32 m0, s60
	s_nop 0
	buffer_load_dwordx4 v171, s[16:19], s59 offen lds
	s_add_i32 s59, s58, 0x100000
	s_mov_b32 m0, s61
	s_nop 0
	buffer_load_dwordx4 v171, s[16:19], s59 offen lds
	s_add_i32 s59, s58, 0x180000
	s_mov_b32 m0, s62
	s_nop 0
	buffer_load_dwordx4 v171, s[16:19], s59 offen lds
	s_mov_b32 m0, s25
	s_add_i32 s59, s53, 0x80000
	buffer_load_dwordx4 v170, s[12:15], s53 offen lds
	s_mov_b32 m0, s63
	s_nop 0
	buffer_load_dwordx4 v170, s[12:15], s59 offen lds
	s_waitcnt vmcnt(8)
	s_waitcnt lgkmcnt(0)
	s_setprio 1
	v_mfma_f32_16x16x32_bf16 v[62:65], v[130:133], v[184:187], v[62:65]
	v_mfma_f32_16x16x32_bf16 v[62:65], v[134:137], v[188:191], v[62:65]
	v_mfma_f32_16x16x32_bf16 v[54:57], v[148:151], v[184:187], v[54:57]
	v_mfma_f32_16x16x32_bf16 v[54:57], v[152:155], v[188:191], v[54:57]
	s_barrier
	v_mfma_f32_16x16x32_bf16 v[46:49], v[130:133], v[192:195], v[46:49]
	v_mfma_f32_16x16x32_bf16 v[46:49], v[134:137], v[196:199], v[46:49]
	v_mfma_f32_16x16x32_bf16 v[38:41], v[148:151], v[192:195], v[38:41]
	v_mfma_f32_16x16x32_bf16 v[38:41], v[152:155], v[196:199], v[38:41]
	v_mfma_f32_16x16x32_bf16 v[30:33], v[130:133], v[200:203], v[30:33]
	v_mfma_f32_16x16x32_bf16 v[30:33], v[134:137], v[204:207], v[30:33]
	v_mfma_f32_16x16x32_bf16 v[22:25], v[148:151], v[200:203], v[22:25]
	v_mfma_f32_16x16x32_bf16 v[22:25], v[152:155], v[204:207], v[22:25]
	v_mfma_f32_16x16x32_bf16 v[14:17], v[130:133], v[208:211], v[14:17]
	v_mfma_f32_16x16x32_bf16 v[14:17], v[134:137], v[212:215], v[14:17]
	v_mfma_f32_16x16x32_bf16 v[6:9], v[148:151], v[208:211], v[6:9]
	v_mfma_f32_16x16x32_bf16 v[6:9], v[152:155], v[212:215], v[6:9]
	v_mfma_f32_16x16x32_bf16 v[58:61], v[156:159], v[184:187], v[58:61]
	v_mfma_f32_16x16x32_bf16 v[58:61], v[160:163], v[188:191], v[58:61]
	v_mfma_f32_16x16x32_bf16 v[50:53], v[164:167], v[184:187], v[50:53]
	v_mfma_f32_16x16x32_bf16 v[50:53], v[180:183], v[188:191], v[50:53]
	v_mfma_f32_16x16x32_bf16 v[42:45], v[156:159], v[192:195], v[42:45]
	v_mfma_f32_16x16x32_bf16 v[42:45], v[160:163], v[196:199], v[42:45]
	v_mfma_f32_16x16x32_bf16 v[34:37], v[164:167], v[192:195], v[34:37]
	v_mfma_f32_16x16x32_bf16 v[34:37], v[180:183], v[196:199], v[34:37]
	v_mfma_f32_16x16x32_bf16 v[26:29], v[156:159], v[200:203], v[26:29]
	v_mfma_f32_16x16x32_bf16 v[26:29], v[160:163], v[204:207], v[26:29]
	v_mfma_f32_16x16x32_bf16 v[18:21], v[164:167], v[200:203], v[18:21]
	v_mfma_f32_16x16x32_bf16 v[18:21], v[180:183], v[204:207], v[18:21]
	v_mfma_f32_16x16x32_bf16 v[10:13], v[156:159], v[208:211], v[10:13]
	v_mfma_f32_16x16x32_bf16 v[10:13], v[160:163], v[212:215], v[10:13]
	v_mfma_f32_16x16x32_bf16 v[2:5], v[164:167], v[208:211], v[2:5]
	v_mfma_f32_16x16x32_bf16 v[2:5], v[180:183], v[212:215], v[2:5]
	s_setprio 0
	s_barrier
	ds_read_b128 v[130:133], v175
	ds_read_b128 v[134:137], v175 offset:1024
	ds_read_b128 v[148:151], v175 offset:2048
	ds_read_b128 v[152:155], v175 offset:3072
	ds_read_b128 v[156:159], v176
	ds_read_b128 v[160:163], v176 offset:1024
	ds_read_b128 v[164:167], v176 offset:2048
	ds_read_b128 v[180:183], v176 offset:3072
	s_mov_b32 m0, s64
	s_add_i32 s59, s53, 0x100000
	ds_read_b128 v[184:187], v174 offset:32768
	ds_read_b128 v[188:191], v174 offset:33792
	ds_read_b128 v[192:195], v174 offset:34816
	ds_read_b128 v[196:199], v174 offset:35840
	ds_read_b128 v[200:203], v174 offset:36864
	ds_read_b128 v[204:207], v174 offset:37888
	ds_read_b128 v[208:211], v174 offset:38912
	ds_read_b128 v[212:215], v174 offset:39936
	buffer_load_dwordx4 v170, s[12:15], s59 offen lds
	s_add_i32 s59, s53, 0x180000
	s_mov_b32 m0, s65
	s_nop 0
	buffer_load_dwordx4 v170, s[12:15], s59 offen lds
	s_waitcnt vmcnt(8)
	s_waitcnt lgkmcnt(0)
	s_setprio 1
	v_mfma_f32_16x16x32_bf16 v[126:129], v[130:133], v[184:187], v[126:129]
	v_mfma_f32_16x16x32_bf16 v[126:129], v[134:137], v[188:191], v[126:129]
	v_mfma_f32_16x16x32_bf16 v[118:121], v[148:151], v[184:187], v[118:121]
	v_mfma_f32_16x16x32_bf16 v[118:121], v[152:155], v[188:191], v[118:121]
	s_barrier
	v_mfma_f32_16x16x32_bf16 v[110:113], v[130:133], v[192:195], v[110:113]
	v_mfma_f32_16x16x32_bf16 v[110:113], v[134:137], v[196:199], v[110:113]
	v_mfma_f32_16x16x32_bf16 v[102:105], v[148:151], v[192:195], v[102:105]
	v_mfma_f32_16x16x32_bf16 v[102:105], v[152:155], v[196:199], v[102:105]
	v_mfma_f32_16x16x32_bf16 v[94:97], v[130:133], v[200:203], v[94:97]
	v_mfma_f32_16x16x32_bf16 v[94:97], v[134:137], v[204:207], v[94:97]
	v_mfma_f32_16x16x32_bf16 v[90:93], v[148:151], v[200:203], v[90:93]
	v_mfma_f32_16x16x32_bf16 v[90:93], v[152:155], v[204:207], v[90:93]
	v_mfma_f32_16x16x32_bf16 v[78:81], v[130:133], v[208:211], v[78:81]
	v_mfma_f32_16x16x32_bf16 v[78:81], v[134:137], v[212:215], v[78:81]
	v_mfma_f32_16x16x32_bf16 v[70:73], v[148:151], v[208:211], v[70:73]
	v_mfma_f32_16x16x32_bf16 v[70:73], v[152:155], v[212:215], v[70:73]
	v_mfma_f32_16x16x32_bf16 v[122:125], v[156:159], v[184:187], v[122:125]
	v_mfma_f32_16x16x32_bf16 v[122:125], v[160:163], v[188:191], v[122:125]
	v_mfma_f32_16x16x32_bf16 v[114:117], v[164:167], v[184:187], v[114:117]
	v_mfma_f32_16x16x32_bf16 v[114:117], v[180:183], v[188:191], v[114:117]
	v_mfma_f32_16x16x32_bf16 v[106:109], v[156:159], v[192:195], v[106:109]
	v_mfma_f32_16x16x32_bf16 v[106:109], v[160:163], v[196:199], v[106:109]
	v_mfma_f32_16x16x32_bf16 v[98:101], v[164:167], v[192:195], v[98:101]
	v_mfma_f32_16x16x32_bf16 v[98:101], v[180:183], v[196:199], v[98:101]
	v_mfma_f32_16x16x32_bf16 v[86:89], v[156:159], v[200:203], v[86:89]
	v_mfma_f32_16x16x32_bf16 v[86:89], v[160:163], v[204:207], v[86:89]
	v_mfma_f32_16x16x32_bf16 v[82:85], v[164:167], v[200:203], v[82:85]
	v_mfma_f32_16x16x32_bf16 v[82:85], v[180:183], v[204:207], v[82:85]
	v_mfma_f32_16x16x32_bf16 v[74:77], v[156:159], v[208:211], v[74:77]
	v_mfma_f32_16x16x32_bf16 v[74:77], v[160:163], v[212:215], v[74:77]
	v_mfma_f32_16x16x32_bf16 v[66:69], v[164:167], v[208:211], v[66:69]
	v_mfma_f32_16x16x32_bf16 v[66:69], v[180:183], v[212:215], v[66:69]
	s_setprio 0
	s_barrier
	s_mov_b32 m0, s70
	s_or_b32 s59, s58, 0x80
	ds_read_b128 v[184:187], v174 offset:49152
	ds_read_b128 v[188:191], v174 offset:50176
	ds_read_b128 v[192:195], v174 offset:51200
	ds_read_b128 v[196:199], v174 offset:52224
	ds_read_b128 v[200:203], v174 offset:53248
	ds_read_b128 v[204:207], v174 offset:54272
	ds_read_b128 v[208:211], v174 offset:55296
	ds_read_b128 v[212:215], v174 offset:56320
	buffer_load_dwordx4 v171, s[16:19], s59 offen lds
	s_add_i32 s59, s58, 0x80080
	s_mov_b32 m0, s71
	s_add_i32 s53, s53, 0x80080
	buffer_load_dwordx4 v171, s[16:19], s59 offen lds
	s_add_i32 s59, s58, 0x100080
	s_mov_b32 m0, s74
	s_add_i32 s58, s58, 0x180080
	buffer_load_dwordx4 v171, s[16:19], s59 offen lds
	s_mov_b32 m0, s75
	s_nop 0
	buffer_load_dwordx4 v171, s[16:19], s58 offen lds
	s_mov_b32 m0, s72
	s_nop 0
	buffer_load_dwordx4 v170, s[12:15], s57 offen lds
	s_mov_b32 m0, s73
	s_nop 0
	buffer_load_dwordx4 v170, s[12:15], s53 offen lds
	s_waitcnt vmcnt(8)
	s_waitcnt lgkmcnt(0)
	s_setprio 1
	v_mfma_f32_16x16x32_bf16 v[62:65], v[130:133], v[184:187], v[62:65]
	v_mfma_f32_16x16x32_bf16 v[62:65], v[134:137], v[188:191], v[62:65]
	v_mfma_f32_16x16x32_bf16 v[54:57], v[148:151], v[184:187], v[54:57]
	v_mfma_f32_16x16x32_bf16 v[54:57], v[152:155], v[188:191], v[54:57]
	s_barrier
	v_mfma_f32_16x16x32_bf16 v[46:49], v[130:133], v[192:195], v[46:49]
	v_mfma_f32_16x16x32_bf16 v[46:49], v[134:137], v[196:199], v[46:49]
	v_mfma_f32_16x16x32_bf16 v[38:41], v[148:151], v[192:195], v[38:41]
	v_mfma_f32_16x16x32_bf16 v[38:41], v[152:155], v[196:199], v[38:41]
	v_mfma_f32_16x16x32_bf16 v[30:33], v[130:133], v[200:203], v[30:33]
	v_mfma_f32_16x16x32_bf16 v[30:33], v[134:137], v[204:207], v[30:33]
	v_mfma_f32_16x16x32_bf16 v[22:25], v[148:151], v[200:203], v[22:25]
	v_mfma_f32_16x16x32_bf16 v[22:25], v[152:155], v[204:207], v[22:25]
	v_mfma_f32_16x16x32_bf16 v[14:17], v[130:133], v[208:211], v[14:17]
	v_mfma_f32_16x16x32_bf16 v[14:17], v[134:137], v[212:215], v[14:17]
	v_mfma_f32_16x16x32_bf16 v[6:9], v[148:151], v[208:211], v[6:9]
	v_mfma_f32_16x16x32_bf16 v[6:9], v[152:155], v[212:215], v[6:9]
	v_mfma_f32_16x16x32_bf16 v[58:61], v[156:159], v[184:187], v[58:61]
	v_mfma_f32_16x16x32_bf16 v[58:61], v[160:163], v[188:191], v[58:61]
	v_mfma_f32_16x16x32_bf16 v[50:53], v[164:167], v[184:187], v[50:53]
	v_mfma_f32_16x16x32_bf16 v[50:53], v[180:183], v[188:191], v[50:53]
	v_mfma_f32_16x16x32_bf16 v[42:45], v[156:159], v[192:195], v[42:45]
	v_mfma_f32_16x16x32_bf16 v[42:45], v[160:163], v[196:199], v[42:45]
	v_mfma_f32_16x16x32_bf16 v[34:37], v[164:167], v[192:195], v[34:37]
	v_mfma_f32_16x16x32_bf16 v[34:37], v[180:183], v[196:199], v[34:37]
	v_mfma_f32_16x16x32_bf16 v[26:29], v[156:159], v[200:203], v[26:29]
	v_mfma_f32_16x16x32_bf16 v[26:29], v[160:163], v[204:207], v[26:29]
	v_mfma_f32_16x16x32_bf16 v[18:21], v[164:167], v[200:203], v[18:21]
	v_mfma_f32_16x16x32_bf16 v[18:21], v[180:183], v[204:207], v[18:21]
	v_mfma_f32_16x16x32_bf16 v[10:13], v[156:159], v[208:211], v[10:13]
	v_mfma_f32_16x16x32_bf16 v[10:13], v[160:163], v[212:215], v[10:13]
	v_mfma_f32_16x16x32_bf16 v[2:5], v[164:167], v[208:211], v[2:5]
	v_mfma_f32_16x16x32_bf16 v[2:5], v[180:183], v[212:215], v[2:5]
	s_setprio 0
	s_barrier
	s_add_i32 s52, s52, 2
	s_addk_i32 s8, 0x100
	s_addk_i32 s9, 0x100
	s_cmp_ge_i32 s52, s21
	s_cbranch_scc0 .LBB0_892
	s_and_b64 vcc, exec, s[48:49]
	s_cbranch_vccz .LBB0_895

.LBB0_1020:
	v_add_u32_e32 v142, 0x10000, v162
	v_add_u32_e32 v150, 0x14000, v162
	ds_read_b128 v[130:133], v142
	ds_read_b128 v[134:137], v142 offset:1024
	ds_read_b128 v[138:141], v142 offset:2048
	ds_read_b128 v[142:145], v142 offset:3072
	ds_read_b128 v[154:157], v150
	ds_read_b128 v[164:167], v150 offset:1024
	ds_read_b128 v[168:171], v150 offset:2048
	ds_read_b128 v[172:175], v150 offset:3072
	s_add_i32 s90, s6, 0x100
	s_add_i32 s7, s88, s6
	s_cmp_eq_u32 s81, s89
	s_cselect_b32 s91, 0, s90
	s_cselect_b32 s93, s87, s7
	s_add_i32 s91, s91, s70
	s_or_b32 s92, s91, 0x80
	s_add_i32 s6, s3, s6
	s_mov_b32 m0, s82
	s_add_i32 s7, s6, 0x20080
	ds_read_b128 v[176:179], v163
	ds_read_b128 v[180:183], v163 offset:1024
	ds_read_b128 v[184:187], v163 offset:2048
	ds_read_b128 v[188:191], v163 offset:3072
	ds_read_b128 v[192:195], v163 offset:4096
	ds_read_b128 v[196:199], v163 offset:5120
	ds_read_b128 v[200:203], v163 offset:6144
	ds_read_b128 v[204:207], v163 offset:7168
	buffer_load_dwordx4 v161, s[12:15], s7 offen lds
	s_add_i32 s6, s6, 0x30080
	s_mov_b32 m0, s83
	s_nop 0
	buffer_load_dwordx4 v161, s[12:15], s6 offen lds
	s_waitcnt vmcnt(8)
	s_waitcnt lgkmcnt(0)
	s_setprio 1
	v_mfma_f32_16x16x32_bf16 v[126:129], v[130:133], v[176:179], v[126:129]
	v_mfma_f32_16x16x32_bf16 v[126:129], v[134:137], v[180:183], v[126:129]
	v_mfma_f32_16x16x32_bf16 v[122:125], v[138:141], v[176:179], v[122:125]
	v_mfma_f32_16x16x32_bf16 v[122:125], v[142:145], v[180:183], v[122:125]
	s_barrier
	v_mfma_f32_16x16x32_bf16 v[110:113], v[130:133], v[184:187], v[110:113]
	v_mfma_f32_16x16x32_bf16 v[110:113], v[134:137], v[188:191], v[110:113]
	v_mfma_f32_16x16x32_bf16 v[106:109], v[138:141], v[184:187], v[106:109]
	v_mfma_f32_16x16x32_bf16 v[106:109], v[142:145], v[188:191], v[106:109]
	v_mfma_f32_16x16x32_bf16 v[94:97], v[130:133], v[192:195], v[94:97]
	v_mfma_f32_16x16x32_bf16 v[94:97], v[134:137], v[196:199], v[94:97]
	v_mfma_f32_16x16x32_bf16 v[90:93], v[138:141], v[192:195], v[90:93]
	v_mfma_f32_16x16x32_bf16 v[90:93], v[142:145], v[196:199], v[90:93]
	v_mfma_f32_16x16x32_bf16 v[78:81], v[130:133], v[200:203], v[78:81]
	v_mfma_f32_16x16x32_bf16 v[78:81], v[134:137], v[204:207], v[78:81]
	v_mfma_f32_16x16x32_bf16 v[74:77], v[138:141], v[200:203], v[74:77]
	v_mfma_f32_16x16x32_bf16 v[74:77], v[142:145], v[204:207], v[74:77]
	v_mfma_f32_16x16x32_bf16 v[118:121], v[154:157], v[176:179], v[118:121]
	v_mfma_f32_16x16x32_bf16 v[118:121], v[164:167], v[180:183], v[118:121]
	v_mfma_f32_16x16x32_bf16 v[114:117], v[168:171], v[176:179], v[114:117]
	v_mfma_f32_16x16x32_bf16 v[114:117], v[172:175], v[180:183], v[114:117]
	v_mfma_f32_16x16x32_bf16 v[102:105], v[154:157], v[184:187], v[102:105]
	v_mfma_f32_16x16x32_bf16 v[102:105], v[164:167], v[188:191], v[102:105]
	v_mfma_f32_16x16x32_bf16 v[98:101], v[168:171], v[184:187], v[98:101]
	v_mfma_f32_16x16x32_bf16 v[98:101], v[172:175], v[188:191], v[98:101]
	v_mfma_f32_16x16x32_bf16 v[86:89], v[154:157], v[192:195], v[86:89]
	v_mfma_f32_16x16x32_bf16 v[86:89], v[164:167], v[196:199], v[86:89]
	v_mfma_f32_16x16x32_bf16 v[82:85], v[168:171], v[192:195], v[82:85]
	v_mfma_f32_16x16x32_bf16 v[82:85], v[172:175], v[196:199], v[82:85]
	v_mfma_f32_16x16x32_bf16 v[70:73], v[154:157], v[200:203], v[70:73]
	v_mfma_f32_16x16x32_bf16 v[70:73], v[164:167], v[204:207], v[70:73]
	v_mfma_f32_16x16x32_bf16 v[66:69], v[168:171], v[200:203], v[66:69]
	v_mfma_f32_16x16x32_bf16 v[66:69], v[172:175], v[204:207], v[66:69]
	s_setprio 0
	s_barrier
	s_mov_b32 m0, s66
	s_mov_b32 s6, s14
	s_mov_b32 s7, s15
	ds_read_b128 v[176:179], v163 offset:16384
	ds_read_b128 v[180:183], v163 offset:17408
	ds_read_b128 v[184:187], v163 offset:18432
	ds_read_b128 v[188:191], v163 offset:19456
	ds_read_b128 v[192:195], v163 offset:20480
	ds_read_b128 v[196:199], v163 offset:21504
	ds_read_b128 v[200:203], v163 offset:22528
	ds_read_b128 v[204:207], v163 offset:23552
	buffer_load_dwordx4 v160, s[4:7], s93 offen lds
	s_add_i32 s94, s93, 0x10000
	s_mov_b32 m0, s67
	s_nop 0
	buffer_load_dwordx4 v160, s[4:7], s94 offen lds
	s_add_i32 s94, s93, 0x20000
	s_mov_b32 m0, s68
	s_nop 0
	buffer_load_dwordx4 v160, s[4:7], s94 offen lds
	s_add_i32 s94, s93, 0x30000
	s_mov_b32 m0, s69
	s_nop 0
	buffer_load_dwordx4 v160, s[4:7], s94 offen lds
	s_mov_b32 m0, s65
	s_add_i32 s94, s91, 0x10000
	buffer_load_dwordx4 v161, s[12:15], s91 offen lds
	s_mov_b32 m0, s71
	s_nop 0
	buffer_load_dwordx4 v161, s[12:15], s94 offen lds
	s_waitcnt vmcnt(8)
	s_waitcnt lgkmcnt(0)
	s_setprio 1
	v_mfma_f32_16x16x32_bf16 v[62:65], v[130:133], v[176:179], v[62:65]
	v_mfma_f32_16x16x32_bf16 v[62:65], v[134:137], v[180:183], v[62:65]
	v_mfma_f32_16x16x32_bf16 v[58:61], v[138:141], v[176:179], v[58:61]
	v_mfma_f32_16x16x32_bf16 v[58:61], v[142:145], v[180:183], v[58:61]
	s_barrier
	v_mfma_f32_16x16x32_bf16 v[46:49], v[130:133], v[184:187], v[46:49]
	v_mfma_f32_16x16x32_bf16 v[46:49], v[134:137], v[188:191], v[46:49]
	v_mfma_f32_16x16x32_bf16 v[42:45], v[138:141], v[184:187], v[42:45]
	v_mfma_f32_16x16x32_bf16 v[42:45], v[142:145], v[188:191], v[42:45]
	v_mfma_f32_16x16x32_bf16 v[30:33], v[130:133], v[192:195], v[30:33]
	v_mfma_f32_16x16x32_bf16 v[30:33], v[134:137], v[196:199], v[30:33]
	v_mfma_f32_16x16x32_bf16 v[26:29], v[138:141], v[192:195], v[26:29]
	v_mfma_f32_16x16x32_bf16 v[26:29], v[142:145], v[196:199], v[26:29]
	v_mfma_f32_16x16x32_bf16 v[14:17], v[130:133], v[200:203], v[14:17]
	v_mfma_f32_16x16x32_bf16 v[14:17], v[134:137], v[204:207], v[14:17]
	v_mfma_f32_16x16x32_bf16 v[10:13], v[138:141], v[200:203], v[10:13]
	v_mfma_f32_16x16x32_bf16 v[10:13], v[142:145], v[204:207], v[10:13]
	v_mfma_f32_16x16x32_bf16 v[54:57], v[154:157], v[176:179], v[54:57]
	v_mfma_f32_16x16x32_bf16 v[54:57], v[164:167], v[180:183], v[54:57]
	v_mfma_f32_16x16x32_bf16 v[50:53], v[168:171], v[176:179], v[50:53]
	v_mfma_f32_16x16x32_bf16 v[50:53], v[172:175], v[180:183], v[50:53]
	v_mfma_f32_16x16x32_bf16 v[38:41], v[154:157], v[184:187], v[38:41]
	v_mfma_f32_16x16x32_bf16 v[38:41], v[164:167], v[188:191], v[38:41]
	v_mfma_f32_16x16x32_bf16 v[34:37], v[168:171], v[184:187], v[34:37]
	v_mfma_f32_16x16x32_bf16 v[34:37], v[172:175], v[188:191], v[34:37]
	v_mfma_f32_16x16x32_bf16 v[22:25], v[154:157], v[192:195], v[22:25]
	v_mfma_f32_16x16x32_bf16 v[22:25], v[164:167], v[196:199], v[22:25]
	v_mfma_f32_16x16x32_bf16 v[18:21], v[168:171], v[192:195], v[18:21]
	v_mfma_f32_16x16x32_bf16 v[18:21], v[172:175], v[196:199], v[18:21]
	v_mfma_f32_16x16x32_bf16 v[6:9], v[154:157], v[200:203], v[6:9]
	v_mfma_f32_16x16x32_bf16 v[6:9], v[164:167], v[204:207], v[6:9]
	v_mfma_f32_16x16x32_bf16 v[2:5], v[168:171], v[200:203], v[2:5]
	v_mfma_f32_16x16x32_bf16 v[2:5], v[172:175], v[204:207], v[2:5]
	s_setprio 0
	s_barrier
	v_add_u32_e32 v142, 0x18000, v162
	v_add_u32_e32 v150, 0x1c000, v162
	ds_read_b128 v[130:133], v142
	ds_read_b128 v[134:137], v142 offset:1024
	ds_read_b128 v[138:141], v142 offset:2048
	ds_read_b128 v[142:145], v142 offset:3072
	ds_read_b128 v[154:157], v150
	ds_read_b128 v[164:167], v150 offset:1024
	ds_read_b128 v[168:171], v150 offset:2048
	ds_read_b128 v[172:175], v150 offset:3072
	s_mov_b32 m0, s72
	s_add_i32 s94, s91, 0x20000
	ds_read_b128 v[176:179], v163 offset:32768
	ds_read_b128 v[180:183], v163 offset:33792
	ds_read_b128 v[184:187], v163 offset:34816
	ds_read_b128 v[188:191], v163 offset:35840
	ds_read_b128 v[192:195], v163 offset:36864
	ds_read_b128 v[196:199], v163 offset:37888
	ds_read_b128 v[200:203], v163 offset:38912
	ds_read_b128 v[204:207], v163 offset:39936
	buffer_load_dwordx4 v161, s[12:15], s94 offen lds
	s_add_i32 s94, s91, 0x30000
	s_mov_b32 m0, s73
	s_nop 0
	buffer_load_dwordx4 v161, s[12:15], s94 offen lds
	s_waitcnt vmcnt(8)
	s_waitcnt lgkmcnt(0)
	s_setprio 1
	v_mfma_f32_16x16x32_bf16 v[126:129], v[130:133], v[176:179], v[126:129]
	v_mfma_f32_16x16x32_bf16 v[126:129], v[134:137], v[180:183], v[126:129]
	v_mfma_f32_16x16x32_bf16 v[122:125], v[138:141], v[176:179], v[122:125]
	v_mfma_f32_16x16x32_bf16 v[122:125], v[142:145], v[180:183], v[122:125]
	s_barrier
	v_mfma_f32_16x16x32_bf16 v[110:113], v[130:133], v[184:187], v[110:113]
	v_mfma_f32_16x16x32_bf16 v[110:113], v[134:137], v[188:191], v[110:113]
	v_mfma_f32_16x16x32_bf16 v[106:109], v[138:141], v[184:187], v[106:109]
	v_mfma_f32_16x16x32_bf16 v[106:109], v[142:145], v[188:191], v[106:109]
	v_mfma_f32_16x16x32_bf16 v[94:97], v[130:133], v[192:195], v[94:97]
	v_mfma_f32_16x16x32_bf16 v[94:97], v[134:137], v[196:199], v[94:97]
	v_mfma_f32_16x16x32_bf16 v[90:93], v[138:141], v[192:195], v[90:93]
	v_mfma_f32_16x16x32_bf16 v[90:93], v[142:145], v[196:199], v[90:93]
	v_mfma_f32_16x16x32_bf16 v[78:81], v[130:133], v[200:203], v[78:81]
	v_mfma_f32_16x16x32_bf16 v[78:81], v[134:137], v[204:207], v[78:81]
	v_mfma_f32_16x16x32_bf16 v[74:77], v[138:141], v[200:203], v[74:77]
	v_mfma_f32_16x16x32_bf16 v[74:77], v[142:145], v[204:207], v[74:77]
	v_mfma_f32_16x16x32_bf16 v[118:121], v[154:157], v[176:179], v[118:121]
	v_mfma_f32_16x16x32_bf16 v[118:121], v[164:167], v[180:183], v[118:121]
	v_mfma_f32_16x16x32_bf16 v[114:117], v[168:171], v[176:179], v[114:117]
	v_mfma_f32_16x16x32_bf16 v[114:117], v[172:175], v[180:183], v[114:117]
	v_mfma_f32_16x16x32_bf16 v[102:105], v[154:157], v[184:187], v[102:105]
	v_mfma_f32_16x16x32_bf16 v[102:105], v[164:167], v[188:191], v[102:105]
	v_mfma_f32_16x16x32_bf16 v[98:101], v[168:171], v[184:187], v[98:101]
	v_mfma_f32_16x16x32_bf16 v[98:101], v[172:175], v[188:191], v[98:101]
	v_mfma_f32_16x16x32_bf16 v[86:89], v[154:157], v[192:195], v[86:89]
	v_mfma_f32_16x16x32_bf16 v[86:89], v[164:167], v[196:199], v[86:89]
	v_mfma_f32_16x16x32_bf16 v[82:85], v[168:171], v[192:195], v[82:85]
	v_mfma_f32_16x16x32_bf16 v[82:85], v[172:175], v[196:199], v[82:85]
	v_mfma_f32_16x16x32_bf16 v[70:73], v[154:157], v[200:203], v[70:73]
	v_mfma_f32_16x16x32_bf16 v[70:73], v[164:167], v[204:207], v[70:73]
	v_mfma_f32_16x16x32_bf16 v[66:69], v[168:171], v[200:203], v[66:69]
	v_mfma_f32_16x16x32_bf16 v[66:69], v[172:175], v[204:207], v[66:69]
	s_setprio 0
	s_barrier
	s_mov_b32 m0, s74
	s_or_b32 s94, s93, 0x80
	ds_read_b128 v[176:179], v163 offset:49152
	ds_read_b128 v[180:183], v163 offset:50176
	ds_read_b128 v[184:187], v163 offset:51200
	ds_read_b128 v[188:191], v163 offset:52224
	ds_read_b128 v[192:195], v163 offset:53248
	ds_read_b128 v[196:199], v163 offset:54272
	ds_read_b128 v[200:203], v163 offset:55296
	ds_read_b128 v[204:207], v163 offset:56320
	buffer_load_dwordx4 v160, s[4:7], s94 offen lds
	s_add_i32 s94, s93, 0x10080
	s_mov_b32 m0, s75
	s_add_i32 s91, s91, 0x10080
	buffer_load_dwordx4 v160, s[4:7], s94 offen lds
	s_add_i32 s94, s93, 0x20080
	s_mov_b32 m0, s78
	s_add_i32 s93, s93, 0x30080
	buffer_load_dwordx4 v160, s[4:7], s94 offen lds
	s_mov_b32 m0, s79
	s_nop 0
	buffer_load_dwordx4 v160, s[4:7], s93 offen lds
	s_mov_b32 m0, s76
	s_nop 0
	buffer_load_dwordx4 v161, s[12:15], s92 offen lds
	s_mov_b32 m0, s77
	s_nop 0
	buffer_load_dwordx4 v161, s[12:15], s91 offen lds
	s_waitcnt vmcnt(8)
	s_waitcnt lgkmcnt(0)
	s_setprio 1
	v_mfma_f32_16x16x32_bf16 v[62:65], v[130:133], v[176:179], v[62:65]
	v_mfma_f32_16x16x32_bf16 v[62:65], v[134:137], v[180:183], v[62:65]
	v_mfma_f32_16x16x32_bf16 v[58:61], v[138:141], v[176:179], v[58:61]
	v_mfma_f32_16x16x32_bf16 v[58:61], v[142:145], v[180:183], v[58:61]
	s_barrier
	v_mfma_f32_16x16x32_bf16 v[46:49], v[130:133], v[184:187], v[46:49]
	v_mfma_f32_16x16x32_bf16 v[46:49], v[134:137], v[188:191], v[46:49]
	v_mfma_f32_16x16x32_bf16 v[42:45], v[138:141], v[184:187], v[42:45]
	v_mfma_f32_16x16x32_bf16 v[42:45], v[142:145], v[188:191], v[42:45]
	v_mfma_f32_16x16x32_bf16 v[30:33], v[130:133], v[192:195], v[30:33]
	v_mfma_f32_16x16x32_bf16 v[30:33], v[134:137], v[196:199], v[30:33]
	v_mfma_f32_16x16x32_bf16 v[26:29], v[138:141], v[192:195], v[26:29]
	v_mfma_f32_16x16x32_bf16 v[26:29], v[142:145], v[196:199], v[26:29]
	v_mfma_f32_16x16x32_bf16 v[14:17], v[130:133], v[200:203], v[14:17]
	v_mfma_f32_16x16x32_bf16 v[14:17], v[134:137], v[204:207], v[14:17]
	v_mfma_f32_16x16x32_bf16 v[10:13], v[138:141], v[200:203], v[10:13]
	v_mfma_f32_16x16x32_bf16 v[10:13], v[142:145], v[204:207], v[10:13]
	v_mfma_f32_16x16x32_bf16 v[54:57], v[154:157], v[176:179], v[54:57]
	v_mfma_f32_16x16x32_bf16 v[54:57], v[164:167], v[180:183], v[54:57]
	v_mfma_f32_16x16x32_bf16 v[50:53], v[168:171], v[176:179], v[50:53]
	v_mfma_f32_16x16x32_bf16 v[50:53], v[172:175], v[180:183], v[50:53]
	v_mfma_f32_16x16x32_bf16 v[38:41], v[154:157], v[184:187], v[38:41]
	v_mfma_f32_16x16x32_bf16 v[38:41], v[164:167], v[188:191], v[38:41]
	v_mfma_f32_16x16x32_bf16 v[34:37], v[168:171], v[184:187], v[34:37]
	v_mfma_f32_16x16x32_bf16 v[34:37], v[172:175], v[188:191], v[34:37]
	v_mfma_f32_16x16x32_bf16 v[22:25], v[154:157], v[192:195], v[22:25]
	v_mfma_f32_16x16x32_bf16 v[22:25], v[164:167], v[196:199], v[22:25]
	v_mfma_f32_16x16x32_bf16 v[18:21], v[168:171], v[192:195], v[18:21]
	v_mfma_f32_16x16x32_bf16 v[18:21], v[172:175], v[196:199], v[18:21]
	v_mfma_f32_16x16x32_bf16 v[6:9], v[154:157], v[200:203], v[6:9]
	v_mfma_f32_16x16x32_bf16 v[6:9], v[164:167], v[204:207], v[6:9]
	v_mfma_f32_16x16x32_bf16 v[2:5], v[168:171], v[200:203], v[2:5]
	v_mfma_f32_16x16x32_bf16 v[2:5], v[172:175], v[204:207], v[2:5]
	s_setprio 0
	s_barrier
	s_add_i32 s89, s89, 2
	s_cmp_ge_i32 s89, s63
	s_mov_b32 s6, s90
	s_cbranch_scc0 .LBB0_1020
	s_and_b64 vcc, exec, s[54:55]
	s_cbranch_vccz .LBB0_1023

.LBB0_1035:
	ds_read_b128 v[140:143], v134
	ds_read_b128 v[148:151], v134 offset:1024
	ds_read_b128 v[152:155], v134 offset:2048
	ds_read_b128 v[156:159], v134 offset:3072
	ds_read_b128 v[160:163], v135
	ds_read_b128 v[164:167], v135 offset:1024
	ds_read_b128 v[168:171], v135 offset:2048
	ds_read_b128 v[172:175], v135 offset:3072
	s_add_i32 s73, s70, 0xfffb8080
	s_cmp_eq_u32 s53, s72
	s_cselect_b32 s73, s68, s73
	s_cselect_b32 s75, s69, s71
	s_add_i32 s74, s73, 0x80
	s_add_i32 s76, s70, 0xfffe8000
	s_mov_b32 m0, s54
	ds_read_b128 v[176:179], v136
	ds_read_b128 v[180:183], v136 offset:1024
	ds_read_b128 v[184:187], v136 offset:2048
	ds_read_b128 v[188:191], v136 offset:3072
	ds_read_b128 v[192:195], v136 offset:4096
	ds_read_b128 v[196:199], v136 offset:5120
	ds_read_b128 v[200:203], v136 offset:6144
	ds_read_b128 v[204:207], v136 offset:7168
	buffer_load_dwordx4 v132, s[12:15], s76 offen lds
	s_mov_b32 m0, s55
	s_nop 0
	buffer_load_dwordx4 v132, s[12:15], s70 offen lds
	s_waitcnt vmcnt(8)
	s_waitcnt lgkmcnt(0)
	s_setprio 1
	v_mfma_f32_16x16x32_bf16 v[126:129], v[140:143], v[176:179], v[126:129]
	v_mfma_f32_16x16x32_bf16 v[126:129], v[148:151], v[180:183], v[126:129]
	v_mfma_f32_16x16x32_bf16 v[122:125], v[152:155], v[176:179], v[122:125]
	v_mfma_f32_16x16x32_bf16 v[122:125], v[156:159], v[180:183], v[122:125]
	s_barrier
	v_mfma_f32_16x16x32_bf16 v[110:113], v[140:143], v[184:187], v[110:113]
	v_mfma_f32_16x16x32_bf16 v[110:113], v[148:151], v[188:191], v[110:113]
	v_mfma_f32_16x16x32_bf16 v[106:109], v[152:155], v[184:187], v[106:109]
	v_mfma_f32_16x16x32_bf16 v[106:109], v[156:159], v[188:191], v[106:109]
	v_mfma_f32_16x16x32_bf16 v[94:97], v[140:143], v[192:195], v[94:97]
	v_mfma_f32_16x16x32_bf16 v[94:97], v[148:151], v[196:199], v[94:97]
	v_mfma_f32_16x16x32_bf16 v[90:93], v[152:155], v[192:195], v[90:93]
	v_mfma_f32_16x16x32_bf16 v[90:93], v[156:159], v[196:199], v[90:93]
	v_mfma_f32_16x16x32_bf16 v[78:81], v[140:143], v[200:203], v[78:81]
	v_mfma_f32_16x16x32_bf16 v[78:81], v[148:151], v[204:207], v[78:81]
	v_mfma_f32_16x16x32_bf16 v[74:77], v[152:155], v[200:203], v[74:77]
	v_mfma_f32_16x16x32_bf16 v[74:77], v[156:159], v[204:207], v[74:77]
	v_mfma_f32_16x16x32_bf16 v[118:121], v[160:163], v[176:179], v[118:121]
	v_mfma_f32_16x16x32_bf16 v[118:121], v[164:167], v[180:183], v[118:121]
	v_mfma_f32_16x16x32_bf16 v[114:117], v[168:171], v[176:179], v[114:117]
	v_mfma_f32_16x16x32_bf16 v[114:117], v[172:175], v[180:183], v[114:117]
	v_mfma_f32_16x16x32_bf16 v[102:105], v[160:163], v[184:187], v[102:105]
	v_mfma_f32_16x16x32_bf16 v[102:105], v[164:167], v[188:191], v[102:105]
	v_mfma_f32_16x16x32_bf16 v[98:101], v[168:171], v[184:187], v[98:101]
	v_mfma_f32_16x16x32_bf16 v[98:101], v[172:175], v[188:191], v[98:101]
	v_mfma_f32_16x16x32_bf16 v[86:89], v[160:163], v[192:195], v[86:89]
	v_mfma_f32_16x16x32_bf16 v[86:89], v[164:167], v[196:199], v[86:89]
	v_mfma_f32_16x16x32_bf16 v[82:85], v[168:171], v[192:195], v[82:85]
	v_mfma_f32_16x16x32_bf16 v[82:85], v[172:175], v[196:199], v[82:85]
	v_mfma_f32_16x16x32_bf16 v[70:73], v[160:163], v[200:203], v[70:73]
	v_mfma_f32_16x16x32_bf16 v[70:73], v[164:167], v[204:207], v[70:73]
	v_mfma_f32_16x16x32_bf16 v[66:69], v[168:171], v[200:203], v[66:69]
	v_mfma_f32_16x16x32_bf16 v[66:69], v[172:175], v[204:207], v[66:69]
	s_setprio 0
	s_barrier
	s_mov_b32 m0, s30
	ds_read_b128 v[176:179], v136 offset:16384
	ds_read_b128 v[180:183], v136 offset:17408
	ds_read_b128 v[184:187], v136 offset:18432
	ds_read_b128 v[188:191], v136 offset:19456
	ds_read_b128 v[192:195], v136 offset:20480
	ds_read_b128 v[196:199], v136 offset:21504
	ds_read_b128 v[200:203], v136 offset:22528
	ds_read_b128 v[204:207], v136 offset:23552
	buffer_load_dwordx4 v133, s[16:19], s75 offen lds
	s_add_i32 s76, s75, 0x200000
	s_mov_b32 m0, s31
	s_nop 0
	buffer_load_dwordx4 v133, s[16:19], s76 offen lds
	s_add_i32 s76, s75, 0x400000
	s_mov_b32 m0, s35
	s_nop 0
	buffer_load_dwordx4 v133, s[16:19], s76 offen lds
	s_add_i32 s76, s75, 0x600000
	s_mov_b32 m0, s42
	s_nop 0
	buffer_load_dwordx4 v133, s[16:19], s76 offen lds
	s_mov_b32 m0, s27
	s_add_i32 s76, s73, 0x18000
	buffer_load_dwordx4 v132, s[12:15], s73 offen lds
	s_mov_b32 m0, s43
	s_nop 0
	buffer_load_dwordx4 v132, s[12:15], s76 offen lds
	s_waitcnt vmcnt(8)
	s_waitcnt lgkmcnt(0)
	s_setprio 1
	v_mfma_f32_16x16x32_bf16 v[62:65], v[140:143], v[176:179], v[62:65]
	v_mfma_f32_16x16x32_bf16 v[62:65], v[148:151], v[180:183], v[62:65]
	v_mfma_f32_16x16x32_bf16 v[58:61], v[152:155], v[176:179], v[58:61]
	v_mfma_f32_16x16x32_bf16 v[58:61], v[156:159], v[180:183], v[58:61]
	s_barrier
	v_mfma_f32_16x16x32_bf16 v[46:49], v[140:143], v[184:187], v[46:49]
	v_mfma_f32_16x16x32_bf16 v[46:49], v[148:151], v[188:191], v[46:49]
	v_mfma_f32_16x16x32_bf16 v[42:45], v[152:155], v[184:187], v[42:45]
	v_mfma_f32_16x16x32_bf16 v[42:45], v[156:159], v[188:191], v[42:45]
	v_mfma_f32_16x16x32_bf16 v[30:33], v[140:143], v[192:195], v[30:33]
	v_mfma_f32_16x16x32_bf16 v[30:33], v[148:151], v[196:199], v[30:33]
	v_mfma_f32_16x16x32_bf16 v[26:29], v[152:155], v[192:195], v[26:29]
	v_mfma_f32_16x16x32_bf16 v[26:29], v[156:159], v[196:199], v[26:29]
	v_mfma_f32_16x16x32_bf16 v[14:17], v[140:143], v[200:203], v[14:17]
	v_mfma_f32_16x16x32_bf16 v[14:17], v[148:151], v[204:207], v[14:17]
	v_mfma_f32_16x16x32_bf16 v[10:13], v[152:155], v[200:203], v[10:13]
	v_mfma_f32_16x16x32_bf16 v[10:13], v[156:159], v[204:207], v[10:13]
	v_mfma_f32_16x16x32_bf16 v[54:57], v[160:163], v[176:179], v[54:57]
	v_mfma_f32_16x16x32_bf16 v[54:57], v[164:167], v[180:183], v[54:57]
	v_mfma_f32_16x16x32_bf16 v[50:53], v[168:171], v[176:179], v[50:53]
	v_mfma_f32_16x16x32_bf16 v[50:53], v[172:175], v[180:183], v[50:53]
	v_mfma_f32_16x16x32_bf16 v[38:41], v[160:163], v[184:187], v[38:41]
	v_mfma_f32_16x16x32_bf16 v[38:41], v[164:167], v[188:191], v[38:41]
	v_mfma_f32_16x16x32_bf16 v[34:37], v[168:171], v[184:187], v[34:37]
	v_mfma_f32_16x16x32_bf16 v[34:37], v[172:175], v[188:191], v[34:37]
	v_mfma_f32_16x16x32_bf16 v[22:25], v[160:163], v[192:195], v[22:25]
	v_mfma_f32_16x16x32_bf16 v[22:25], v[164:167], v[196:199], v[22:25]
	v_mfma_f32_16x16x32_bf16 v[18:21], v[168:171], v[192:195], v[18:21]
	v_mfma_f32_16x16x32_bf16 v[18:21], v[172:175], v[196:199], v[18:21]
	v_mfma_f32_16x16x32_bf16 v[6:9], v[160:163], v[200:203], v[6:9]
	v_mfma_f32_16x16x32_bf16 v[6:9], v[164:167], v[204:207], v[6:9]
	v_mfma_f32_16x16x32_bf16 v[2:5], v[168:171], v[200:203], v[2:5]
	v_mfma_f32_16x16x32_bf16 v[2:5], v[172:175], v[204:207], v[2:5]
	s_setprio 0
	s_barrier
	ds_read_b128 v[140:143], v137
	ds_read_b128 v[148:151], v137 offset:1024
	ds_read_b128 v[152:155], v137 offset:2048
	ds_read_b128 v[156:159], v137 offset:3072
	ds_read_b128 v[160:163], v138
	ds_read_b128 v[164:167], v138 offset:1024
	ds_read_b128 v[168:171], v138 offset:2048
	ds_read_b128 v[172:175], v138 offset:3072
	s_mov_b32 m0, s44
	s_add_i32 s76, s73, 0x30000
	ds_read_b128 v[176:179], v136 offset:32768
	ds_read_b128 v[180:183], v136 offset:33792
	ds_read_b128 v[184:187], v136 offset:34816
	ds_read_b128 v[188:191], v136 offset:35840
	ds_read_b128 v[192:195], v136 offset:36864
	ds_read_b128 v[196:199], v136 offset:37888
	ds_read_b128 v[200:203], v136 offset:38912
	ds_read_b128 v[204:207], v136 offset:39936
	buffer_load_dwordx4 v132, s[12:15], s76 offen lds
	s_add_i32 s76, s73, 0x48000
	s_mov_b32 m0, s45
	s_nop 0
	buffer_load_dwordx4 v132, s[12:15], s76 offen lds
	s_waitcnt vmcnt(8)
	s_waitcnt lgkmcnt(0)
	s_setprio 1
	v_mfma_f32_16x16x32_bf16 v[126:129], v[140:143], v[176:179], v[126:129]
	v_mfma_f32_16x16x32_bf16 v[126:129], v[148:151], v[180:183], v[126:129]
	v_mfma_f32_16x16x32_bf16 v[122:125], v[152:155], v[176:179], v[122:125]
	v_mfma_f32_16x16x32_bf16 v[122:125], v[156:159], v[180:183], v[122:125]
	s_barrier
	v_mfma_f32_16x16x32_bf16 v[110:113], v[140:143], v[184:187], v[110:113]
	v_mfma_f32_16x16x32_bf16 v[110:113], v[148:151], v[188:191], v[110:113]
	v_mfma_f32_16x16x32_bf16 v[106:109], v[152:155], v[184:187], v[106:109]
	v_mfma_f32_16x16x32_bf16 v[106:109], v[156:159], v[188:191], v[106:109]
	v_mfma_f32_16x16x32_bf16 v[94:97], v[140:143], v[192:195], v[94:97]
	v_mfma_f32_16x16x32_bf16 v[94:97], v[148:151], v[196:199], v[94:97]
	v_mfma_f32_16x16x32_bf16 v[90:93], v[152:155], v[192:195], v[90:93]
	v_mfma_f32_16x16x32_bf16 v[90:93], v[156:159], v[196:199], v[90:93]
	v_mfma_f32_16x16x32_bf16 v[78:81], v[140:143], v[200:203], v[78:81]
	v_mfma_f32_16x16x32_bf16 v[78:81], v[148:151], v[204:207], v[78:81]
	v_mfma_f32_16x16x32_bf16 v[74:77], v[152:155], v[200:203], v[74:77]
	v_mfma_f32_16x16x32_bf16 v[74:77], v[156:159], v[204:207], v[74:77]
	v_mfma_f32_16x16x32_bf16 v[118:121], v[160:163], v[176:179], v[118:121]
	v_mfma_f32_16x16x32_bf16 v[118:121], v[164:167], v[180:183], v[118:121]
	v_mfma_f32_16x16x32_bf16 v[114:117], v[168:171], v[176:179], v[114:117]
	v_mfma_f32_16x16x32_bf16 v[114:117], v[172:175], v[180:183], v[114:117]
	v_mfma_f32_16x16x32_bf16 v[102:105], v[160:163], v[184:187], v[102:105]
	v_mfma_f32_16x16x32_bf16 v[102:105], v[164:167], v[188:191], v[102:105]
	v_mfma_f32_16x16x32_bf16 v[98:101], v[168:171], v[184:187], v[98:101]
	v_mfma_f32_16x16x32_bf16 v[98:101], v[172:175], v[188:191], v[98:101]
	v_mfma_f32_16x16x32_bf16 v[86:89], v[160:163], v[192:195], v[86:89]
	v_mfma_f32_16x16x32_bf16 v[86:89], v[164:167], v[196:199], v[86:89]
	v_mfma_f32_16x16x32_bf16 v[82:85], v[168:171], v[192:195], v[82:85]
	v_mfma_f32_16x16x32_bf16 v[82:85], v[172:175], v[196:199], v[82:85]
	v_mfma_f32_16x16x32_bf16 v[70:73], v[160:163], v[200:203], v[70:73]
	v_mfma_f32_16x16x32_bf16 v[70:73], v[164:167], v[204:207], v[70:73]
	v_mfma_f32_16x16x32_bf16 v[66:69], v[168:171], v[200:203], v[66:69]
	v_mfma_f32_16x16x32_bf16 v[66:69], v[172:175], v[204:207], v[66:69]
	s_setprio 0
	s_barrier
	s_mov_b32 m0, s46
	s_add_i32 s76, s75, 0x80
	ds_read_b128 v[176:179], v136 offset:49152
	ds_read_b128 v[180:183], v136 offset:50176
	ds_read_b128 v[184:187], v136 offset:51200
	ds_read_b128 v[188:191], v136 offset:52224
	ds_read_b128 v[192:195], v136 offset:53248
	ds_read_b128 v[196:199], v136 offset:54272
	ds_read_b128 v[200:203], v136 offset:55296
	ds_read_b128 v[204:207], v136 offset:56320
	buffer_load_dwordx4 v133, s[16:19], s76 offen lds
	s_add_i32 s76, s75, 0x200080
	s_mov_b32 m0, s47
	s_add_i32 s73, s73, 0x18080
	buffer_load_dwordx4 v133, s[16:19], s76 offen lds
	s_add_i32 s76, s75, 0x400080
	s_mov_b32 m0, s50
	s_add_i32 s75, s75, 0x600080
	buffer_load_dwordx4 v133, s[16:19], s76 offen lds
	s_mov_b32 m0, s51
	s_nop 0
	buffer_load_dwordx4 v133, s[16:19], s75 offen lds
	s_mov_b32 m0, s48
	s_nop 0
	buffer_load_dwordx4 v132, s[12:15], s74 offen lds
	s_mov_b32 m0, s49
	s_nop 0
	buffer_load_dwordx4 v132, s[12:15], s73 offen lds
	s_waitcnt vmcnt(8)
	s_waitcnt lgkmcnt(0)
	s_setprio 1
	v_mfma_f32_16x16x32_bf16 v[62:65], v[140:143], v[176:179], v[62:65]
	v_mfma_f32_16x16x32_bf16 v[62:65], v[148:151], v[180:183], v[62:65]
	v_mfma_f32_16x16x32_bf16 v[58:61], v[152:155], v[176:179], v[58:61]
	v_mfma_f32_16x16x32_bf16 v[58:61], v[156:159], v[180:183], v[58:61]
	s_barrier
	v_mfma_f32_16x16x32_bf16 v[46:49], v[140:143], v[184:187], v[46:49]
	v_mfma_f32_16x16x32_bf16 v[46:49], v[148:151], v[188:191], v[46:49]
	v_mfma_f32_16x16x32_bf16 v[42:45], v[152:155], v[184:187], v[42:45]
	v_mfma_f32_16x16x32_bf16 v[42:45], v[156:159], v[188:191], v[42:45]
	v_mfma_f32_16x16x32_bf16 v[30:33], v[140:143], v[192:195], v[30:33]
	v_mfma_f32_16x16x32_bf16 v[30:33], v[148:151], v[196:199], v[30:33]
	v_mfma_f32_16x16x32_bf16 v[26:29], v[152:155], v[192:195], v[26:29]
	v_mfma_f32_16x16x32_bf16 v[26:29], v[156:159], v[196:199], v[26:29]
	v_mfma_f32_16x16x32_bf16 v[14:17], v[140:143], v[200:203], v[14:17]
	v_mfma_f32_16x16x32_bf16 v[14:17], v[148:151], v[204:207], v[14:17]
	v_mfma_f32_16x16x32_bf16 v[10:13], v[152:155], v[200:203], v[10:13]
	v_mfma_f32_16x16x32_bf16 v[10:13], v[156:159], v[204:207], v[10:13]
	v_mfma_f32_16x16x32_bf16 v[54:57], v[160:163], v[176:179], v[54:57]
	v_mfma_f32_16x16x32_bf16 v[54:57], v[164:167], v[180:183], v[54:57]
	v_mfma_f32_16x16x32_bf16 v[50:53], v[168:171], v[176:179], v[50:53]
	v_mfma_f32_16x16x32_bf16 v[50:53], v[172:175], v[180:183], v[50:53]
	v_mfma_f32_16x16x32_bf16 v[38:41], v[160:163], v[184:187], v[38:41]
	v_mfma_f32_16x16x32_bf16 v[38:41], v[164:167], v[188:191], v[38:41]
	v_mfma_f32_16x16x32_bf16 v[34:37], v[168:171], v[184:187], v[34:37]
	v_mfma_f32_16x16x32_bf16 v[34:37], v[172:175], v[188:191], v[34:37]
	v_mfma_f32_16x16x32_bf16 v[22:25], v[160:163], v[192:195], v[22:25]
	v_mfma_f32_16x16x32_bf16 v[22:25], v[164:167], v[196:199], v[22:25]
	v_mfma_f32_16x16x32_bf16 v[18:21], v[168:171], v[192:195], v[18:21]
	v_mfma_f32_16x16x32_bf16 v[18:21], v[172:175], v[196:199], v[18:21]
	v_mfma_f32_16x16x32_bf16 v[6:9], v[160:163], v[200:203], v[6:9]
	v_mfma_f32_16x16x32_bf16 v[6:9], v[164:167], v[204:207], v[6:9]
	v_mfma_f32_16x16x32_bf16 v[2:5], v[168:171], v[200:203], v[2:5]
	v_mfma_f32_16x16x32_bf16 v[2:5], v[172:175], v[204:207], v[2:5]
	s_setprio 0
	s_barrier
	s_add_i32 s72, s72, 2
	s_addk_i32 s70, 0x100
	s_addk_i32 s71, 0x100
	s_cmp_ge_i32 s72, s21
	s_cbranch_scc0 .LBB0_1035

.LBB0_1050:
	ds_read_b128 v[132:135], v142
	ds_read_b128 v[136:139], v142 offset:1024
	ds_read_b128 v[148:151], v142 offset:2048
	ds_read_b128 v[152:155], v142 offset:3072
	ds_read_b128 v[156:159], v143
	ds_read_b128 v[160:163], v143 offset:1024
	ds_read_b128 v[164:167], v143 offset:2048
	ds_read_b128 v[168:171], v143 offset:3072
	s_add_i32 s18, s61, 0xfff40080
	s_cmp_eq_u32 s54, s62
	s_cselect_b32 s64, s35, s18
	s_add_i32 s63, s64, 0x80
	s_add_i32 s18, s61, 0xfffc0000
	s_mov_b32 m0, s55
	ds_read_b128 v[172:175], v144
	ds_read_b128 v[176:179], v144 offset:1024
	ds_read_b128 v[180:183], v144 offset:2048
	ds_read_b128 v[184:187], v144 offset:3072
	ds_read_b128 v[188:191], v144 offset:4096
	ds_read_b128 v[192:195], v144 offset:5120
	ds_read_b128 v[196:199], v144 offset:6144
	ds_read_b128 v[200:203], v144 offset:7168
	buffer_load_dwordx4 v140, s[12:15], s18 offen lds
	s_mov_b32 m0, s56
	s_nop 0
	buffer_load_dwordx4 v140, s[12:15], s61 offen lds
	s_waitcnt vmcnt(8)
	s_waitcnt lgkmcnt(0)
	s_setprio 1
	v_mfma_f32_16x16x32_bf16 v[126:129], v[132:135], v[172:175], v[126:129]
	v_mfma_f32_16x16x32_bf16 v[126:129], v[136:139], v[176:179], v[126:129]
	v_mfma_f32_16x16x32_bf16 v[122:125], v[148:151], v[172:175], v[122:125]
	v_mfma_f32_16x16x32_bf16 v[122:125], v[152:155], v[176:179], v[122:125]
	s_barrier
	v_mfma_f32_16x16x32_bf16 v[110:113], v[132:135], v[180:183], v[110:113]
	v_mfma_f32_16x16x32_bf16 v[110:113], v[136:139], v[184:187], v[110:113]
	v_mfma_f32_16x16x32_bf16 v[106:109], v[148:151], v[180:183], v[106:109]
	v_mfma_f32_16x16x32_bf16 v[106:109], v[152:155], v[184:187], v[106:109]
	v_mfma_f32_16x16x32_bf16 v[94:97], v[132:135], v[188:191], v[94:97]
	v_mfma_f32_16x16x32_bf16 v[94:97], v[136:139], v[192:195], v[94:97]
	v_mfma_f32_16x16x32_bf16 v[90:93], v[148:151], v[188:191], v[90:93]
	v_mfma_f32_16x16x32_bf16 v[90:93], v[152:155], v[192:195], v[90:93]
	v_mfma_f32_16x16x32_bf16 v[78:81], v[132:135], v[196:199], v[78:81]
	v_mfma_f32_16x16x32_bf16 v[78:81], v[136:139], v[200:203], v[78:81]
	v_mfma_f32_16x16x32_bf16 v[74:77], v[148:151], v[196:199], v[74:77]
	v_mfma_f32_16x16x32_bf16 v[74:77], v[152:155], v[200:203], v[74:77]
	v_mfma_f32_16x16x32_bf16 v[118:121], v[156:159], v[172:175], v[118:121]
	v_mfma_f32_16x16x32_bf16 v[118:121], v[160:163], v[176:179], v[118:121]
	v_mfma_f32_16x16x32_bf16 v[114:117], v[164:167], v[172:175], v[114:117]
	v_mfma_f32_16x16x32_bf16 v[114:117], v[168:171], v[176:179], v[114:117]
	v_mfma_f32_16x16x32_bf16 v[102:105], v[156:159], v[180:183], v[102:105]
	v_mfma_f32_16x16x32_bf16 v[102:105], v[160:163], v[184:187], v[102:105]
	v_mfma_f32_16x16x32_bf16 v[98:101], v[164:167], v[180:183], v[98:101]
	v_mfma_f32_16x16x32_bf16 v[98:101], v[168:171], v[184:187], v[98:101]
	v_mfma_f32_16x16x32_bf16 v[86:89], v[156:159], v[188:191], v[86:89]
	v_mfma_f32_16x16x32_bf16 v[86:89], v[160:163], v[192:195], v[86:89]
	v_mfma_f32_16x16x32_bf16 v[82:85], v[164:167], v[188:191], v[82:85]
	v_mfma_f32_16x16x32_bf16 v[82:85], v[168:171], v[192:195], v[82:85]
	v_mfma_f32_16x16x32_bf16 v[70:73], v[156:159], v[196:199], v[70:73]
	v_mfma_f32_16x16x32_bf16 v[70:73], v[160:163], v[200:203], v[70:73]
	v_mfma_f32_16x16x32_bf16 v[66:69], v[164:167], v[196:199], v[66:69]
	v_mfma_f32_16x16x32_bf16 v[66:69], v[168:171], v[200:203], v[66:69]
	s_setprio 0
	s_barrier
	s_mov_b32 m0, s25
	s_mov_b32 s18, s14
	s_mov_b32 s19, s15
	ds_read_b128 v[172:175], v144 offset:16384
	ds_read_b128 v[176:179], v144 offset:17408
	ds_read_b128 v[180:183], v144 offset:18432
	ds_read_b128 v[184:187], v144 offset:19456
	ds_read_b128 v[188:191], v144 offset:20480
	ds_read_b128 v[192:195], v144 offset:21504
	ds_read_b128 v[196:199], v144 offset:22528
	ds_read_b128 v[200:203], v144 offset:23552
	buffer_load_dwordx4 v141, s[16:19], s64 offen lds
	s_add_i32 s65, s64, 0x40000
	s_mov_b32 m0, s27
	s_add_i32 s66, s64, 0x80000
	buffer_load_dwordx4 v141, s[16:19], s65 offen lds
	s_mov_b32 m0, s30
	s_add_i32 s67, s64, 0xc0000
	buffer_load_dwordx4 v141, s[16:19], s66 offen lds
	s_mov_b32 m0, s31
	s_nop 0
	buffer_load_dwordx4 v141, s[16:19], s67 offen lds
	s_mov_b32 m0, s21
	s_nop 0
	buffer_load_dwordx4 v140, s[12:15], s64 offen lds
	s_mov_b32 m0, s38
	s_nop 0
	buffer_load_dwordx4 v140, s[12:15], s65 offen lds
	s_waitcnt vmcnt(8)
	s_waitcnt lgkmcnt(0)
	s_setprio 1
	v_mfma_f32_16x16x32_bf16 v[62:65], v[132:135], v[172:175], v[62:65]
	v_mfma_f32_16x16x32_bf16 v[62:65], v[136:139], v[176:179], v[62:65]
	v_mfma_f32_16x16x32_bf16 v[58:61], v[148:151], v[172:175], v[58:61]
	v_mfma_f32_16x16x32_bf16 v[58:61], v[152:155], v[176:179], v[58:61]
	s_barrier
	v_mfma_f32_16x16x32_bf16 v[46:49], v[132:135], v[180:183], v[46:49]
	v_mfma_f32_16x16x32_bf16 v[46:49], v[136:139], v[184:187], v[46:49]
	v_mfma_f32_16x16x32_bf16 v[42:45], v[148:151], v[180:183], v[42:45]
	v_mfma_f32_16x16x32_bf16 v[42:45], v[152:155], v[184:187], v[42:45]
	v_mfma_f32_16x16x32_bf16 v[30:33], v[132:135], v[188:191], v[30:33]
	v_mfma_f32_16x16x32_bf16 v[30:33], v[136:139], v[192:195], v[30:33]
	v_mfma_f32_16x16x32_bf16 v[26:29], v[148:151], v[188:191], v[26:29]
	v_mfma_f32_16x16x32_bf16 v[26:29], v[152:155], v[192:195], v[26:29]
	v_mfma_f32_16x16x32_bf16 v[14:17], v[132:135], v[196:199], v[14:17]
	v_mfma_f32_16x16x32_bf16 v[14:17], v[136:139], v[200:203], v[14:17]
	v_mfma_f32_16x16x32_bf16 v[10:13], v[148:151], v[196:199], v[10:13]
	v_mfma_f32_16x16x32_bf16 v[10:13], v[152:155], v[200:203], v[10:13]
	v_mfma_f32_16x16x32_bf16 v[54:57], v[156:159], v[172:175], v[54:57]
	v_mfma_f32_16x16x32_bf16 v[54:57], v[160:163], v[176:179], v[54:57]
	v_mfma_f32_16x16x32_bf16 v[50:53], v[164:167], v[172:175], v[50:53]
	v_mfma_f32_16x16x32_bf16 v[50:53], v[168:171], v[176:179], v[50:53]
	v_mfma_f32_16x16x32_bf16 v[38:41], v[156:159], v[180:183], v[38:41]
	v_mfma_f32_16x16x32_bf16 v[38:41], v[160:163], v[184:187], v[38:41]
	v_mfma_f32_16x16x32_bf16 v[34:37], v[164:167], v[180:183], v[34:37]
	v_mfma_f32_16x16x32_bf16 v[34:37], v[168:171], v[184:187], v[34:37]
	v_mfma_f32_16x16x32_bf16 v[22:25], v[156:159], v[188:191], v[22:25]
	v_mfma_f32_16x16x32_bf16 v[22:25], v[160:163], v[192:195], v[22:25]
	v_mfma_f32_16x16x32_bf16 v[18:21], v[164:167], v[188:191], v[18:21]
	v_mfma_f32_16x16x32_bf16 v[18:21], v[168:171], v[192:195], v[18:21]
	v_mfma_f32_16x16x32_bf16 v[6:9], v[156:159], v[196:199], v[6:9]
	v_mfma_f32_16x16x32_bf16 v[6:9], v[160:163], v[200:203], v[6:9]
	v_mfma_f32_16x16x32_bf16 v[2:5], v[164:167], v[196:199], v[2:5]
	v_mfma_f32_16x16x32_bf16 v[2:5], v[168:171], v[200:203], v[2:5]
	s_setprio 0
	s_barrier
	ds_read_b128 v[132:135], v145
	ds_read_b128 v[136:139], v145 offset:1024
	ds_read_b128 v[148:151], v145 offset:2048
	ds_read_b128 v[152:155], v145 offset:3072
	ds_read_b128 v[156:159], v147
	ds_read_b128 v[160:163], v147 offset:1024
	ds_read_b128 v[164:167], v147 offset:2048
	ds_read_b128 v[168:171], v147 offset:3072
	s_mov_b32 m0, s39
	ds_read_b128 v[172:175], v144 offset:32768
	ds_read_b128 v[176:179], v144 offset:33792
	ds_read_b128 v[180:183], v144 offset:34816
	ds_read_b128 v[184:187], v144 offset:35840
	ds_read_b128 v[188:191], v144 offset:36864
	ds_read_b128 v[192:195], v144 offset:37888
	ds_read_b128 v[196:199], v144 offset:38912
	ds_read_b128 v[200:203], v144 offset:39936
	buffer_load_dwordx4 v140, s[12:15], s66 offen lds
	s_mov_b32 m0, s40
	s_nop 0
	buffer_load_dwordx4 v140, s[12:15], s67 offen lds
	s_waitcnt vmcnt(8)
	s_waitcnt lgkmcnt(0)
	s_setprio 1
	v_mfma_f32_16x16x32_bf16 v[126:129], v[132:135], v[172:175], v[126:129]
	v_mfma_f32_16x16x32_bf16 v[126:129], v[136:139], v[176:179], v[126:129]
	v_mfma_f32_16x16x32_bf16 v[122:125], v[148:151], v[172:175], v[122:125]
	v_mfma_f32_16x16x32_bf16 v[122:125], v[152:155], v[176:179], v[122:125]
	s_barrier
	v_mfma_f32_16x16x32_bf16 v[110:113], v[132:135], v[180:183], v[110:113]
	v_mfma_f32_16x16x32_bf16 v[110:113], v[136:139], v[184:187], v[110:113]
	v_mfma_f32_16x16x32_bf16 v[106:109], v[148:151], v[180:183], v[106:109]
	v_mfma_f32_16x16x32_bf16 v[106:109], v[152:155], v[184:187], v[106:109]
	v_mfma_f32_16x16x32_bf16 v[94:97], v[132:135], v[188:191], v[94:97]
	v_mfma_f32_16x16x32_bf16 v[94:97], v[136:139], v[192:195], v[94:97]
	v_mfma_f32_16x16x32_bf16 v[90:93], v[148:151], v[188:191], v[90:93]
	v_mfma_f32_16x16x32_bf16 v[90:93], v[152:155], v[192:195], v[90:93]
	v_mfma_f32_16x16x32_bf16 v[78:81], v[132:135], v[196:199], v[78:81]
	v_mfma_f32_16x16x32_bf16 v[78:81], v[136:139], v[200:203], v[78:81]
	v_mfma_f32_16x16x32_bf16 v[74:77], v[148:151], v[196:199], v[74:77]
	v_mfma_f32_16x16x32_bf16 v[74:77], v[152:155], v[200:203], v[74:77]
	v_mfma_f32_16x16x32_bf16 v[118:121], v[156:159], v[172:175], v[118:121]
	v_mfma_f32_16x16x32_bf16 v[118:121], v[160:163], v[176:179], v[118:121]
	v_mfma_f32_16x16x32_bf16 v[114:117], v[164:167], v[172:175], v[114:117]
	v_mfma_f32_16x16x32_bf16 v[114:117], v[168:171], v[176:179], v[114:117]
	v_mfma_f32_16x16x32_bf16 v[102:105], v[156:159], v[180:183], v[102:105]
	v_mfma_f32_16x16x32_bf16 v[102:105], v[160:163], v[184:187], v[102:105]
	v_mfma_f32_16x16x32_bf16 v[98:101], v[164:167], v[180:183], v[98:101]
	v_mfma_f32_16x16x32_bf16 v[98:101], v[168:171], v[184:187], v[98:101]
	v_mfma_f32_16x16x32_bf16 v[86:89], v[156:159], v[188:191], v[86:89]
	v_mfma_f32_16x16x32_bf16 v[86:89], v[160:163], v[192:195], v[86:89]
	v_mfma_f32_16x16x32_bf16 v[82:85], v[164:167], v[188:191], v[82:85]
	v_mfma_f32_16x16x32_bf16 v[82:85], v[168:171], v[192:195], v[82:85]
	v_mfma_f32_16x16x32_bf16 v[70:73], v[156:159], v[196:199], v[70:73]
	v_mfma_f32_16x16x32_bf16 v[70:73], v[160:163], v[200:203], v[70:73]
	v_mfma_f32_16x16x32_bf16 v[66:69], v[164:167], v[196:199], v[66:69]
	v_mfma_f32_16x16x32_bf16 v[66:69], v[168:171], v[200:203], v[66:69]
	s_setprio 0
	s_barrier
	s_mov_b32 m0, s48
	ds_read_b128 v[172:175], v144 offset:49152
	ds_read_b128 v[176:179], v144 offset:50176
	ds_read_b128 v[180:183], v144 offset:51200
	ds_read_b128 v[184:187], v144 offset:52224
	ds_read_b128 v[188:191], v144 offset:53248
	ds_read_b128 v[192:195], v144 offset:54272
	ds_read_b128 v[196:199], v144 offset:55296
	ds_read_b128 v[200:203], v144 offset:56320
	buffer_load_dwordx4 v141, s[16:19], s63 offen lds
	s_add_i32 s65, s64, 0x40080
	s_mov_b32 m0, s49
	s_add_i32 s66, s64, 0x80080
	buffer_load_dwordx4 v141, s[16:19], s65 offen lds
	s_mov_b32 m0, s52
	s_add_i32 s64, s64, 0xc0080
	buffer_load_dwordx4 v141, s[16:19], s66 offen lds
	s_mov_b32 m0, s53
	s_nop 0
	buffer_load_dwordx4 v141, s[16:19], s64 offen lds
	s_mov_b32 m0, s50
	s_nop 0
	buffer_load_dwordx4 v140, s[12:15], s63 offen lds
	s_mov_b32 m0, s51
	s_nop 0
	buffer_load_dwordx4 v140, s[12:15], s65 offen lds
	s_waitcnt vmcnt(8)
	s_waitcnt lgkmcnt(0)
	s_setprio 1
	v_mfma_f32_16x16x32_bf16 v[62:65], v[132:135], v[172:175], v[62:65]
	v_mfma_f32_16x16x32_bf16 v[62:65], v[136:139], v[176:179], v[62:65]
	v_mfma_f32_16x16x32_bf16 v[58:61], v[148:151], v[172:175], v[58:61]
	v_mfma_f32_16x16x32_bf16 v[58:61], v[152:155], v[176:179], v[58:61]
	s_barrier
	v_mfma_f32_16x16x32_bf16 v[46:49], v[132:135], v[180:183], v[46:49]
	v_mfma_f32_16x16x32_bf16 v[46:49], v[136:139], v[184:187], v[46:49]
	v_mfma_f32_16x16x32_bf16 v[42:45], v[148:151], v[180:183], v[42:45]
	v_mfma_f32_16x16x32_bf16 v[42:45], v[152:155], v[184:187], v[42:45]
	v_mfma_f32_16x16x32_bf16 v[30:33], v[132:135], v[188:191], v[30:33]
	v_mfma_f32_16x16x32_bf16 v[30:33], v[136:139], v[192:195], v[30:33]
	v_mfma_f32_16x16x32_bf16 v[26:29], v[148:151], v[188:191], v[26:29]
	v_mfma_f32_16x16x32_bf16 v[26:29], v[152:155], v[192:195], v[26:29]
	v_mfma_f32_16x16x32_bf16 v[14:17], v[132:135], v[196:199], v[14:17]
	v_mfma_f32_16x16x32_bf16 v[14:17], v[136:139], v[200:203], v[14:17]
	v_mfma_f32_16x16x32_bf16 v[10:13], v[148:151], v[196:199], v[10:13]
	v_mfma_f32_16x16x32_bf16 v[10:13], v[152:155], v[200:203], v[10:13]
	v_mfma_f32_16x16x32_bf16 v[54:57], v[156:159], v[172:175], v[54:57]
	v_mfma_f32_16x16x32_bf16 v[54:57], v[160:163], v[176:179], v[54:57]
	v_mfma_f32_16x16x32_bf16 v[50:53], v[164:167], v[172:175], v[50:53]
	v_mfma_f32_16x16x32_bf16 v[50:53], v[168:171], v[176:179], v[50:53]
	v_mfma_f32_16x16x32_bf16 v[38:41], v[156:159], v[180:183], v[38:41]
	v_mfma_f32_16x16x32_bf16 v[38:41], v[160:163], v[184:187], v[38:41]
	v_mfma_f32_16x16x32_bf16 v[34:37], v[164:167], v[180:183], v[34:37]
	v_mfma_f32_16x16x32_bf16 v[34:37], v[168:171], v[184:187], v[34:37]
	v_mfma_f32_16x16x32_bf16 v[22:25], v[156:159], v[188:191], v[22:25]
	v_mfma_f32_16x16x32_bf16 v[22:25], v[160:163], v[192:195], v[22:25]
	v_mfma_f32_16x16x32_bf16 v[18:21], v[164:167], v[188:191], v[18:21]
	v_mfma_f32_16x16x32_bf16 v[18:21], v[168:171], v[192:195], v[18:21]
	v_mfma_f32_16x16x32_bf16 v[6:9], v[156:159], v[196:199], v[6:9]
	v_mfma_f32_16x16x32_bf16 v[6:9], v[160:163], v[200:203], v[6:9]
	v_mfma_f32_16x16x32_bf16 v[2:5], v[164:167], v[196:199], v[2:5]
	v_mfma_f32_16x16x32_bf16 v[2:5], v[168:171], v[200:203], v[2:5]
	s_setprio 0
	s_barrier
	s_add_i32 s62, s62, 2
	s_addk_i32 s61, 0x100
	s_cmp_ge_i32 s62, s3
	s_cbranch_scc0 .LBB0_1050

.LBB0_1181:
	v_add_u32_e32 v2, 0x10000, v232
	ds_read_b128 v[134:137], v2
	ds_read_b128 v[138:141], v2 offset:1024
	ds_read_b128 v[142:145], v2 offset:2048
	ds_read_b128 v[146:149], v2 offset:3072
	v_add_u32_e32 v2, 0x14000, v232
	ds_read_b128 v[150:153], v2
	ds_read_b128 v[154:157], v2 offset:1024
	ds_read_b128 v[158:161], v2 offset:2048
	ds_read_b128 v[162:165], v2 offset:3072
	s_add_i32 s50, s47, s90
	s_and_b64 s[18:19], exec, s[18:19]
	s_cselect_b32 s51, s88, s50
	s_add_i32 s50, s92, 0x80
	s_or_b32 s52, s51, 0x80
	s_add_i32 s18, s89, s93
	s_add_i32 s94, s94, 0x1bfffc80
	s_cmp_lt_u32 s91, 8
	s_cselect_b32 s18, s18, s94
	s_mov_b32 m0, s74
	s_add_i32 s19, s18, 0x80000
	ds_read_b128 v[166:169], v233
	ds_read_b128 v[170:173], v233 offset:1024
	ds_read_b128 v[174:177], v233 offset:2048
	ds_read_b128 v[178:181], v233 offset:3072
	ds_read_b128 v[182:185], v233 offset:4096
	ds_read_b128 v[186:189], v233 offset:5120
	ds_read_b128 v[190:193], v233 offset:6144
	ds_read_b128 v[194:197], v233 offset:7168
	buffer_load_dwordx4 v230, s[12:15], s19 offen lds
	s_add_i32 s18, s18, 0xc0000
	s_mov_b32 m0, s75
	s_nop 0
	buffer_load_dwordx4 v230, s[12:15], s18 offen lds
	s_waitcnt vmcnt(8)
	s_waitcnt lgkmcnt(0)
	s_setprio 1
	v_mfma_f32_16x16x32_bf16 v[130:133], v[134:137], v[166:169], v[130:133]
	v_mfma_f32_16x16x32_bf16 v[130:133], v[138:141], v[170:173], v[130:133]
	v_mfma_f32_16x16x32_bf16 v[126:129], v[142:145], v[166:169], v[126:129]
	v_mfma_f32_16x16x32_bf16 v[126:129], v[146:149], v[170:173], v[126:129]
	s_barrier
	v_mfma_f32_16x16x32_bf16 v[114:117], v[134:137], v[174:177], v[114:117]
	v_mfma_f32_16x16x32_bf16 v[114:117], v[138:141], v[178:181], v[114:117]
	v_mfma_f32_16x16x32_bf16 v[110:113], v[142:145], v[174:177], v[110:113]
	v_mfma_f32_16x16x32_bf16 v[110:113], v[146:149], v[178:181], v[110:113]
	v_mfma_f32_16x16x32_bf16 v[98:101], v[134:137], v[182:185], v[98:101]
	v_mfma_f32_16x16x32_bf16 v[98:101], v[138:141], v[186:189], v[98:101]
	v_mfma_f32_16x16x32_bf16 v[94:97], v[142:145], v[182:185], v[94:97]
	v_mfma_f32_16x16x32_bf16 v[94:97], v[146:149], v[186:189], v[94:97]
	v_mfma_f32_16x16x32_bf16 v[82:85], v[134:137], v[190:193], v[82:85]
	v_mfma_f32_16x16x32_bf16 v[82:85], v[138:141], v[194:197], v[82:85]
	v_mfma_f32_16x16x32_bf16 v[78:81], v[142:145], v[190:193], v[78:81]
	v_mfma_f32_16x16x32_bf16 v[78:81], v[146:149], v[194:197], v[78:81]
	v_mfma_f32_16x16x32_bf16 v[122:125], v[150:153], v[166:169], v[122:125]
	v_mfma_f32_16x16x32_bf16 v[122:125], v[154:157], v[170:173], v[122:125]
	v_mfma_f32_16x16x32_bf16 v[118:121], v[158:161], v[166:169], v[118:121]
	v_mfma_f32_16x16x32_bf16 v[118:121], v[162:165], v[170:173], v[118:121]
	v_mfma_f32_16x16x32_bf16 v[106:109], v[150:153], v[174:177], v[106:109]
	v_mfma_f32_16x16x32_bf16 v[106:109], v[154:157], v[178:181], v[106:109]
	v_mfma_f32_16x16x32_bf16 v[102:105], v[158:161], v[174:177], v[102:105]
	v_mfma_f32_16x16x32_bf16 v[102:105], v[162:165], v[178:181], v[102:105]
	v_mfma_f32_16x16x32_bf16 v[90:93], v[150:153], v[182:185], v[90:93]
	v_mfma_f32_16x16x32_bf16 v[90:93], v[154:157], v[186:189], v[90:93]
	v_mfma_f32_16x16x32_bf16 v[86:89], v[158:161], v[182:185], v[86:89]
	v_mfma_f32_16x16x32_bf16 v[86:89], v[162:165], v[186:189], v[86:89]
	v_mfma_f32_16x16x32_bf16 v[74:77], v[150:153], v[190:193], v[74:77]
	v_mfma_f32_16x16x32_bf16 v[74:77], v[154:157], v[194:197], v[74:77]
	v_mfma_f32_16x16x32_bf16 v[70:73], v[158:161], v[190:193], v[70:73]
	v_mfma_f32_16x16x32_bf16 v[70:73], v[162:165], v[194:197], v[70:73]
	s_setprio 0
	s_barrier
	s_mov_b32 m0, s27
	s_mov_b32 s18, s14
	s_mov_b32 s19, s15
	ds_read_b128 v[166:169], v233 offset:16384
	ds_read_b128 v[170:173], v233 offset:17408
	ds_read_b128 v[174:177], v233 offset:18432
	ds_read_b128 v[178:181], v233 offset:19456
	ds_read_b128 v[182:185], v233 offset:20480
	ds_read_b128 v[186:189], v233 offset:21504
	ds_read_b128 v[190:193], v233 offset:22528
	ds_read_b128 v[194:197], v233 offset:23552
	buffer_load_dwordx4 v231, s[16:19], s51 offen lds
	s_add_i32 s53, s51, 0x18000
	s_mov_b32 m0, s30
	s_nop 0
	buffer_load_dwordx4 v231, s[16:19], s53 offen lds
	s_add_i32 s53, s51, 0x30000
	s_mov_b32 m0, s31
	s_nop 0
	buffer_load_dwordx4 v231, s[16:19], s53 offen lds
	s_add_i32 s53, s51, 0x48000
	s_mov_b32 m0, s54
	s_nop 0
	buffer_load_dwordx4 v231, s[16:19], s53 offen lds
	s_mov_b32 m0, s25
	s_add_i32 s53, s92, 0x40000
	buffer_load_dwordx4 v230, s[12:15], s92 offen lds
	s_mov_b32 m0, s55
	s_nop 0
	buffer_load_dwordx4 v230, s[12:15], s53 offen lds
	s_waitcnt vmcnt(8)
	s_waitcnt lgkmcnt(0)
	s_setprio 1
	v_mfma_f32_16x16x32_bf16 v[66:69], v[134:137], v[166:169], v[66:69]
	v_mfma_f32_16x16x32_bf16 v[62:65], v[142:145], v[166:169], v[62:65]
	v_mfma_f32_16x16x32_bf16 v[50:53], v[134:137], v[174:177], v[50:53]
	v_mfma_f32_16x16x32_bf16 v[46:49], v[142:145], v[174:177], v[46:49]
	s_barrier
	v_mfma_f32_16x16x32_bf16 v[34:37], v[134:137], v[182:185], v[34:37]
	v_mfma_f32_16x16x32_bf16 v[30:33], v[142:145], v[182:185], v[30:33]
	v_mfma_f32_16x16x32_bf16 v[18:21], v[134:137], v[190:193], v[18:21]
	v_mfma_f32_16x16x32_bf16 v[14:17], v[142:145], v[190:193], v[14:17]
	v_mfma_f32_16x16x32_bf16 v[58:61], v[150:153], v[166:169], v[58:61]
	v_mfma_f32_16x16x32_bf16 v[54:57], v[158:161], v[166:169], v[54:57]
	v_mfma_f32_16x16x32_bf16 v[42:45], v[150:153], v[174:177], v[42:45]
	v_mfma_f32_16x16x32_bf16 v[38:41], v[158:161], v[174:177], v[38:41]
	v_mfma_f32_16x16x32_bf16 v[26:29], v[150:153], v[182:185], v[26:29]
	v_mfma_f32_16x16x32_bf16 v[22:25], v[158:161], v[182:185], v[22:25]
	v_mfma_f32_16x16x32_bf16 v[10:13], v[150:153], v[190:193], v[10:13]
	v_mfma_f32_16x16x32_bf16 v[4:7], v[158:161], v[190:193], v[6:9]
	v_mfma_f32_16x16x32_bf16 v[66:69], v[138:141], v[170:173], v[66:69]
	v_mfma_f32_16x16x32_bf16 v[62:65], v[146:149], v[170:173], v[62:65]
	v_mfma_f32_16x16x32_bf16 v[50:53], v[138:141], v[178:181], v[50:53]
	v_mfma_f32_16x16x32_bf16 v[46:49], v[146:149], v[178:181], v[46:49]
	v_mfma_f32_16x16x32_bf16 v[34:37], v[138:141], v[186:189], v[34:37]
	v_mfma_f32_16x16x32_bf16 v[30:33], v[146:149], v[186:189], v[30:33]
	v_mfma_f32_16x16x32_bf16 v[18:21], v[138:141], v[194:197], v[18:21]
	v_mfma_f32_16x16x32_bf16 v[14:17], v[146:149], v[194:197], v[14:17]
	v_mfma_f32_16x16x32_bf16 v[58:61], v[154:157], v[170:173], v[58:61]
	v_mfma_f32_16x16x32_bf16 v[54:57], v[162:165], v[170:173], v[54:57]
	v_mfma_f32_16x16x32_bf16 v[42:45], v[154:157], v[178:181], v[42:45]
	v_mfma_f32_16x16x32_bf16 v[38:41], v[162:165], v[178:181], v[38:41]
	v_mfma_f32_16x16x32_bf16 v[26:29], v[154:157], v[186:189], v[26:29]
	v_mfma_f32_16x16x32_bf16 v[22:25], v[162:165], v[186:189], v[22:25]
	v_mfma_f32_16x16x32_bf16 v[10:13], v[154:157], v[194:197], v[10:13]
	v_mfma_f32_16x16x32_bf16 v[4:7], v[162:165], v[194:197], v[4:7]
	s_setprio 0
	s_barrier
	v_add_u32_e32 v2, 0x18000, v232
	ds_read_b128 v[134:137], v2
	ds_read_b128 v[138:141], v2 offset:1024
	ds_read_b128 v[142:145], v2 offset:2048
	ds_read_b128 v[146:149], v2 offset:3072
	v_add_u32_e32 v2, 0x1c000, v232
	ds_read_b128 v[150:153], v2
	ds_read_b128 v[154:157], v2 offset:1024
	ds_read_b128 v[158:161], v2 offset:2048
	ds_read_b128 v[162:165], v2 offset:3072
	s_mov_b32 m0, s56
	s_add_i32 s53, s92, 0x80000
	ds_read_b128 v[166:169], v233 offset:32768
	ds_read_b128 v[170:173], v233 offset:33792
	ds_read_b128 v[174:177], v233 offset:34816
	ds_read_b128 v[178:181], v233 offset:35840
	ds_read_b128 v[182:185], v233 offset:36864
	ds_read_b128 v[186:189], v233 offset:37888
	ds_read_b128 v[190:193], v233 offset:38912
	ds_read_b128 v[194:197], v233 offset:39936
	buffer_load_dwordx4 v230, s[12:15], s53 offen lds
	s_add_i32 s53, s92, 0xc0000
	s_mov_b32 m0, s57
	s_nop 0
	buffer_load_dwordx4 v230, s[12:15], s53 offen lds
	s_waitcnt vmcnt(8)
	s_waitcnt lgkmcnt(0)
	s_setprio 1
	v_mfma_f32_16x16x32_bf16 v[130:133], v[134:137], v[166:169], v[130:133]
	v_mfma_f32_16x16x32_bf16 v[130:133], v[138:141], v[170:173], v[130:133]
	v_mfma_f32_16x16x32_bf16 v[126:129], v[142:145], v[166:169], v[126:129]
	v_mfma_f32_16x16x32_bf16 v[126:129], v[146:149], v[170:173], v[126:129]
	s_barrier
	v_mfma_f32_16x16x32_bf16 v[114:117], v[134:137], v[174:177], v[114:117]
	v_mfma_f32_16x16x32_bf16 v[114:117], v[138:141], v[178:181], v[114:117]
	v_mfma_f32_16x16x32_bf16 v[110:113], v[142:145], v[174:177], v[110:113]
	v_mfma_f32_16x16x32_bf16 v[110:113], v[146:149], v[178:181], v[110:113]
	v_mfma_f32_16x16x32_bf16 v[98:101], v[134:137], v[182:185], v[98:101]
	v_mfma_f32_16x16x32_bf16 v[98:101], v[138:141], v[186:189], v[98:101]
	v_mfma_f32_16x16x32_bf16 v[94:97], v[142:145], v[182:185], v[94:97]
	v_mfma_f32_16x16x32_bf16 v[94:97], v[146:149], v[186:189], v[94:97]
	v_mfma_f32_16x16x32_bf16 v[82:85], v[134:137], v[190:193], v[82:85]
	v_mfma_f32_16x16x32_bf16 v[82:85], v[138:141], v[194:197], v[82:85]
	v_mfma_f32_16x16x32_bf16 v[78:81], v[142:145], v[190:193], v[78:81]
	v_mfma_f32_16x16x32_bf16 v[78:81], v[146:149], v[194:197], v[78:81]
	v_mfma_f32_16x16x32_bf16 v[122:125], v[150:153], v[166:169], v[122:125]
	v_mfma_f32_16x16x32_bf16 v[122:125], v[154:157], v[170:173], v[122:125]
	v_mfma_f32_16x16x32_bf16 v[118:121], v[158:161], v[166:169], v[118:121]
	v_mfma_f32_16x16x32_bf16 v[118:121], v[162:165], v[170:173], v[118:121]
	v_mfma_f32_16x16x32_bf16 v[106:109], v[150:153], v[174:177], v[106:109]
	v_mfma_f32_16x16x32_bf16 v[106:109], v[154:157], v[178:181], v[106:109]
	v_mfma_f32_16x16x32_bf16 v[102:105], v[158:161], v[174:177], v[102:105]
	v_mfma_f32_16x16x32_bf16 v[102:105], v[162:165], v[178:181], v[102:105]
	v_mfma_f32_16x16x32_bf16 v[90:93], v[150:153], v[182:185], v[90:93]
	v_mfma_f32_16x16x32_bf16 v[90:93], v[154:157], v[186:189], v[90:93]
	v_mfma_f32_16x16x32_bf16 v[86:89], v[158:161], v[182:185], v[86:89]
	v_mfma_f32_16x16x32_bf16 v[86:89], v[162:165], v[186:189], v[86:89]
	v_mfma_f32_16x16x32_bf16 v[74:77], v[150:153], v[190:193], v[74:77]
	v_mfma_f32_16x16x32_bf16 v[74:77], v[154:157], v[194:197], v[74:77]
	v_mfma_f32_16x16x32_bf16 v[70:73], v[158:161], v[190:193], v[70:73]
	v_mfma_f32_16x16x32_bf16 v[70:73], v[162:165], v[194:197], v[70:73]
	s_setprio 0
	s_barrier
	s_mov_b32 m0, s64
	ds_read_b128 v[166:169], v233 offset:49152
	ds_read_b128 v[170:173], v233 offset:50176
	ds_read_b128 v[174:177], v233 offset:51200
	ds_read_b128 v[178:181], v233 offset:52224
	ds_read_b128 v[182:185], v233 offset:53248
	ds_read_b128 v[186:189], v233 offset:54272
	ds_read_b128 v[190:193], v233 offset:55296
	ds_read_b128 v[194:197], v233 offset:56320
	buffer_load_dwordx4 v231, s[16:19], s52 offen lds
	s_add_i32 s52, s51, 0x18080
	s_mov_b32 m0, s65
	s_nop 0
	buffer_load_dwordx4 v231, s[16:19], s52 offen lds
	s_add_i32 s52, s51, 0x30080
	s_mov_b32 m0, s68
	s_add_i32 s51, s51, 0x48080
	buffer_load_dwordx4 v231, s[16:19], s52 offen lds
	s_mov_b32 m0, s69
	s_nop 0
	buffer_load_dwordx4 v231, s[16:19], s51 offen lds
	s_mov_b32 m0, s66
	s_add_i32 s18, s92, 0x40080
	buffer_load_dwordx4 v230, s[12:15], s50 offen lds
	s_mov_b32 m0, s67
	s_nop 0
	buffer_load_dwordx4 v230, s[12:15], s18 offen lds
	s_waitcnt vmcnt(8)
	s_waitcnt lgkmcnt(0)
	s_setprio 1
	v_mfma_f32_16x16x32_bf16 v[66:69], v[134:137], v[166:169], v[66:69]
	v_mfma_f32_16x16x32_bf16 v[62:65], v[142:145], v[166:169], v[62:65]
	v_mfma_f32_16x16x32_bf16 v[50:53], v[134:137], v[174:177], v[50:53]
	v_mfma_f32_16x16x32_bf16 v[46:49], v[142:145], v[174:177], v[46:49]
	s_barrier
	v_mfma_f32_16x16x32_bf16 v[34:37], v[134:137], v[182:185], v[34:37]
	v_mfma_f32_16x16x32_bf16 v[30:33], v[142:145], v[182:185], v[30:33]
	v_mfma_f32_16x16x32_bf16 v[18:21], v[134:137], v[190:193], v[18:21]
	v_mfma_f32_16x16x32_bf16 v[14:17], v[142:145], v[190:193], v[14:17]
	v_mfma_f32_16x16x32_bf16 v[58:61], v[150:153], v[166:169], v[58:61]
	v_mfma_f32_16x16x32_bf16 v[54:57], v[158:161], v[166:169], v[54:57]
	v_mfma_f32_16x16x32_bf16 v[42:45], v[150:153], v[174:177], v[42:45]
	v_mfma_f32_16x16x32_bf16 v[38:41], v[158:161], v[174:177], v[38:41]
	v_mfma_f32_16x16x32_bf16 v[26:29], v[150:153], v[182:185], v[26:29]
	v_mfma_f32_16x16x32_bf16 v[22:25], v[158:161], v[182:185], v[22:25]
	v_mfma_f32_16x16x32_bf16 v[8:11], v[150:153], v[190:193], v[10:13]
	v_mfma_f32_16x16x32_bf16 v[4:7], v[158:161], v[190:193], v[4:7]
	v_mfma_f32_16x16x32_bf16 v[66:69], v[138:141], v[170:173], v[66:69]
	v_mfma_f32_16x16x32_bf16 v[62:65], v[146:149], v[170:173], v[62:65]
	v_mfma_f32_16x16x32_bf16 v[50:53], v[138:141], v[178:181], v[50:53]
	v_mfma_f32_16x16x32_bf16 v[46:49], v[146:149], v[178:181], v[46:49]
	v_mfma_f32_16x16x32_bf16 v[34:37], v[138:141], v[186:189], v[34:37]
	v_mfma_f32_16x16x32_bf16 v[30:33], v[146:149], v[186:189], v[30:33]
	v_mfma_f32_16x16x32_bf16 v[18:21], v[138:141], v[194:197], v[18:21]
	v_mfma_f32_16x16x32_bf16 v[14:17], v[146:149], v[194:197], v[14:17]
	v_mfma_f32_16x16x32_bf16 v[58:61], v[154:157], v[170:173], v[58:61]
	v_mfma_f32_16x16x32_bf16 v[54:57], v[162:165], v[170:173], v[54:57]
	v_mfma_f32_16x16x32_bf16 v[42:45], v[154:157], v[178:181], v[42:45]
	v_mfma_f32_16x16x32_bf16 v[38:41], v[162:165], v[178:181], v[38:41]
	v_mfma_f32_16x16x32_bf16 v[26:29], v[154:157], v[186:189], v[26:29]
	v_mfma_f32_16x16x32_bf16 v[22:25], v[162:165], v[186:189], v[22:25]
	v_mfma_f32_16x16x32_bf16 v[10:13], v[154:157], v[194:197], v[8:11]
	v_mfma_f32_16x16x32_bf16 v[6:9], v[162:165], v[194:197], v[4:7]
	s_setprio 0
	s_barrier
	s_add_i32 s91, s91, 2
	s_addk_i32 s90, 0x100
	s_cmp_ge_i32 s91, s3
	s_cbranch_scc1 .LBB0_1193

.LBB0_1290:
	ds_read_b128 v[106:109], v224
	ds_read_b128 v[118:121], v224 offset:1024
	ds_read_b128 v[130:133], v224 offset:2048
	ds_read_b128 v[138:141], v224 offset:3072
	ds_read_b128 v[146:149], v225
	ds_read_b128 v[150:153], v225 offset:1024
	ds_read_b128 v[154:157], v225 offset:2048
	ds_read_b128 v[158:161], v225 offset:3072
	s_add_i32 s18, s72, 0xffe80080
	s_cmp_eq_u32 s56, s74
	s_cselect_b32 s75, s6, s18
	s_cselect_b32 s77, s7, s73
	s_or_b32 s76, s75, 0x80
	s_add_i32 s18, s72, 0xfff80000
	s_mov_b32 m0, s57
	ds_read_b128 v[162:165], v226
	ds_read_b128 v[166:169], v226 offset:1024
	ds_read_b128 v[170:173], v226 offset:2048
	ds_read_b128 v[174:177], v226 offset:3072
	ds_read_b128 v[178:181], v226 offset:4096
	ds_read_b128 v[182:185], v226 offset:5120
	ds_read_b128 v[190:193], v226 offset:6144
	ds_read_b128 v[194:197], v226 offset:7168
	buffer_load_dwordx4 v222, s[12:15], s18 offen lds
	s_mov_b32 m0, s60
	s_nop 0
	buffer_load_dwordx4 v222, s[12:15], s72 offen lds
	s_waitcnt vmcnt(8)
	s_waitcnt lgkmcnt(0)
	s_setprio 1
	v_mfma_f32_16x16x32_bf16 v[142:145], v[106:109], v[162:165], v[142:145]
	v_mfma_f32_16x16x32_bf16 v[142:145], v[118:121], v[166:169], v[142:145]
	v_mfma_f32_16x16x32_bf16 v[134:137], v[130:133], v[162:165], v[134:137]
	v_mfma_f32_16x16x32_bf16 v[134:137], v[138:141], v[166:169], v[134:137]
	s_barrier
	v_mfma_f32_16x16x32_bf16 v[114:117], v[106:109], v[170:173], v[114:117]
	v_mfma_f32_16x16x32_bf16 v[114:117], v[118:121], v[174:177], v[114:117]
	v_mfma_f32_16x16x32_bf16 v[110:113], v[130:133], v[170:173], v[110:113]
	v_mfma_f32_16x16x32_bf16 v[110:113], v[138:141], v[174:177], v[110:113]
	v_mfma_f32_16x16x32_bf16 v[94:97], v[106:109], v[178:181], v[94:97]
	v_mfma_f32_16x16x32_bf16 v[94:97], v[118:121], v[182:185], v[94:97]
	v_mfma_f32_16x16x32_bf16 v[90:93], v[130:133], v[178:181], v[90:93]
	v_mfma_f32_16x16x32_bf16 v[90:93], v[138:141], v[182:185], v[90:93]
	v_mfma_f32_16x16x32_bf16 v[78:81], v[106:109], v[190:193], v[78:81]
	v_mfma_f32_16x16x32_bf16 v[78:81], v[118:121], v[194:197], v[78:81]
	v_mfma_f32_16x16x32_bf16 v[74:77], v[130:133], v[190:193], v[74:77]
	v_mfma_f32_16x16x32_bf16 v[74:77], v[138:141], v[194:197], v[74:77]
	v_mfma_f32_16x16x32_bf16 v[126:129], v[146:149], v[162:165], v[126:129]
	v_mfma_f32_16x16x32_bf16 v[126:129], v[150:153], v[166:169], v[126:129]
	v_mfma_f32_16x16x32_bf16 v[122:125], v[154:157], v[162:165], v[122:125]
	v_mfma_f32_16x16x32_bf16 v[122:125], v[158:161], v[166:169], v[122:125]
	v_mfma_f32_16x16x32_bf16 v[102:105], v[146:149], v[170:173], v[102:105]
	v_mfma_f32_16x16x32_bf16 v[102:105], v[150:153], v[174:177], v[102:105]
	v_mfma_f32_16x16x32_bf16 v[98:101], v[154:157], v[170:173], v[98:101]
	v_mfma_f32_16x16x32_bf16 v[98:101], v[158:161], v[174:177], v[98:101]
	v_mfma_f32_16x16x32_bf16 v[86:89], v[146:149], v[178:181], v[86:89]
	v_mfma_f32_16x16x32_bf16 v[86:89], v[150:153], v[182:185], v[86:89]
	v_mfma_f32_16x16x32_bf16 v[82:85], v[154:157], v[178:181], v[82:85]
	v_mfma_f32_16x16x32_bf16 v[82:85], v[158:161], v[182:185], v[82:85]
	v_mfma_f32_16x16x32_bf16 v[70:73], v[146:149], v[190:193], v[70:73]
	v_mfma_f32_16x16x32_bf16 v[70:73], v[150:153], v[194:197], v[70:73]
	v_mfma_f32_16x16x32_bf16 v[66:69], v[154:157], v[190:193], v[66:69]
	v_mfma_f32_16x16x32_bf16 v[66:69], v[158:161], v[194:197], v[66:69]
	s_setprio 0
	s_barrier
	s_mov_b32 m0, s27
	s_mov_b32 s18, s14
	s_mov_b32 s19, s15
	ds_read_b128 v[162:165], v226 offset:16384
	ds_read_b128 v[166:169], v226 offset:17408
	ds_read_b128 v[170:173], v226 offset:18432
	ds_read_b128 v[174:177], v226 offset:19456
	ds_read_b128 v[178:181], v226 offset:20480
	ds_read_b128 v[182:185], v226 offset:21504
	ds_read_b128 v[190:193], v226 offset:22528
	ds_read_b128 v[194:197], v226 offset:23552
	buffer_load_dwordx4 v223, s[16:19], s77 offen lds
	s_add_i32 s78, s77, 0x80000
	s_mov_b32 m0, s30
	s_nop 0
	buffer_load_dwordx4 v223, s[16:19], s78 offen lds
	s_add_i32 s78, s77, 0x100000
	s_mov_b32 m0, s31
	s_nop 0
	buffer_load_dwordx4 v223, s[16:19], s78 offen lds
	s_add_i32 s78, s77, 0x180000
	s_mov_b32 m0, s41
	s_nop 0
	buffer_load_dwordx4 v223, s[16:19], s78 offen lds
	s_mov_b32 m0, s25
	s_add_i32 s78, s75, 0x80000
	buffer_load_dwordx4 v222, s[12:15], s75 offen lds
	s_mov_b32 m0, s42
	s_nop 0
	buffer_load_dwordx4 v222, s[12:15], s78 offen lds
	s_waitcnt vmcnt(8)
	s_waitcnt lgkmcnt(0)
	s_setprio 1
	v_mfma_f32_16x16x32_bf16 v[62:65], v[106:109], v[162:165], v[62:65]
	v_mfma_f32_16x16x32_bf16 v[62:65], v[118:121], v[166:169], v[62:65]
	v_mfma_f32_16x16x32_bf16 v[58:61], v[130:133], v[162:165], v[58:61]
	v_mfma_f32_16x16x32_bf16 v[58:61], v[138:141], v[166:169], v[58:61]
	s_barrier
	v_mfma_f32_16x16x32_bf16 v[46:49], v[106:109], v[170:173], v[46:49]
	v_mfma_f32_16x16x32_bf16 v[46:49], v[118:121], v[174:177], v[46:49]
	v_mfma_f32_16x16x32_bf16 v[42:45], v[130:133], v[170:173], v[42:45]
	v_mfma_f32_16x16x32_bf16 v[42:45], v[138:141], v[174:177], v[42:45]
	v_mfma_f32_16x16x32_bf16 v[30:33], v[106:109], v[178:181], v[30:33]
	v_mfma_f32_16x16x32_bf16 v[30:33], v[118:121], v[182:185], v[30:33]
	v_mfma_f32_16x16x32_bf16 v[26:29], v[130:133], v[178:181], v[26:29]
	v_mfma_f32_16x16x32_bf16 v[26:29], v[138:141], v[182:185], v[26:29]
	v_mfma_f32_16x16x32_bf16 v[14:17], v[106:109], v[190:193], v[14:17]
	v_mfma_f32_16x16x32_bf16 v[14:17], v[118:121], v[194:197], v[14:17]
	v_mfma_f32_16x16x32_bf16 v[10:13], v[130:133], v[190:193], v[10:13]
	v_mfma_f32_16x16x32_bf16 v[10:13], v[138:141], v[194:197], v[10:13]
	v_mfma_f32_16x16x32_bf16 v[54:57], v[146:149], v[162:165], v[54:57]
	v_mfma_f32_16x16x32_bf16 v[54:57], v[150:153], v[166:169], v[54:57]
	v_mfma_f32_16x16x32_bf16 v[50:53], v[154:157], v[162:165], v[50:53]
	v_mfma_f32_16x16x32_bf16 v[50:53], v[158:161], v[166:169], v[50:53]
	v_mfma_f32_16x16x32_bf16 v[38:41], v[146:149], v[170:173], v[38:41]
	v_mfma_f32_16x16x32_bf16 v[38:41], v[150:153], v[174:177], v[38:41]
	v_mfma_f32_16x16x32_bf16 v[34:37], v[154:157], v[170:173], v[34:37]
	v_mfma_f32_16x16x32_bf16 v[34:37], v[158:161], v[174:177], v[34:37]
	v_mfma_f32_16x16x32_bf16 v[22:25], v[146:149], v[178:181], v[22:25]
	v_mfma_f32_16x16x32_bf16 v[22:25], v[150:153], v[182:185], v[22:25]
	v_mfma_f32_16x16x32_bf16 v[18:21], v[154:157], v[178:181], v[18:21]
	v_mfma_f32_16x16x32_bf16 v[18:21], v[158:161], v[182:185], v[18:21]
	v_mfma_f32_16x16x32_bf16 v[6:9], v[146:149], v[190:193], v[6:9]
	v_mfma_f32_16x16x32_bf16 v[6:9], v[150:153], v[194:197], v[6:9]
	v_mfma_f32_16x16x32_bf16 v[2:5], v[154:157], v[190:193], v[2:5]
	v_mfma_f32_16x16x32_bf16 v[2:5], v[158:161], v[194:197], v[2:5]
	s_setprio 0
	s_barrier
	ds_read_b128 v[106:109], v227
	ds_read_b128 v[118:121], v227 offset:1024
	ds_read_b128 v[130:133], v227 offset:2048
	ds_read_b128 v[138:141], v227 offset:3072
	ds_read_b128 v[146:149], v228
	ds_read_b128 v[150:153], v228 offset:1024
	ds_read_b128 v[154:157], v228 offset:2048
	ds_read_b128 v[158:161], v228 offset:3072
	s_mov_b32 m0, s43
	s_add_i32 s78, s75, 0x100000
	ds_read_b128 v[162:165], v226 offset:32768
	ds_read_b128 v[166:169], v226 offset:33792
	ds_read_b128 v[170:173], v226 offset:34816
	ds_read_b128 v[174:177], v226 offset:35840
	ds_read_b128 v[178:181], v226 offset:36864
	ds_read_b128 v[182:185], v226 offset:37888
	ds_read_b128 v[190:193], v226 offset:38912
	ds_read_b128 v[194:197], v226 offset:39936
	buffer_load_dwordx4 v222, s[12:15], s78 offen lds
	s_add_i32 s78, s75, 0x180000
	s_mov_b32 m0, s44
	s_nop 0
	buffer_load_dwordx4 v222, s[12:15], s78 offen lds
	s_waitcnt vmcnt(8)
	s_waitcnt lgkmcnt(0)
	s_setprio 1
	v_mfma_f32_16x16x32_bf16 v[142:145], v[106:109], v[162:165], v[142:145]
	v_mfma_f32_16x16x32_bf16 v[142:145], v[118:121], v[166:169], v[142:145]
	v_mfma_f32_16x16x32_bf16 v[134:137], v[130:133], v[162:165], v[134:137]
	v_mfma_f32_16x16x32_bf16 v[134:137], v[138:141], v[166:169], v[134:137]
	s_barrier
	v_mfma_f32_16x16x32_bf16 v[114:117], v[106:109], v[170:173], v[114:117]
	v_mfma_f32_16x16x32_bf16 v[114:117], v[118:121], v[174:177], v[114:117]
	v_mfma_f32_16x16x32_bf16 v[110:113], v[130:133], v[170:173], v[110:113]
	v_mfma_f32_16x16x32_bf16 v[110:113], v[138:141], v[174:177], v[110:113]
	v_mfma_f32_16x16x32_bf16 v[94:97], v[106:109], v[178:181], v[94:97]
	v_mfma_f32_16x16x32_bf16 v[94:97], v[118:121], v[182:185], v[94:97]
	v_mfma_f32_16x16x32_bf16 v[90:93], v[130:133], v[178:181], v[90:93]
	v_mfma_f32_16x16x32_bf16 v[90:93], v[138:141], v[182:185], v[90:93]
	v_mfma_f32_16x16x32_bf16 v[78:81], v[106:109], v[190:193], v[78:81]
	v_mfma_f32_16x16x32_bf16 v[78:81], v[118:121], v[194:197], v[78:81]
	v_mfma_f32_16x16x32_bf16 v[74:77], v[130:133], v[190:193], v[74:77]
	v_mfma_f32_16x16x32_bf16 v[74:77], v[138:141], v[194:197], v[74:77]
	v_mfma_f32_16x16x32_bf16 v[126:129], v[146:149], v[162:165], v[126:129]
	v_mfma_f32_16x16x32_bf16 v[126:129], v[150:153], v[166:169], v[126:129]
	v_mfma_f32_16x16x32_bf16 v[122:125], v[154:157], v[162:165], v[122:125]
	v_mfma_f32_16x16x32_bf16 v[122:125], v[158:161], v[166:169], v[122:125]
	v_mfma_f32_16x16x32_bf16 v[102:105], v[146:149], v[170:173], v[102:105]
	v_mfma_f32_16x16x32_bf16 v[102:105], v[150:153], v[174:177], v[102:105]
	v_mfma_f32_16x16x32_bf16 v[98:101], v[154:157], v[170:173], v[98:101]
	v_mfma_f32_16x16x32_bf16 v[98:101], v[158:161], v[174:177], v[98:101]
	v_mfma_f32_16x16x32_bf16 v[86:89], v[146:149], v[178:181], v[86:89]
	v_mfma_f32_16x16x32_bf16 v[86:89], v[150:153], v[182:185], v[86:89]
	v_mfma_f32_16x16x32_bf16 v[82:85], v[154:157], v[178:181], v[82:85]
	v_mfma_f32_16x16x32_bf16 v[82:85], v[158:161], v[182:185], v[82:85]
	v_mfma_f32_16x16x32_bf16 v[70:73], v[146:149], v[190:193], v[70:73]
	v_mfma_f32_16x16x32_bf16 v[70:73], v[150:153], v[194:197], v[70:73]
	v_mfma_f32_16x16x32_bf16 v[66:69], v[154:157], v[190:193], v[66:69]
	v_mfma_f32_16x16x32_bf16 v[66:69], v[158:161], v[194:197], v[66:69]
	s_setprio 0
	s_barrier
	s_mov_b32 m0, s48
	s_or_b32 s78, s77, 0x80
	ds_read_b128 v[162:165], v226 offset:49152
	ds_read_b128 v[166:169], v226 offset:50176
	ds_read_b128 v[170:173], v226 offset:51200
	ds_read_b128 v[174:177], v226 offset:52224
	ds_read_b128 v[178:181], v226 offset:53248
	ds_read_b128 v[182:185], v226 offset:54272
	ds_read_b128 v[190:193], v226 offset:55296
	ds_read_b128 v[194:197], v226 offset:56320
	buffer_load_dwordx4 v223, s[16:19], s78 offen lds
	s_add_i32 s78, s77, 0x80080
	s_mov_b32 m0, s49
	s_add_i32 s75, s75, 0x80080
	buffer_load_dwordx4 v223, s[16:19], s78 offen lds
	s_add_i32 s78, s77, 0x100080
	s_mov_b32 m0, s52
	s_add_i32 s77, s77, 0x180080
	buffer_load_dwordx4 v223, s[16:19], s78 offen lds
	s_mov_b32 m0, s53
	s_nop 0
	buffer_load_dwordx4 v223, s[16:19], s77 offen lds
	s_mov_b32 m0, s50
	s_nop 0
	buffer_load_dwordx4 v222, s[12:15], s76 offen lds
	s_mov_b32 m0, s51
	s_nop 0
	buffer_load_dwordx4 v222, s[12:15], s75 offen lds
	s_waitcnt vmcnt(8)
	s_waitcnt lgkmcnt(0)
	s_setprio 1
	v_mfma_f32_16x16x32_bf16 v[62:65], v[106:109], v[162:165], v[62:65]
	v_mfma_f32_16x16x32_bf16 v[62:65], v[118:121], v[166:169], v[62:65]
	v_mfma_f32_16x16x32_bf16 v[58:61], v[130:133], v[162:165], v[58:61]
	v_mfma_f32_16x16x32_bf16 v[58:61], v[138:141], v[166:169], v[58:61]
	s_barrier
	v_mfma_f32_16x16x32_bf16 v[46:49], v[106:109], v[170:173], v[46:49]
	v_mfma_f32_16x16x32_bf16 v[46:49], v[118:121], v[174:177], v[46:49]
	v_mfma_f32_16x16x32_bf16 v[42:45], v[130:133], v[170:173], v[42:45]
	v_mfma_f32_16x16x32_bf16 v[42:45], v[138:141], v[174:177], v[42:45]
	v_mfma_f32_16x16x32_bf16 v[30:33], v[106:109], v[178:181], v[30:33]
	v_mfma_f32_16x16x32_bf16 v[30:33], v[118:121], v[182:185], v[30:33]
	v_mfma_f32_16x16x32_bf16 v[26:29], v[130:133], v[178:181], v[26:29]
	v_mfma_f32_16x16x32_bf16 v[26:29], v[138:141], v[182:185], v[26:29]
	v_mfma_f32_16x16x32_bf16 v[14:17], v[106:109], v[190:193], v[14:17]
	v_mfma_f32_16x16x32_bf16 v[14:17], v[118:121], v[194:197], v[14:17]
	v_mfma_f32_16x16x32_bf16 v[10:13], v[130:133], v[190:193], v[10:13]
	v_mfma_f32_16x16x32_bf16 v[10:13], v[138:141], v[194:197], v[10:13]
	v_mfma_f32_16x16x32_bf16 v[54:57], v[146:149], v[162:165], v[54:57]
	v_mfma_f32_16x16x32_bf16 v[54:57], v[150:153], v[166:169], v[54:57]
	v_mfma_f32_16x16x32_bf16 v[50:53], v[154:157], v[162:165], v[50:53]
	v_mfma_f32_16x16x32_bf16 v[50:53], v[158:161], v[166:169], v[50:53]
	v_mfma_f32_16x16x32_bf16 v[38:41], v[146:149], v[170:173], v[38:41]
	v_mfma_f32_16x16x32_bf16 v[38:41], v[150:153], v[174:177], v[38:41]
	v_mfma_f32_16x16x32_bf16 v[34:37], v[154:157], v[170:173], v[34:37]
	v_mfma_f32_16x16x32_bf16 v[34:37], v[158:161], v[174:177], v[34:37]
	v_mfma_f32_16x16x32_bf16 v[22:25], v[146:149], v[178:181], v[22:25]
	v_mfma_f32_16x16x32_bf16 v[22:25], v[150:153], v[182:185], v[22:25]
	v_mfma_f32_16x16x32_bf16 v[18:21], v[154:157], v[178:181], v[18:21]
	v_mfma_f32_16x16x32_bf16 v[18:21], v[158:161], v[182:185], v[18:21]
	v_mfma_f32_16x16x32_bf16 v[6:9], v[146:149], v[190:193], v[6:9]
	v_mfma_f32_16x16x32_bf16 v[6:9], v[150:153], v[194:197], v[6:9]
	v_mfma_f32_16x16x32_bf16 v[2:5], v[154:157], v[190:193], v[2:5]
	v_mfma_f32_16x16x32_bf16 v[2:5], v[158:161], v[194:197], v[2:5]
	s_setprio 0
	s_barrier
	s_add_i32 s74, s74, 2
	s_addk_i32 s72, 0x100
	s_addk_i32 s73, 0x100
	s_cmp_ge_i32 s74, s3
	s_cbranch_scc0 .LBB0_1290
	s_and_b64 vcc, exec, s[38:39]
	s_cbranch_vccz .LBB0_1293

.LBB0_1382:
	ds_read_b128 v[144:147], v138
	ds_read_b128 v[148:151], v138 offset:1024
	ds_read_b128 v[152:155], v138 offset:2048
	ds_read_b128 v[156:159], v138 offset:3072
	ds_read_b128 v[160:163], v139
	ds_read_b128 v[164:167], v139 offset:1024
	ds_read_b128 v[168:171], v139 offset:2048
	ds_read_b128 v[172:175], v139 offset:3072
	s_add_i32 s14, s74, 0xffe80080
	s_cmp_eq_u32 s61, s76
	s_cselect_b32 s77, s72, s14
	s_cselect_b32 s79, s73, s75
	s_or_b32 s78, s77, 0x80
	s_add_i32 s14, s74, 0xfff80000
	s_mov_b32 m0, s62
	ds_read_b128 v[176:179], v140
	ds_read_b128 v[180:183], v140 offset:1024
	ds_read_b128 v[184:187], v140 offset:2048
	ds_read_b128 v[188:191], v140 offset:3072
	ds_read_b128 v[192:195], v140 offset:4096
	ds_read_b128 v[196:199], v140 offset:5120
	ds_read_b128 v[200:203], v140 offset:6144
	ds_read_b128 v[204:207], v140 offset:7168
	buffer_load_dwordx4 v136, s[16:19], s14 offen lds
	s_mov_b32 m0, s63
	s_nop 0
	buffer_load_dwordx4 v136, s[16:19], s74 offen lds
	s_waitcnt vmcnt(8)
	s_waitcnt lgkmcnt(0)
	s_setprio 1
	v_mfma_f32_16x16x32_bf16 v[118:121], v[144:147], v[176:179], v[118:121]
	v_mfma_f32_16x16x32_bf16 v[118:121], v[148:151], v[180:183], v[118:121]
	v_mfma_f32_16x16x32_bf16 v[114:117], v[152:155], v[176:179], v[114:117]
	v_mfma_f32_16x16x32_bf16 v[114:117], v[156:159], v[180:183], v[114:117]
	s_barrier
	v_mfma_f32_16x16x32_bf16 v[110:113], v[144:147], v[184:187], v[110:113]
	v_mfma_f32_16x16x32_bf16 v[110:113], v[148:151], v[188:191], v[110:113]
	v_mfma_f32_16x16x32_bf16 v[102:105], v[152:155], v[184:187], v[102:105]
	v_mfma_f32_16x16x32_bf16 v[102:105], v[156:159], v[188:191], v[102:105]
	v_mfma_f32_16x16x32_bf16 v[94:97], v[144:147], v[192:195], v[94:97]
	v_mfma_f32_16x16x32_bf16 v[94:97], v[148:151], v[196:199], v[94:97]
	v_mfma_f32_16x16x32_bf16 v[86:89], v[152:155], v[192:195], v[86:89]
	v_mfma_f32_16x16x32_bf16 v[86:89], v[156:159], v[196:199], v[86:89]
	v_mfma_f32_16x16x32_bf16 v[78:81], v[144:147], v[200:203], v[78:81]
	v_mfma_f32_16x16x32_bf16 v[78:81], v[148:151], v[204:207], v[78:81]
	v_mfma_f32_16x16x32_bf16 v[66:69], v[152:155], v[200:203], v[66:69]
	v_mfma_f32_16x16x32_bf16 v[66:69], v[156:159], v[204:207], v[66:69]
	v_mfma_f32_16x16x32_bf16 v[126:129], v[160:163], v[176:179], v[126:129]
	v_mfma_f32_16x16x32_bf16 v[126:129], v[164:167], v[180:183], v[126:129]
	v_mfma_f32_16x16x32_bf16 v[122:125], v[168:171], v[176:179], v[122:125]
	v_mfma_f32_16x16x32_bf16 v[122:125], v[172:175], v[180:183], v[122:125]
	v_mfma_f32_16x16x32_bf16 v[106:109], v[160:163], v[184:187], v[106:109]
	v_mfma_f32_16x16x32_bf16 v[106:109], v[164:167], v[188:191], v[106:109]
	v_mfma_f32_16x16x32_bf16 v[98:101], v[168:171], v[184:187], v[98:101]
	v_mfma_f32_16x16x32_bf16 v[98:101], v[172:175], v[188:191], v[98:101]
	v_mfma_f32_16x16x32_bf16 v[90:93], v[160:163], v[192:195], v[90:93]
	v_mfma_f32_16x16x32_bf16 v[90:93], v[164:167], v[196:199], v[90:93]
	v_mfma_f32_16x16x32_bf16 v[82:85], v[168:171], v[192:195], v[82:85]
	v_mfma_f32_16x16x32_bf16 v[82:85], v[172:175], v[196:199], v[82:85]
	v_mfma_f32_16x16x32_bf16 v[74:77], v[160:163], v[200:203], v[74:77]
	v_mfma_f32_16x16x32_bf16 v[74:77], v[164:167], v[204:207], v[74:77]
	v_mfma_f32_16x16x32_bf16 v[70:73], v[168:171], v[200:203], v[70:73]
	v_mfma_f32_16x16x32_bf16 v[70:73], v[172:175], v[204:207], v[70:73]
	s_setprio 0
	s_barrier
	s_mov_b32 m0, s45
	s_mov_b32 s14, s18
	s_mov_b32 s15, s19
	ds_read_b128 v[176:179], v140 offset:16384
	ds_read_b128 v[180:183], v140 offset:17408
	ds_read_b128 v[184:187], v140 offset:18432
	ds_read_b128 v[188:191], v140 offset:19456
	ds_read_b128 v[192:195], v140 offset:20480
	ds_read_b128 v[196:199], v140 offset:21504
	ds_read_b128 v[200:203], v140 offset:22528
	ds_read_b128 v[204:207], v140 offset:23552
	buffer_load_dwordx4 v137, s[12:15], s79 offen lds
	s_add_i32 s80, s79, 0x80000
	s_mov_b32 m0, s46
	s_nop 0
	buffer_load_dwordx4 v137, s[12:15], s80 offen lds
	s_add_i32 s80, s79, 0x100000
	s_mov_b32 m0, s47
	s_nop 0
	buffer_load_dwordx4 v137, s[12:15], s80 offen lds
	s_add_i32 s80, s79, 0x180000
	s_mov_b32 m0, s48
	s_nop 0
	buffer_load_dwordx4 v137, s[12:15], s80 offen lds
	s_mov_b32 m0, s44
	s_add_i32 s80, s77, 0x80000
	buffer_load_dwordx4 v136, s[16:19], s77 offen lds
	s_mov_b32 m0, s49
	s_nop 0
	buffer_load_dwordx4 v136, s[16:19], s80 offen lds
	s_waitcnt vmcnt(8)
	s_waitcnt lgkmcnt(0)
	s_setprio 1
	v_mfma_f32_16x16x32_bf16 v[62:65], v[144:147], v[176:179], v[62:65]
	v_mfma_f32_16x16x32_bf16 v[62:65], v[148:151], v[180:183], v[62:65]
	v_mfma_f32_16x16x32_bf16 v[54:57], v[152:155], v[176:179], v[54:57]
	v_mfma_f32_16x16x32_bf16 v[54:57], v[156:159], v[180:183], v[54:57]
	s_barrier
	v_mfma_f32_16x16x32_bf16 v[46:49], v[144:147], v[184:187], v[46:49]
	v_mfma_f32_16x16x32_bf16 v[46:49], v[148:151], v[188:191], v[46:49]
	v_mfma_f32_16x16x32_bf16 v[38:41], v[152:155], v[184:187], v[38:41]
	v_mfma_f32_16x16x32_bf16 v[38:41], v[156:159], v[188:191], v[38:41]
	v_mfma_f32_16x16x32_bf16 v[30:33], v[144:147], v[192:195], v[30:33]
	v_mfma_f32_16x16x32_bf16 v[30:33], v[148:151], v[196:199], v[30:33]
	v_mfma_f32_16x16x32_bf16 v[22:25], v[152:155], v[192:195], v[22:25]
	v_mfma_f32_16x16x32_bf16 v[22:25], v[156:159], v[196:199], v[22:25]
	v_mfma_f32_16x16x32_bf16 v[14:17], v[144:147], v[200:203], v[14:17]
	v_mfma_f32_16x16x32_bf16 v[14:17], v[148:151], v[204:207], v[14:17]
	v_mfma_f32_16x16x32_bf16 v[6:9], v[152:155], v[200:203], v[6:9]
	v_mfma_f32_16x16x32_bf16 v[6:9], v[156:159], v[204:207], v[6:9]
	v_mfma_f32_16x16x32_bf16 v[58:61], v[160:163], v[176:179], v[58:61]
	v_mfma_f32_16x16x32_bf16 v[58:61], v[164:167], v[180:183], v[58:61]
	v_mfma_f32_16x16x32_bf16 v[50:53], v[168:171], v[176:179], v[50:53]
	v_mfma_f32_16x16x32_bf16 v[50:53], v[172:175], v[180:183], v[50:53]
	v_mfma_f32_16x16x32_bf16 v[42:45], v[160:163], v[184:187], v[42:45]
	v_mfma_f32_16x16x32_bf16 v[42:45], v[164:167], v[188:191], v[42:45]
	v_mfma_f32_16x16x32_bf16 v[34:37], v[168:171], v[184:187], v[34:37]
	v_mfma_f32_16x16x32_bf16 v[34:37], v[172:175], v[188:191], v[34:37]
	v_mfma_f32_16x16x32_bf16 v[26:29], v[160:163], v[192:195], v[26:29]
	v_mfma_f32_16x16x32_bf16 v[26:29], v[164:167], v[196:199], v[26:29]
	v_mfma_f32_16x16x32_bf16 v[18:21], v[168:171], v[192:195], v[18:21]
	v_mfma_f32_16x16x32_bf16 v[18:21], v[172:175], v[196:199], v[18:21]
	v_mfma_f32_16x16x32_bf16 v[10:13], v[160:163], v[200:203], v[10:13]
	v_mfma_f32_16x16x32_bf16 v[10:13], v[164:167], v[204:207], v[10:13]
	v_mfma_f32_16x16x32_bf16 v[2:5], v[168:171], v[200:203], v[2:5]
	v_mfma_f32_16x16x32_bf16 v[2:5], v[172:175], v[204:207], v[2:5]
	s_setprio 0
	s_barrier
	ds_read_b128 v[144:147], v141
	ds_read_b128 v[148:151], v141 offset:1024
	ds_read_b128 v[152:155], v141 offset:2048
	ds_read_b128 v[156:159], v141 offset:3072
	ds_read_b128 v[160:163], v142
	ds_read_b128 v[164:167], v142 offset:1024
	ds_read_b128 v[168:171], v142 offset:2048
	ds_read_b128 v[172:175], v142 offset:3072
	s_mov_b32 m0, s50
	s_add_i32 s80, s77, 0x100000
	ds_read_b128 v[176:179], v140 offset:32768
	ds_read_b128 v[180:183], v140 offset:33792
	ds_read_b128 v[184:187], v140 offset:34816
	ds_read_b128 v[188:191], v140 offset:35840
	ds_read_b128 v[192:195], v140 offset:36864
	ds_read_b128 v[196:199], v140 offset:37888
	ds_read_b128 v[200:203], v140 offset:38912
	ds_read_b128 v[204:207], v140 offset:39936
	buffer_load_dwordx4 v136, s[16:19], s80 offen lds
	s_add_i32 s80, s77, 0x180000
	s_mov_b32 m0, s51
	s_nop 0
	buffer_load_dwordx4 v136, s[16:19], s80 offen lds
	s_waitcnt vmcnt(8)
	s_waitcnt lgkmcnt(0)
	s_setprio 1
	v_mfma_f32_16x16x32_bf16 v[118:121], v[144:147], v[176:179], v[118:121]
	v_mfma_f32_16x16x32_bf16 v[118:121], v[148:151], v[180:183], v[118:121]
	v_mfma_f32_16x16x32_bf16 v[114:117], v[152:155], v[176:179], v[114:117]
	v_mfma_f32_16x16x32_bf16 v[114:117], v[156:159], v[180:183], v[114:117]
	s_barrier
	v_mfma_f32_16x16x32_bf16 v[110:113], v[144:147], v[184:187], v[110:113]
	v_mfma_f32_16x16x32_bf16 v[110:113], v[148:151], v[188:191], v[110:113]
	v_mfma_f32_16x16x32_bf16 v[102:105], v[152:155], v[184:187], v[102:105]
	v_mfma_f32_16x16x32_bf16 v[102:105], v[156:159], v[188:191], v[102:105]
	v_mfma_f32_16x16x32_bf16 v[94:97], v[144:147], v[192:195], v[94:97]
	v_mfma_f32_16x16x32_bf16 v[94:97], v[148:151], v[196:199], v[94:97]
	v_mfma_f32_16x16x32_bf16 v[86:89], v[152:155], v[192:195], v[86:89]
	v_mfma_f32_16x16x32_bf16 v[86:89], v[156:159], v[196:199], v[86:89]
	v_mfma_f32_16x16x32_bf16 v[78:81], v[144:147], v[200:203], v[78:81]
	v_mfma_f32_16x16x32_bf16 v[78:81], v[148:151], v[204:207], v[78:81]
	v_mfma_f32_16x16x32_bf16 v[66:69], v[152:155], v[200:203], v[66:69]
	v_mfma_f32_16x16x32_bf16 v[66:69], v[156:159], v[204:207], v[66:69]
	v_mfma_f32_16x16x32_bf16 v[126:129], v[160:163], v[176:179], v[126:129]
	v_mfma_f32_16x16x32_bf16 v[126:129], v[164:167], v[180:183], v[126:129]
	v_mfma_f32_16x16x32_bf16 v[122:125], v[168:171], v[176:179], v[122:125]
	v_mfma_f32_16x16x32_bf16 v[122:125], v[172:175], v[180:183], v[122:125]
	v_mfma_f32_16x16x32_bf16 v[106:109], v[160:163], v[184:187], v[106:109]
	v_mfma_f32_16x16x32_bf16 v[106:109], v[164:167], v[188:191], v[106:109]
	v_mfma_f32_16x16x32_bf16 v[98:101], v[168:171], v[184:187], v[98:101]
	v_mfma_f32_16x16x32_bf16 v[98:101], v[172:175], v[188:191], v[98:101]
	v_mfma_f32_16x16x32_bf16 v[90:93], v[160:163], v[192:195], v[90:93]
	v_mfma_f32_16x16x32_bf16 v[90:93], v[164:167], v[196:199], v[90:93]
	v_mfma_f32_16x16x32_bf16 v[82:85], v[168:171], v[192:195], v[82:85]
	v_mfma_f32_16x16x32_bf16 v[82:85], v[172:175], v[196:199], v[82:85]
	v_mfma_f32_16x16x32_bf16 v[74:77], v[160:163], v[200:203], v[74:77]
	v_mfma_f32_16x16x32_bf16 v[74:77], v[164:167], v[204:207], v[74:77]
	v_mfma_f32_16x16x32_bf16 v[70:73], v[168:171], v[200:203], v[70:73]
	v_mfma_f32_16x16x32_bf16 v[70:73], v[172:175], v[204:207], v[70:73]
	s_setprio 0
	s_barrier
	s_mov_b32 m0, s53
	s_or_b32 s80, s79, 0x80
	ds_read_b128 v[176:179], v140 offset:49152
	ds_read_b128 v[180:183], v140 offset:50176
	ds_read_b128 v[184:187], v140 offset:51200
	ds_read_b128 v[188:191], v140 offset:52224
	ds_read_b128 v[192:195], v140 offset:53248
	ds_read_b128 v[196:199], v140 offset:54272
	ds_read_b128 v[200:203], v140 offset:55296
	ds_read_b128 v[204:207], v140 offset:56320
	buffer_load_dwordx4 v137, s[12:15], s80 offen lds
	s_add_i32 s80, s79, 0x80080
	s_mov_b32 m0, s54
	s_add_i32 s77, s77, 0x80080
	buffer_load_dwordx4 v137, s[12:15], s80 offen lds
	s_add_i32 s80, s79, 0x100080
	s_mov_b32 m0, s57
	s_add_i32 s79, s79, 0x180080
	buffer_load_dwordx4 v137, s[12:15], s80 offen lds
	s_mov_b32 m0, s58
	s_nop 0
	buffer_load_dwordx4 v137, s[12:15], s79 offen lds
	s_mov_b32 m0, s55
	s_nop 0
	buffer_load_dwordx4 v136, s[16:19], s78 offen lds
	s_mov_b32 m0, s56
	s_nop 0
	buffer_load_dwordx4 v136, s[16:19], s77 offen lds
	s_waitcnt vmcnt(8)
	s_waitcnt lgkmcnt(0)
	s_setprio 1
	v_mfma_f32_16x16x32_bf16 v[62:65], v[144:147], v[176:179], v[62:65]
	v_mfma_f32_16x16x32_bf16 v[62:65], v[148:151], v[180:183], v[62:65]
	v_mfma_f32_16x16x32_bf16 v[54:57], v[152:155], v[176:179], v[54:57]
	v_mfma_f32_16x16x32_bf16 v[54:57], v[156:159], v[180:183], v[54:57]
	s_barrier
	v_mfma_f32_16x16x32_bf16 v[46:49], v[144:147], v[184:187], v[46:49]
	v_mfma_f32_16x16x32_bf16 v[46:49], v[148:151], v[188:191], v[46:49]
	v_mfma_f32_16x16x32_bf16 v[38:41], v[152:155], v[184:187], v[38:41]
	v_mfma_f32_16x16x32_bf16 v[38:41], v[156:159], v[188:191], v[38:41]
	v_mfma_f32_16x16x32_bf16 v[30:33], v[144:147], v[192:195], v[30:33]
	v_mfma_f32_16x16x32_bf16 v[30:33], v[148:151], v[196:199], v[30:33]
	v_mfma_f32_16x16x32_bf16 v[22:25], v[152:155], v[192:195], v[22:25]
	v_mfma_f32_16x16x32_bf16 v[22:25], v[156:159], v[196:199], v[22:25]
	v_mfma_f32_16x16x32_bf16 v[14:17], v[144:147], v[200:203], v[14:17]
	v_mfma_f32_16x16x32_bf16 v[14:17], v[148:151], v[204:207], v[14:17]
	v_mfma_f32_16x16x32_bf16 v[6:9], v[152:155], v[200:203], v[6:9]
	v_mfma_f32_16x16x32_bf16 v[6:9], v[156:159], v[204:207], v[6:9]
	v_mfma_f32_16x16x32_bf16 v[58:61], v[160:163], v[176:179], v[58:61]
	v_mfma_f32_16x16x32_bf16 v[58:61], v[164:167], v[180:183], v[58:61]
	v_mfma_f32_16x16x32_bf16 v[50:53], v[168:171], v[176:179], v[50:53]
	v_mfma_f32_16x16x32_bf16 v[50:53], v[172:175], v[180:183], v[50:53]
	v_mfma_f32_16x16x32_bf16 v[42:45], v[160:163], v[184:187], v[42:45]
	v_mfma_f32_16x16x32_bf16 v[42:45], v[164:167], v[188:191], v[42:45]
	v_mfma_f32_16x16x32_bf16 v[34:37], v[168:171], v[184:187], v[34:37]
	v_mfma_f32_16x16x32_bf16 v[34:37], v[172:175], v[188:191], v[34:37]
	v_mfma_f32_16x16x32_bf16 v[26:29], v[160:163], v[192:195], v[26:29]
	v_mfma_f32_16x16x32_bf16 v[26:29], v[164:167], v[196:199], v[26:29]
	v_mfma_f32_16x16x32_bf16 v[18:21], v[168:171], v[192:195], v[18:21]
	v_mfma_f32_16x16x32_bf16 v[18:21], v[172:175], v[196:199], v[18:21]
	v_mfma_f32_16x16x32_bf16 v[10:13], v[160:163], v[200:203], v[10:13]
	v_mfma_f32_16x16x32_bf16 v[10:13], v[164:167], v[204:207], v[10:13]
	v_mfma_f32_16x16x32_bf16 v[2:5], v[168:171], v[200:203], v[2:5]
	v_mfma_f32_16x16x32_bf16 v[2:5], v[172:175], v[204:207], v[2:5]
	s_setprio 0
	s_barrier
	s_add_i32 s76, s76, 2
	s_addk_i32 s74, 0x100
	s_addk_i32 s75, 0x100
	s_cmp_ge_i32 s76, s27
	s_cbranch_scc0 .LBB0_1382
	s_and_b64 vcc, exec, s[42:43]
	s_cbranch_vccz .LBB0_1385

.LBB0_1402:
	ds_read_b128 v[146:149], v138
	ds_read_b128 v[150:153], v138 offset:1024
	ds_read_b128 v[154:157], v138 offset:2048
	ds_read_b128 v[158:161], v138 offset:3072
	ds_read_b128 v[162:165], v139
	ds_read_b128 v[166:169], v139 offset:1024
	ds_read_b128 v[170:173], v139 offset:2048
	ds_read_b128 v[174:177], v139 offset:3072
	s_add_i32 s22, s75, 0xffe80080
	s_cmp_eq_u32 s62, s77
	s_cselect_b32 s78, s73, s22
	s_cselect_b32 s80, s74, s76
	s_or_b32 s79, s78, 0x80
	s_add_i32 s22, s75, 0xfff80000
	s_mov_b32 m0, s63
	ds_read_b128 v[178:181], v140
	ds_read_b128 v[182:185], v140 offset:1024
	ds_read_b128 v[186:189], v140 offset:2048
	ds_read_b128 v[190:193], v140 offset:3072
	ds_read_b128 v[194:197], v140 offset:4096
	ds_read_b128 v[198:201], v140 offset:5120
	ds_read_b128 v[202:205], v140 offset:6144
	ds_read_b128 v[206:209], v140 offset:7168
	buffer_load_dwordx4 v136, s[16:19], s22 offen lds
	s_mov_b32 m0, s64
	s_nop 0
	buffer_load_dwordx4 v136, s[16:19], s75 offen lds
	s_waitcnt vmcnt(8)
	s_waitcnt lgkmcnt(0)
	s_setprio 1
	v_mfma_f32_16x16x32_bf16 v[118:121], v[146:149], v[178:181], v[118:121]
	v_mfma_f32_16x16x32_bf16 v[118:121], v[150:153], v[182:185], v[118:121]
	v_mfma_f32_16x16x32_bf16 v[114:117], v[154:157], v[178:181], v[114:117]
	v_mfma_f32_16x16x32_bf16 v[114:117], v[158:161], v[182:185], v[114:117]
	s_barrier
	v_mfma_f32_16x16x32_bf16 v[110:113], v[146:149], v[186:189], v[110:113]
	v_mfma_f32_16x16x32_bf16 v[110:113], v[150:153], v[190:193], v[110:113]
	v_mfma_f32_16x16x32_bf16 v[102:105], v[154:157], v[186:189], v[102:105]
	v_mfma_f32_16x16x32_bf16 v[102:105], v[158:161], v[190:193], v[102:105]
	v_mfma_f32_16x16x32_bf16 v[94:97], v[146:149], v[194:197], v[94:97]
	v_mfma_f32_16x16x32_bf16 v[94:97], v[150:153], v[198:201], v[94:97]
	v_mfma_f32_16x16x32_bf16 v[86:89], v[154:157], v[194:197], v[86:89]
	v_mfma_f32_16x16x32_bf16 v[86:89], v[158:161], v[198:201], v[86:89]
	v_mfma_f32_16x16x32_bf16 v[78:81], v[146:149], v[202:205], v[78:81]
	v_mfma_f32_16x16x32_bf16 v[78:81], v[150:153], v[206:209], v[78:81]
	v_mfma_f32_16x16x32_bf16 v[66:69], v[154:157], v[202:205], v[66:69]
	v_mfma_f32_16x16x32_bf16 v[66:69], v[158:161], v[206:209], v[66:69]
	v_mfma_f32_16x16x32_bf16 v[126:129], v[162:165], v[178:181], v[126:129]
	v_mfma_f32_16x16x32_bf16 v[126:129], v[166:169], v[182:185], v[126:129]
	v_mfma_f32_16x16x32_bf16 v[122:125], v[170:173], v[178:181], v[122:125]
	v_mfma_f32_16x16x32_bf16 v[122:125], v[174:177], v[182:185], v[122:125]
	v_mfma_f32_16x16x32_bf16 v[106:109], v[162:165], v[186:189], v[106:109]
	v_mfma_f32_16x16x32_bf16 v[106:109], v[166:169], v[190:193], v[106:109]
	v_mfma_f32_16x16x32_bf16 v[98:101], v[170:173], v[186:189], v[98:101]
	v_mfma_f32_16x16x32_bf16 v[98:101], v[174:177], v[190:193], v[98:101]
	v_mfma_f32_16x16x32_bf16 v[90:93], v[162:165], v[194:197], v[90:93]
	v_mfma_f32_16x16x32_bf16 v[90:93], v[166:169], v[198:201], v[90:93]
	v_mfma_f32_16x16x32_bf16 v[82:85], v[170:173], v[194:197], v[82:85]
	v_mfma_f32_16x16x32_bf16 v[82:85], v[174:177], v[198:201], v[82:85]
	v_mfma_f32_16x16x32_bf16 v[74:77], v[162:165], v[202:205], v[74:77]
	v_mfma_f32_16x16x32_bf16 v[74:77], v[166:169], v[206:209], v[74:77]
	v_mfma_f32_16x16x32_bf16 v[70:73], v[170:173], v[202:205], v[70:73]
	v_mfma_f32_16x16x32_bf16 v[70:73], v[174:177], v[206:209], v[70:73]
	s_setprio 0
	s_barrier
	s_mov_b32 m0, s31
	s_mov_b32 s22, s18
	s_mov_b32 s23, s19
	ds_read_b128 v[178:181], v140 offset:16384
	ds_read_b128 v[182:185], v140 offset:17408
	ds_read_b128 v[186:189], v140 offset:18432
	ds_read_b128 v[190:193], v140 offset:19456
	ds_read_b128 v[194:197], v140 offset:20480
	ds_read_b128 v[198:201], v140 offset:21504
	ds_read_b128 v[202:205], v140 offset:22528
	ds_read_b128 v[206:209], v140 offset:23552
	buffer_load_dwordx4 v137, s[20:23], s80 offen lds
	s_add_i32 s81, s80, 0x80000
	s_mov_b32 m0, s48
	s_nop 0
	buffer_load_dwordx4 v137, s[20:23], s81 offen lds
	s_add_i32 s81, s80, 0x100000
	s_mov_b32 m0, s49
	s_nop 0
	buffer_load_dwordx4 v137, s[20:23], s81 offen lds
	s_add_i32 s81, s80, 0x180000
	s_mov_b32 m0, s50
	s_nop 0
	buffer_load_dwordx4 v137, s[20:23], s81 offen lds
	s_mov_b32 m0, s30
	s_add_i32 s81, s78, 0x80000
	buffer_load_dwordx4 v136, s[16:19], s78 offen lds
	s_mov_b32 m0, s51
	s_nop 0
	buffer_load_dwordx4 v136, s[16:19], s81 offen lds
	s_waitcnt vmcnt(8)
	s_waitcnt lgkmcnt(0)
	s_setprio 1
	v_mfma_f32_16x16x32_bf16 v[62:65], v[146:149], v[178:181], v[62:65]
	v_mfma_f32_16x16x32_bf16 v[62:65], v[150:153], v[182:185], v[62:65]
	v_mfma_f32_16x16x32_bf16 v[54:57], v[154:157], v[178:181], v[54:57]
	v_mfma_f32_16x16x32_bf16 v[54:57], v[158:161], v[182:185], v[54:57]
	s_barrier
	v_mfma_f32_16x16x32_bf16 v[46:49], v[146:149], v[186:189], v[46:49]
	v_mfma_f32_16x16x32_bf16 v[46:49], v[150:153], v[190:193], v[46:49]
	v_mfma_f32_16x16x32_bf16 v[38:41], v[154:157], v[186:189], v[38:41]
	v_mfma_f32_16x16x32_bf16 v[38:41], v[158:161], v[190:193], v[38:41]
	v_mfma_f32_16x16x32_bf16 v[30:33], v[146:149], v[194:197], v[30:33]
	v_mfma_f32_16x16x32_bf16 v[30:33], v[150:153], v[198:201], v[30:33]
	v_mfma_f32_16x16x32_bf16 v[22:25], v[154:157], v[194:197], v[22:25]
	v_mfma_f32_16x16x32_bf16 v[22:25], v[158:161], v[198:201], v[22:25]
	v_mfma_f32_16x16x32_bf16 v[14:17], v[146:149], v[202:205], v[14:17]
	v_mfma_f32_16x16x32_bf16 v[14:17], v[150:153], v[206:209], v[14:17]
	v_mfma_f32_16x16x32_bf16 v[6:9], v[154:157], v[202:205], v[6:9]
	v_mfma_f32_16x16x32_bf16 v[6:9], v[158:161], v[206:209], v[6:9]
	v_mfma_f32_16x16x32_bf16 v[58:61], v[162:165], v[178:181], v[58:61]
	v_mfma_f32_16x16x32_bf16 v[58:61], v[166:169], v[182:185], v[58:61]
	v_mfma_f32_16x16x32_bf16 v[50:53], v[170:173], v[178:181], v[50:53]
	v_mfma_f32_16x16x32_bf16 v[50:53], v[174:177], v[182:185], v[50:53]
	v_mfma_f32_16x16x32_bf16 v[42:45], v[162:165], v[186:189], v[42:45]
	v_mfma_f32_16x16x32_bf16 v[42:45], v[166:169], v[190:193], v[42:45]
	v_mfma_f32_16x16x32_bf16 v[34:37], v[170:173], v[186:189], v[34:37]
	v_mfma_f32_16x16x32_bf16 v[34:37], v[174:177], v[190:193], v[34:37]
	v_mfma_f32_16x16x32_bf16 v[26:29], v[162:165], v[194:197], v[26:29]
	v_mfma_f32_16x16x32_bf16 v[26:29], v[166:169], v[198:201], v[26:29]
	v_mfma_f32_16x16x32_bf16 v[18:21], v[170:173], v[194:197], v[18:21]
	v_mfma_f32_16x16x32_bf16 v[18:21], v[174:177], v[198:201], v[18:21]
	v_mfma_f32_16x16x32_bf16 v[10:13], v[162:165], v[202:205], v[10:13]
	v_mfma_f32_16x16x32_bf16 v[10:13], v[166:169], v[206:209], v[10:13]
	v_mfma_f32_16x16x32_bf16 v[2:5], v[170:173], v[202:205], v[2:5]
	v_mfma_f32_16x16x32_bf16 v[2:5], v[174:177], v[206:209], v[2:5]
	s_setprio 0
	s_barrier
	ds_read_b128 v[146:149], v141
	ds_read_b128 v[150:153], v141 offset:1024
	ds_read_b128 v[154:157], v141 offset:2048
	ds_read_b128 v[158:161], v141 offset:3072
	ds_read_b128 v[162:165], v142
	ds_read_b128 v[166:169], v142 offset:1024
	ds_read_b128 v[170:173], v142 offset:2048
	ds_read_b128 v[174:177], v142 offset:3072
	s_mov_b32 m0, s52
	s_add_i32 s81, s78, 0x100000
	ds_read_b128 v[178:181], v140 offset:32768
	ds_read_b128 v[182:185], v140 offset:33792
	ds_read_b128 v[186:189], v140 offset:34816
	ds_read_b128 v[190:193], v140 offset:35840
	ds_read_b128 v[194:197], v140 offset:36864
	ds_read_b128 v[198:201], v140 offset:37888
	ds_read_b128 v[202:205], v140 offset:38912
	ds_read_b128 v[206:209], v140 offset:39936
	buffer_load_dwordx4 v136, s[16:19], s81 offen lds
	s_add_i32 s81, s78, 0x180000
	s_mov_b32 m0, s53
	s_nop 0
	buffer_load_dwordx4 v136, s[16:19], s81 offen lds
	s_waitcnt vmcnt(8)
	s_waitcnt lgkmcnt(0)
	s_setprio 1
	v_mfma_f32_16x16x32_bf16 v[118:121], v[146:149], v[178:181], v[118:121]
	v_mfma_f32_16x16x32_bf16 v[118:121], v[150:153], v[182:185], v[118:121]
	v_mfma_f32_16x16x32_bf16 v[114:117], v[154:157], v[178:181], v[114:117]
	v_mfma_f32_16x16x32_bf16 v[114:117], v[158:161], v[182:185], v[114:117]
	s_barrier
	v_mfma_f32_16x16x32_bf16 v[110:113], v[146:149], v[186:189], v[110:113]
	v_mfma_f32_16x16x32_bf16 v[110:113], v[150:153], v[190:193], v[110:113]
	v_mfma_f32_16x16x32_bf16 v[102:105], v[154:157], v[186:189], v[102:105]
	v_mfma_f32_16x16x32_bf16 v[102:105], v[158:161], v[190:193], v[102:105]
	v_mfma_f32_16x16x32_bf16 v[94:97], v[146:149], v[194:197], v[94:97]
	v_mfma_f32_16x16x32_bf16 v[94:97], v[150:153], v[198:201], v[94:97]
	v_mfma_f32_16x16x32_bf16 v[86:89], v[154:157], v[194:197], v[86:89]
	v_mfma_f32_16x16x32_bf16 v[86:89], v[158:161], v[198:201], v[86:89]
	v_mfma_f32_16x16x32_bf16 v[78:81], v[146:149], v[202:205], v[78:81]
	v_mfma_f32_16x16x32_bf16 v[78:81], v[150:153], v[206:209], v[78:81]
	v_mfma_f32_16x16x32_bf16 v[66:69], v[154:157], v[202:205], v[66:69]
	v_mfma_f32_16x16x32_bf16 v[66:69], v[158:161], v[206:209], v[66:69]
	v_mfma_f32_16x16x32_bf16 v[126:129], v[162:165], v[178:181], v[126:129]
	v_mfma_f32_16x16x32_bf16 v[126:129], v[166:169], v[182:185], v[126:129]
	v_mfma_f32_16x16x32_bf16 v[122:125], v[170:173], v[178:181], v[122:125]
	v_mfma_f32_16x16x32_bf16 v[122:125], v[174:177], v[182:185], v[122:125]
	v_mfma_f32_16x16x32_bf16 v[106:109], v[162:165], v[186:189], v[106:109]
	v_mfma_f32_16x16x32_bf16 v[106:109], v[166:169], v[190:193], v[106:109]
	v_mfma_f32_16x16x32_bf16 v[98:101], v[170:173], v[186:189], v[98:101]
	v_mfma_f32_16x16x32_bf16 v[98:101], v[174:177], v[190:193], v[98:101]
	v_mfma_f32_16x16x32_bf16 v[90:93], v[162:165], v[194:197], v[90:93]
	v_mfma_f32_16x16x32_bf16 v[90:93], v[166:169], v[198:201], v[90:93]
	v_mfma_f32_16x16x32_bf16 v[82:85], v[170:173], v[194:197], v[82:85]
	v_mfma_f32_16x16x32_bf16 v[82:85], v[174:177], v[198:201], v[82:85]
	v_mfma_f32_16x16x32_bf16 v[74:77], v[162:165], v[202:205], v[74:77]
	v_mfma_f32_16x16x32_bf16 v[74:77], v[166:169], v[206:209], v[74:77]
	v_mfma_f32_16x16x32_bf16 v[70:73], v[170:173], v[202:205], v[70:73]
	v_mfma_f32_16x16x32_bf16 v[70:73], v[174:177], v[206:209], v[70:73]
	s_setprio 0
	s_barrier
	s_mov_b32 m0, s54
	s_or_b32 s81, s80, 0x80
	ds_read_b128 v[178:181], v140 offset:49152
	ds_read_b128 v[182:185], v140 offset:50176
	ds_read_b128 v[186:189], v140 offset:51200
	ds_read_b128 v[190:193], v140 offset:52224
	ds_read_b128 v[194:197], v140 offset:53248
	ds_read_b128 v[198:201], v140 offset:54272
	ds_read_b128 v[202:205], v140 offset:55296
	ds_read_b128 v[206:209], v140 offset:56320
	buffer_load_dwordx4 v137, s[20:23], s81 offen lds
	s_add_i32 s81, s80, 0x80080
	s_mov_b32 m0, s55
	s_add_i32 s78, s78, 0x80080
	buffer_load_dwordx4 v137, s[20:23], s81 offen lds
	s_add_i32 s81, s80, 0x100080
	s_mov_b32 m0, s58
	s_add_i32 s80, s80, 0x180080
	buffer_load_dwordx4 v137, s[20:23], s81 offen lds
	s_mov_b32 m0, s59
	s_nop 0
	buffer_load_dwordx4 v137, s[20:23], s80 offen lds
	s_mov_b32 m0, s56
	s_nop 0
	buffer_load_dwordx4 v136, s[16:19], s79 offen lds
	s_mov_b32 m0, s57
	s_nop 0
	buffer_load_dwordx4 v136, s[16:19], s78 offen lds
	s_waitcnt vmcnt(8)
	s_waitcnt lgkmcnt(0)
	s_setprio 1
	v_mfma_f32_16x16x32_bf16 v[62:65], v[146:149], v[178:181], v[62:65]
	v_mfma_f32_16x16x32_bf16 v[62:65], v[150:153], v[182:185], v[62:65]
	v_mfma_f32_16x16x32_bf16 v[54:57], v[154:157], v[178:181], v[54:57]
	v_mfma_f32_16x16x32_bf16 v[54:57], v[158:161], v[182:185], v[54:57]
	s_barrier
	v_mfma_f32_16x16x32_bf16 v[46:49], v[146:149], v[186:189], v[46:49]
	v_mfma_f32_16x16x32_bf16 v[46:49], v[150:153], v[190:193], v[46:49]
	v_mfma_f32_16x16x32_bf16 v[38:41], v[154:157], v[186:189], v[38:41]
	v_mfma_f32_16x16x32_bf16 v[38:41], v[158:161], v[190:193], v[38:41]
	v_mfma_f32_16x16x32_bf16 v[30:33], v[146:149], v[194:197], v[30:33]
	v_mfma_f32_16x16x32_bf16 v[30:33], v[150:153], v[198:201], v[30:33]
	v_mfma_f32_16x16x32_bf16 v[22:25], v[154:157], v[194:197], v[22:25]
	v_mfma_f32_16x16x32_bf16 v[22:25], v[158:161], v[198:201], v[22:25]
	v_mfma_f32_16x16x32_bf16 v[14:17], v[146:149], v[202:205], v[14:17]
	v_mfma_f32_16x16x32_bf16 v[14:17], v[150:153], v[206:209], v[14:17]
	v_mfma_f32_16x16x32_bf16 v[6:9], v[154:157], v[202:205], v[6:9]
	v_mfma_f32_16x16x32_bf16 v[6:9], v[158:161], v[206:209], v[6:9]
	v_mfma_f32_16x16x32_bf16 v[58:61], v[162:165], v[178:181], v[58:61]
	v_mfma_f32_16x16x32_bf16 v[58:61], v[166:169], v[182:185], v[58:61]
	v_mfma_f32_16x16x32_bf16 v[50:53], v[170:173], v[178:181], v[50:53]
	v_mfma_f32_16x16x32_bf16 v[50:53], v[174:177], v[182:185], v[50:53]
	v_mfma_f32_16x16x32_bf16 v[42:45], v[162:165], v[186:189], v[42:45]
	v_mfma_f32_16x16x32_bf16 v[42:45], v[166:169], v[190:193], v[42:45]
	v_mfma_f32_16x16x32_bf16 v[34:37], v[170:173], v[186:189], v[34:37]
	v_mfma_f32_16x16x32_bf16 v[34:37], v[174:177], v[190:193], v[34:37]
	v_mfma_f32_16x16x32_bf16 v[26:29], v[162:165], v[194:197], v[26:29]
	v_mfma_f32_16x16x32_bf16 v[26:29], v[166:169], v[198:201], v[26:29]
	v_mfma_f32_16x16x32_bf16 v[18:21], v[170:173], v[194:197], v[18:21]
	v_mfma_f32_16x16x32_bf16 v[18:21], v[174:177], v[198:201], v[18:21]
	v_mfma_f32_16x16x32_bf16 v[10:13], v[162:165], v[202:205], v[10:13]
	v_mfma_f32_16x16x32_bf16 v[10:13], v[166:169], v[206:209], v[10:13]
	v_mfma_f32_16x16x32_bf16 v[2:5], v[170:173], v[202:205], v[2:5]
	v_mfma_f32_16x16x32_bf16 v[2:5], v[174:177], v[206:209], v[2:5]
	s_setprio 0
	s_barrier
	s_add_i32 s77, s77, 2
	s_addk_i32 s75, 0x100
	s_addk_i32 s76, 0x100
	s_cmp_ge_i32 s77, s13
	s_cbranch_scc0 .LBB0_1402
	s_and_b64 vcc, exec, s[46:47]
	s_cbranch_vccz .LBB0_1405

.LBB0_1519:
	ds_read_b128 v[134:137], v208
	ds_read_b128 v[138:141], v208 offset:1024
	ds_read_b128 v[142:145], v208 offset:2048
	ds_read_b128 v[146:149], v208 offset:3072
	ds_read_b128 v[150:153], v209
	ds_read_b128 v[154:157], v209 offset:1024
	ds_read_b128 v[158:161], v209 offset:2048
	ds_read_b128 v[162:165], v209 offset:3072
	s_add_i32 s18, s80, 0xffbf8080
	s_cmp_eq_u32 s65, s82
	s_cselect_b32 s83, s6, s18
	s_cselect_b32 s85, s7, s81
	s_or_b32 s84, s83, 0x80
	s_add_i32 s18, s80, 0xffea8000
	s_mov_b32 m0, s66
	ds_read_b128 v[166:169], v210
	ds_read_b128 v[170:173], v210 offset:1024
	ds_read_b128 v[174:177], v210 offset:2048
	ds_read_b128 v[178:181], v210 offset:3072
	ds_read_b128 v[182:185], v210 offset:4096
	ds_read_b128 v[186:189], v210 offset:5120
	ds_read_b128 v[190:193], v210 offset:6144
	ds_read_b128 v[194:197], v210 offset:7168
	buffer_load_dwordx4 v206, s[12:15], s18 offen lds
	s_mov_b32 m0, s69
	s_nop 0
	buffer_load_dwordx4 v206, s[12:15], s80 offen lds
	s_waitcnt vmcnt(8)
	s_waitcnt lgkmcnt(0)
	s_setprio 1
	v_mfma_f32_16x16x32_bf16 v[126:129], v[134:137], v[166:169], v[126:129]
	v_mfma_f32_16x16x32_bf16 v[126:129], v[138:141], v[170:173], v[126:129]
	v_mfma_f32_16x16x32_bf16 v[122:125], v[142:145], v[166:169], v[122:125]
	v_mfma_f32_16x16x32_bf16 v[122:125], v[146:149], v[170:173], v[122:125]
	s_barrier
	v_mfma_f32_16x16x32_bf16 v[118:121], v[134:137], v[174:177], v[118:121]
	v_mfma_f32_16x16x32_bf16 v[118:121], v[138:141], v[178:181], v[118:121]
	v_mfma_f32_16x16x32_bf16 v[114:117], v[142:145], v[174:177], v[114:117]
	v_mfma_f32_16x16x32_bf16 v[114:117], v[146:149], v[178:181], v[114:117]
	v_mfma_f32_16x16x32_bf16 v[106:109], v[134:137], v[182:185], v[106:109]
	v_mfma_f32_16x16x32_bf16 v[106:109], v[138:141], v[186:189], v[106:109]
	v_mfma_f32_16x16x32_bf16 v[98:101], v[142:145], v[182:185], v[98:101]
	v_mfma_f32_16x16x32_bf16 v[98:101], v[146:149], v[186:189], v[98:101]
	v_mfma_f32_16x16x32_bf16 v[90:93], v[134:137], v[190:193], v[90:93]
	v_mfma_f32_16x16x32_bf16 v[90:93], v[138:141], v[194:197], v[90:93]
	v_mfma_f32_16x16x32_bf16 v[82:85], v[142:145], v[190:193], v[82:85]
	v_mfma_f32_16x16x32_bf16 v[82:85], v[146:149], v[194:197], v[82:85]
	v_mfma_f32_16x16x32_bf16 v[110:113], v[150:153], v[166:169], v[110:113]
	v_mfma_f32_16x16x32_bf16 v[110:113], v[154:157], v[170:173], v[110:113]
	v_mfma_f32_16x16x32_bf16 v[102:105], v[158:161], v[166:169], v[102:105]
	v_mfma_f32_16x16x32_bf16 v[102:105], v[162:165], v[170:173], v[102:105]
	v_mfma_f32_16x16x32_bf16 v[94:97], v[150:153], v[174:177], v[94:97]
	v_mfma_f32_16x16x32_bf16 v[94:97], v[154:157], v[178:181], v[94:97]
	v_mfma_f32_16x16x32_bf16 v[86:89], v[158:161], v[174:177], v[86:89]
	v_mfma_f32_16x16x32_bf16 v[86:89], v[162:165], v[178:181], v[86:89]
	v_mfma_f32_16x16x32_bf16 v[78:81], v[150:153], v[182:185], v[78:81]
	v_mfma_f32_16x16x32_bf16 v[78:81], v[154:157], v[186:189], v[78:81]
	v_mfma_f32_16x16x32_bf16 v[74:77], v[158:161], v[182:185], v[74:77]
	v_mfma_f32_16x16x32_bf16 v[74:77], v[162:165], v[186:189], v[74:77]
	v_mfma_f32_16x16x32_bf16 v[70:73], v[150:153], v[190:193], v[70:73]
	v_mfma_f32_16x16x32_bf16 v[70:73], v[154:157], v[194:197], v[70:73]
	v_mfma_f32_16x16x32_bf16 v[66:69], v[158:161], v[190:193], v[66:69]
	v_mfma_f32_16x16x32_bf16 v[66:69], v[162:165], v[194:197], v[66:69]
	s_setprio 0
	s_barrier
	s_mov_b32 m0, s27
	s_mov_b32 s18, s14
	s_mov_b32 s19, s15
	ds_read_b128 v[166:169], v210 offset:16384
	ds_read_b128 v[170:173], v210 offset:17408
	ds_read_b128 v[174:177], v210 offset:18432
	ds_read_b128 v[178:181], v210 offset:19456
	ds_read_b128 v[182:185], v210 offset:20480
	ds_read_b128 v[186:189], v210 offset:21504
	ds_read_b128 v[190:193], v210 offset:22528
	ds_read_b128 v[194:197], v210 offset:23552
	buffer_load_dwordx4 v207, s[16:19], s85 offen lds
	s_add_i32 s86, s85, 0x158000
	s_mov_b32 m0, s30
	s_nop 0
	buffer_load_dwordx4 v207, s[16:19], s86 offen lds
	s_add_i32 s86, s85, 0x2b0000
	s_mov_b32 m0, s31
	s_nop 0
	buffer_load_dwordx4 v207, s[16:19], s86 offen lds
	s_add_i32 s86, s85, 0x408000
	s_mov_b32 m0, s50
	s_nop 0
	buffer_load_dwordx4 v207, s[16:19], s86 offen lds
	s_mov_b32 m0, s25
	s_add_i32 s86, s83, 0x158000
	buffer_load_dwordx4 v206, s[12:15], s83 offen lds
	s_mov_b32 m0, s51
	s_nop 0
	buffer_load_dwordx4 v206, s[12:15], s86 offen lds
	s_waitcnt vmcnt(8)
	s_waitcnt lgkmcnt(0)
	s_setprio 1
	v_mfma_f32_16x16x32_bf16 v[62:65], v[134:137], v[166:169], v[62:65]
	v_mfma_f32_16x16x32_bf16 v[62:65], v[138:141], v[170:173], v[62:65]
	v_mfma_f32_16x16x32_bf16 v[58:61], v[142:145], v[166:169], v[58:61]
	v_mfma_f32_16x16x32_bf16 v[58:61], v[146:149], v[170:173], v[58:61]
	s_barrier
	v_mfma_f32_16x16x32_bf16 v[54:57], v[134:137], v[174:177], v[54:57]
	v_mfma_f32_16x16x32_bf16 v[54:57], v[138:141], v[178:181], v[54:57]
	v_mfma_f32_16x16x32_bf16 v[50:53], v[142:145], v[174:177], v[50:53]
	v_mfma_f32_16x16x32_bf16 v[50:53], v[146:149], v[178:181], v[50:53]
	v_mfma_f32_16x16x32_bf16 v[42:45], v[134:137], v[182:185], v[42:45]
	v_mfma_f32_16x16x32_bf16 v[42:45], v[138:141], v[186:189], v[42:45]
	v_mfma_f32_16x16x32_bf16 v[34:37], v[142:145], v[182:185], v[34:37]
	v_mfma_f32_16x16x32_bf16 v[34:37], v[146:149], v[186:189], v[34:37]
	v_mfma_f32_16x16x32_bf16 v[26:29], v[134:137], v[190:193], v[26:29]
	v_mfma_f32_16x16x32_bf16 v[26:29], v[138:141], v[194:197], v[26:29]
	v_mfma_f32_16x16x32_bf16 v[18:21], v[142:145], v[190:193], v[18:21]
	v_mfma_f32_16x16x32_bf16 v[18:21], v[146:149], v[194:197], v[18:21]
	v_mfma_f32_16x16x32_bf16 v[46:49], v[150:153], v[166:169], v[46:49]
	v_mfma_f32_16x16x32_bf16 v[46:49], v[154:157], v[170:173], v[46:49]
	v_mfma_f32_16x16x32_bf16 v[38:41], v[158:161], v[166:169], v[38:41]
	v_mfma_f32_16x16x32_bf16 v[38:41], v[162:165], v[170:173], v[38:41]
	v_mfma_f32_16x16x32_bf16 v[30:33], v[150:153], v[174:177], v[30:33]
	v_mfma_f32_16x16x32_bf16 v[30:33], v[154:157], v[178:181], v[30:33]
	v_mfma_f32_16x16x32_bf16 v[22:25], v[158:161], v[174:177], v[22:25]
	v_mfma_f32_16x16x32_bf16 v[22:25], v[162:165], v[178:181], v[22:25]
	v_mfma_f32_16x16x32_bf16 v[14:17], v[150:153], v[182:185], v[14:17]
	v_mfma_f32_16x16x32_bf16 v[14:17], v[154:157], v[186:189], v[14:17]
	v_mfma_f32_16x16x32_bf16 v[10:13], v[158:161], v[182:185], v[10:13]
	v_mfma_f32_16x16x32_bf16 v[10:13], v[162:165], v[186:189], v[10:13]
	v_mfma_f32_16x16x32_bf16 v[6:9], v[150:153], v[190:193], v[6:9]
	v_mfma_f32_16x16x32_bf16 v[6:9], v[154:157], v[194:197], v[6:9]
	v_mfma_f32_16x16x32_bf16 v[2:5], v[158:161], v[190:193], v[2:5]
	v_mfma_f32_16x16x32_bf16 v[2:5], v[162:165], v[194:197], v[2:5]
	s_setprio 0
	s_barrier
	ds_read_b128 v[134:137], v211
	ds_read_b128 v[138:141], v211 offset:1024
	ds_read_b128 v[142:145], v211 offset:2048
	ds_read_b128 v[146:149], v211 offset:3072
	ds_read_b128 v[150:153], v212
	ds_read_b128 v[154:157], v212 offset:1024
	ds_read_b128 v[158:161], v212 offset:2048
	ds_read_b128 v[162:165], v212 offset:3072
	s_mov_b32 m0, s52
	s_add_i32 s86, s83, 0x2b0000
	ds_read_b128 v[166:169], v210 offset:32768
	ds_read_b128 v[170:173], v210 offset:33792
	ds_read_b128 v[174:177], v210 offset:34816
	ds_read_b128 v[178:181], v210 offset:35840
	ds_read_b128 v[182:185], v210 offset:36864
	ds_read_b128 v[186:189], v210 offset:37888
	ds_read_b128 v[190:193], v210 offset:38912
	ds_read_b128 v[194:197], v210 offset:39936
	buffer_load_dwordx4 v206, s[12:15], s86 offen lds
	s_add_i32 s86, s83, 0x408000
	s_mov_b32 m0, s53
	s_nop 0
	buffer_load_dwordx4 v206, s[12:15], s86 offen lds
	s_waitcnt vmcnt(8)
	s_waitcnt lgkmcnt(0)
	s_setprio 1
	v_mfma_f32_16x16x32_bf16 v[126:129], v[134:137], v[166:169], v[126:129]
	v_mfma_f32_16x16x32_bf16 v[126:129], v[138:141], v[170:173], v[126:129]
	v_mfma_f32_16x16x32_bf16 v[122:125], v[142:145], v[166:169], v[122:125]
	v_mfma_f32_16x16x32_bf16 v[122:125], v[146:149], v[170:173], v[122:125]
	s_barrier
	v_mfma_f32_16x16x32_bf16 v[118:121], v[134:137], v[174:177], v[118:121]
	v_mfma_f32_16x16x32_bf16 v[118:121], v[138:141], v[178:181], v[118:121]
	v_mfma_f32_16x16x32_bf16 v[114:117], v[142:145], v[174:177], v[114:117]
	v_mfma_f32_16x16x32_bf16 v[114:117], v[146:149], v[178:181], v[114:117]
	v_mfma_f32_16x16x32_bf16 v[106:109], v[134:137], v[182:185], v[106:109]
	v_mfma_f32_16x16x32_bf16 v[106:109], v[138:141], v[186:189], v[106:109]
	v_mfma_f32_16x16x32_bf16 v[98:101], v[142:145], v[182:185], v[98:101]
	v_mfma_f32_16x16x32_bf16 v[98:101], v[146:149], v[186:189], v[98:101]
	v_mfma_f32_16x16x32_bf16 v[90:93], v[134:137], v[190:193], v[90:93]
	v_mfma_f32_16x16x32_bf16 v[90:93], v[138:141], v[194:197], v[90:93]
	v_mfma_f32_16x16x32_bf16 v[82:85], v[142:145], v[190:193], v[82:85]
	v_mfma_f32_16x16x32_bf16 v[82:85], v[146:149], v[194:197], v[82:85]
	v_mfma_f32_16x16x32_bf16 v[110:113], v[150:153], v[166:169], v[110:113]
	v_mfma_f32_16x16x32_bf16 v[110:113], v[154:157], v[170:173], v[110:113]
	v_mfma_f32_16x16x32_bf16 v[102:105], v[158:161], v[166:169], v[102:105]
	v_mfma_f32_16x16x32_bf16 v[102:105], v[162:165], v[170:173], v[102:105]
	v_mfma_f32_16x16x32_bf16 v[94:97], v[150:153], v[174:177], v[94:97]
	v_mfma_f32_16x16x32_bf16 v[94:97], v[154:157], v[178:181], v[94:97]
	v_mfma_f32_16x16x32_bf16 v[86:89], v[158:161], v[174:177], v[86:89]
	v_mfma_f32_16x16x32_bf16 v[86:89], v[162:165], v[178:181], v[86:89]
	v_mfma_f32_16x16x32_bf16 v[78:81], v[150:153], v[182:185], v[78:81]
	v_mfma_f32_16x16x32_bf16 v[78:81], v[154:157], v[186:189], v[78:81]
	v_mfma_f32_16x16x32_bf16 v[74:77], v[158:161], v[182:185], v[74:77]
	v_mfma_f32_16x16x32_bf16 v[74:77], v[162:165], v[186:189], v[74:77]
	v_mfma_f32_16x16x32_bf16 v[70:73], v[150:153], v[190:193], v[70:73]
	v_mfma_f32_16x16x32_bf16 v[70:73], v[154:157], v[194:197], v[70:73]
	v_mfma_f32_16x16x32_bf16 v[66:69], v[158:161], v[190:193], v[66:69]
	v_mfma_f32_16x16x32_bf16 v[66:69], v[162:165], v[194:197], v[66:69]
	s_setprio 0
	s_barrier
	s_mov_b32 m0, s57
	s_or_b32 s86, s85, 0x80
	ds_read_b128 v[166:169], v210 offset:49152
	ds_read_b128 v[170:173], v210 offset:50176
	ds_read_b128 v[174:177], v210 offset:51200
	ds_read_b128 v[178:181], v210 offset:52224
	ds_read_b128 v[182:185], v210 offset:53248
	ds_read_b128 v[186:189], v210 offset:54272
	ds_read_b128 v[190:193], v210 offset:55296
	ds_read_b128 v[194:197], v210 offset:56320
	buffer_load_dwordx4 v207, s[16:19], s86 offen lds
	s_add_i32 s86, s85, 0x158080
	s_mov_b32 m0, s58
	s_add_i32 s83, s83, 0x158080
	buffer_load_dwordx4 v207, s[16:19], s86 offen lds
	s_add_i32 s86, s85, 0x2b0080
	s_mov_b32 m0, s61
	s_add_i32 s85, s85, 0x408080
	buffer_load_dwordx4 v207, s[16:19], s86 offen lds
	s_mov_b32 m0, s62
	s_nop 0
	buffer_load_dwordx4 v207, s[16:19], s85 offen lds
	s_mov_b32 m0, s59
	s_nop 0
	buffer_load_dwordx4 v206, s[12:15], s84 offen lds
	s_mov_b32 m0, s60
	s_nop 0
	buffer_load_dwordx4 v206, s[12:15], s83 offen lds
	s_waitcnt vmcnt(8)
	s_waitcnt lgkmcnt(0)
	s_setprio 1
	v_mfma_f32_16x16x32_bf16 v[62:65], v[134:137], v[166:169], v[62:65]
	v_mfma_f32_16x16x32_bf16 v[62:65], v[138:141], v[170:173], v[62:65]
	v_mfma_f32_16x16x32_bf16 v[58:61], v[142:145], v[166:169], v[58:61]
	v_mfma_f32_16x16x32_bf16 v[58:61], v[146:149], v[170:173], v[58:61]
	s_barrier
	v_mfma_f32_16x16x32_bf16 v[54:57], v[134:137], v[174:177], v[54:57]
	v_mfma_f32_16x16x32_bf16 v[54:57], v[138:141], v[178:181], v[54:57]
	v_mfma_f32_16x16x32_bf16 v[50:53], v[142:145], v[174:177], v[50:53]
	v_mfma_f32_16x16x32_bf16 v[50:53], v[146:149], v[178:181], v[50:53]
	v_mfma_f32_16x16x32_bf16 v[42:45], v[134:137], v[182:185], v[42:45]
	v_mfma_f32_16x16x32_bf16 v[42:45], v[138:141], v[186:189], v[42:45]
	v_mfma_f32_16x16x32_bf16 v[34:37], v[142:145], v[182:185], v[34:37]
	v_mfma_f32_16x16x32_bf16 v[34:37], v[146:149], v[186:189], v[34:37]
	v_mfma_f32_16x16x32_bf16 v[26:29], v[134:137], v[190:193], v[26:29]
	v_mfma_f32_16x16x32_bf16 v[26:29], v[138:141], v[194:197], v[26:29]
	v_mfma_f32_16x16x32_bf16 v[18:21], v[142:145], v[190:193], v[18:21]
	v_mfma_f32_16x16x32_bf16 v[18:21], v[146:149], v[194:197], v[18:21]
	v_mfma_f32_16x16x32_bf16 v[46:49], v[150:153], v[166:169], v[46:49]
	v_mfma_f32_16x16x32_bf16 v[46:49], v[154:157], v[170:173], v[46:49]
	v_mfma_f32_16x16x32_bf16 v[38:41], v[158:161], v[166:169], v[38:41]
	v_mfma_f32_16x16x32_bf16 v[38:41], v[162:165], v[170:173], v[38:41]
	v_mfma_f32_16x16x32_bf16 v[30:33], v[150:153], v[174:177], v[30:33]
	v_mfma_f32_16x16x32_bf16 v[30:33], v[154:157], v[178:181], v[30:33]
	v_mfma_f32_16x16x32_bf16 v[22:25], v[158:161], v[174:177], v[22:25]
	v_mfma_f32_16x16x32_bf16 v[22:25], v[162:165], v[178:181], v[22:25]
	v_mfma_f32_16x16x32_bf16 v[14:17], v[150:153], v[182:185], v[14:17]
	v_mfma_f32_16x16x32_bf16 v[14:17], v[154:157], v[186:189], v[14:17]
	v_mfma_f32_16x16x32_bf16 v[10:13], v[158:161], v[182:185], v[10:13]
	v_mfma_f32_16x16x32_bf16 v[10:13], v[162:165], v[186:189], v[10:13]
	v_mfma_f32_16x16x32_bf16 v[6:9], v[150:153], v[190:193], v[6:9]
	v_mfma_f32_16x16x32_bf16 v[6:9], v[154:157], v[194:197], v[6:9]
	v_mfma_f32_16x16x32_bf16 v[2:5], v[158:161], v[190:193], v[2:5]
	v_mfma_f32_16x16x32_bf16 v[2:5], v[162:165], v[194:197], v[2:5]
	s_setprio 0
	s_barrier
	s_add_i32 s82, s82, 2
	s_addk_i32 s80, 0x100
	s_addk_i32 s81, 0x100
	s_cmp_ge_i32 s82, s3
	s_cbranch_scc0 .LBB0_1519
	v_pk_mul_f32 v[182:183], v[128:129], 0.5 op_sel_hi:[1,0]
	v_pk_mul_f32 v[184:185], v[126:127], 0.5 op_sel_hi:[1,0]
	v_pk_mul_f32 v[186:187], v[124:125], 0.5 op_sel_hi:[1,0]
	v_pk_mul_f32 v[188:189], v[122:123], 0.5 op_sel_hi:[1,0]
	v_pk_mul_f32 v[196:197], v[112:113], 0.5 op_sel_hi:[1,0]
	v_pk_mul_f32 v[194:195], v[110:111], 0.5 op_sel_hi:[1,0]
	v_pk_mul_f32 v[192:193], v[104:105], 0.5 op_sel_hi:[1,0]
	v_pk_mul_f32 v[190:191], v[102:103], 0.5 op_sel_hi:[1,0]
	v_pk_mul_f32 v[180:181], v[120:121], 0.5 op_sel_hi:[1,0]
	v_pk_mul_f32 v[178:179], v[118:119], 0.5 op_sel_hi:[1,0]
	v_pk_mul_f32 v[176:177], v[116:117], 0.5 op_sel_hi:[1,0]
	v_pk_mul_f32 v[174:175], v[114:115], 0.5 op_sel_hi:[1,0]
	v_pk_mul_f32 v[170:171], v[96:97], 0.5 op_sel_hi:[1,0]
	v_pk_mul_f32 v[168:169], v[94:95], 0.5 op_sel_hi:[1,0]
	v_pk_mul_f32 v[166:167], v[88:89], 0.5 op_sel_hi:[1,0]
	v_pk_mul_f32 v[164:165], v[86:87], 0.5 op_sel_hi:[1,0]
	v_pk_mul_f32 v[162:163], v[108:109], 0.5 op_sel_hi:[1,0]
	v_pk_mul_f32 v[160:161], v[106:107], 0.5 op_sel_hi:[1,0]
	v_pk_mul_f32 v[158:159], v[100:101], 0.5 op_sel_hi:[1,0]
	v_pk_mul_f32 v[156:157], v[98:99], 0.5 op_sel_hi:[1,0]
	v_pk_mul_f32 v[154:155], v[80:81], 0.5 op_sel_hi:[1,0]
	v_pk_mul_f32 v[152:153], v[78:79], 0.5 op_sel_hi:[1,0]
	v_pk_mul_f32 v[150:151], v[76:77], 0.5 op_sel_hi:[1,0]
	v_pk_mul_f32 v[148:149], v[74:75], 0.5 op_sel_hi:[1,0]
	v_pk_mul_f32 v[144:145], v[92:93], 0.5 op_sel_hi:[1,0]
	v_pk_mul_f32 v[142:143], v[90:91], 0.5 op_sel_hi:[1,0]
	v_pk_mul_f32 v[140:141], v[84:85], 0.5 op_sel_hi:[1,0]
	v_pk_mul_f32 v[138:139], v[82:83], 0.5 op_sel_hi:[1,0]
	v_pk_mul_f32 v[136:137], v[72:73], 0.5 op_sel_hi:[1,0]
	v_pk_mul_f32 v[134:135], v[70:71], 0.5 op_sel_hi:[1,0]
	v_pk_mul_f32 v[128:129], v[68:69], 0.5 op_sel_hi:[1,0]
	v_pk_mul_f32 v[126:127], v[66:67], 0.5 op_sel_hi:[1,0]
	v_pk_mul_f32 v[122:123], v[64:65], 0.5 op_sel_hi:[1,0]
	v_pk_mul_f32 v[120:121], v[62:63], 0.5 op_sel_hi:[1,0]
	v_pk_mul_f32 v[118:119], v[60:61], 0.5 op_sel_hi:[1,0]
	v_pk_mul_f32 v[116:117], v[58:59], 0.5 op_sel_hi:[1,0]
	v_pk_mul_f32 v[112:113], v[48:49], 0.5 op_sel_hi:[1,0]
	v_pk_mul_f32 v[110:111], v[46:47], 0.5 op_sel_hi:[1,0]
	v_pk_mul_f32 v[108:109], v[40:41], 0.5 op_sel_hi:[1,0]
	v_pk_mul_f32 v[106:107], v[38:39], 0.5 op_sel_hi:[1,0]
	v_pk_mul_f32 v[104:105], v[56:57], 0.5 op_sel_hi:[1,0]
	v_pk_mul_f32 v[102:103], v[54:55], 0.5 op_sel_hi:[1,0]
	v_pk_mul_f32 v[100:101], v[52:53], 0.5 op_sel_hi:[1,0]
	v_pk_mul_f32 v[98:99], v[50:51], 0.5 op_sel_hi:[1,0]
	v_pk_mul_f32 v[96:97], v[32:33], 0.5 op_sel_hi:[1,0]
	v_pk_mul_f32 v[94:95], v[30:31], 0.5 op_sel_hi:[1,0]
	v_pk_mul_f32 v[92:93], v[24:25], 0.5 op_sel_hi:[1,0]
	v_pk_mul_f32 v[90:91], v[22:23], 0.5 op_sel_hi:[1,0]
	v_pk_mul_f32 v[88:89], v[44:45], 0.5 op_sel_hi:[1,0]
	v_pk_mul_f32 v[86:87], v[42:43], 0.5 op_sel_hi:[1,0]
	v_pk_mul_f32 v[84:85], v[36:37], 0.5 op_sel_hi:[1,0]
	v_pk_mul_f32 v[82:83], v[34:35], 0.5 op_sel_hi:[1,0]
	v_pk_mul_f32 v[80:81], v[16:17], 0.5 op_sel_hi:[1,0]
	v_pk_mul_f32 v[78:79], v[14:15], 0.5 op_sel_hi:[1,0]
	v_pk_mul_f32 v[76:77], v[12:13], 0.5 op_sel_hi:[1,0]
	v_pk_mul_f32 v[74:75], v[10:11], 0.5 op_sel_hi:[1,0]
	v_pk_mul_f32 v[72:73], v[28:29], 0.5 op_sel_hi:[1,0]
	v_pk_mul_f32 v[70:71], v[26:27], 0.5 op_sel_hi:[1,0]
	v_pk_mul_f32 v[68:69], v[20:21], 0.5 op_sel_hi:[1,0]
	v_pk_mul_f32 v[66:67], v[18:19], 0.5 op_sel_hi:[1,0]
	v_pk_mul_f32 v[64:65], v[8:9], 0.5 op_sel_hi:[1,0]
	v_pk_mul_f32 v[62:63], v[6:7], 0.5 op_sel_hi:[1,0]
	v_pk_mul_f32 v[60:61], v[4:5], 0.5 op_sel_hi:[1,0]
	v_pk_mul_f32 v[58:59], v[2:3], 0.5 op_sel_hi:[1,0]
	s_and_b64 vcc, exec, s[40:41]
	s_cbranch_vccz .LBB0_1522
